# both half-workgroups run the tile epilogue together (extra barrier pairing) in FFN-down, branch and out projections
# speedup vs baseline: 1.0175x; 1.0175x over previous
; #define PG8_BAR __builtin_amdgcn_s_barrier()
;     __host__ __device__ bool next(int i, Unit& u) const {
;         const long L = (long)i * G + c; if (L >= nwg) return false;
;         int wgid = (int)L; { const int q = nwg / NXCD, r = nwg % NXCD, xcd = wgid % NXCD, off = wgid / NXCD; wgid = (xcd < r ? xcd * (q + 1) : r * (q + 1) + (xcd - r) * q) + off; }
;         const int nig = WGM * nN, gid = wgid / nig, fm = gid * WGM, gsz = (nM - fm) < WGM ? (nM - fm) : WGM;
;         u.pm = fm + ((wgid % nig) % gsz); u.pn = (wgid % nig) / gsz; return true;
;     }
; template <class Epi, class Sched, bool ALIGN_EPI = false, bool SP2 = false>
; __device__ __forceinline__ void gemm_phase(PG8_LAS unsigned char* lds, const Gemm g, const Sched& S, const Epi& E) {
;     ...
;         if (!has_next) break;
; #pragma unroll
;         for (int a = 0; a < 2; ++a)
; #pragma unroll
;             for (int b = 0; b < 2; ++b)
; #pragma unroll
;                 for (int m = 0; m < 4; ++m)
; #pragma unroll
;                     for (int n = 0; n < 2; ++n) acc[a][b][m][n] = (f32x4){0.f, 0.f, 0.f, 0.f};
;         cur = nxt; cA = nA; cB = nB; ++ui;
;         if constexpr (ALIGN_EPI) { if (wr == 1) PG8_BAR; }
.LBB0_258:
	s_or_b64 exec, exec, s[22:23]
	s_and_b64 vcc, exec, s[4:5]
	s_mov_b32 s82, s80
	s_mov_b32 s83, s81
	s_mov_b64 s[22:23], s[6:7]
	s_mov_b64 s[20:21], s[0:1]
	s_cbranch_vccnz .LBB0_283
	s_cmpk_lt_u32 s26, 0x100
	s_cbranch_scc1 .Lal_p2_post
	s_barrier
.Lal_p2_post:
.LBB0_259:
	s_add_i32 s44, s44, 1
	s_mul_i32 s0, s44, s47
	s_mul_hi_u32 s1, s44, s11
	s_add_i32 s1, s1, s0
	s_mul_i32 s0, s44, s11
	s_add_u32 s6, s0, s10
	s_addc_u32 s7, s1, s48
	v_cmp_gt_i64_e64 s[4:5], s[6:7], v[158:159]
	v_cmp_lt_i64_e64 s[0:1], s[6:7], v[156:157]
	s_and_b64 vcc, exec, s[4:5]
	s_cbranch_vccnz .LBB0_261
	s_ashr_i32 s7, s6, 31
	s_lshr_b32 s7, s7, 29
	s_add_i32 s7, s6, s7
	s_ashr_i32 s24, s7, 3
	s_and_b32 s7, s7, -8
	s_sub_i32 s6, s6, s7
	s_cmp_lt_i32 s6, 0
	s_cselect_b32 s7, s61, 0x60
	s_mul_i32 s6, s6, s7
	s_add_i32 s6, s6, s24
	s_ashr_i32 s7, s6, 31
	s_lshr_b32 s7, s7, 27
	s_add_i32 s7, s6, s7
	s_ashr_i32 s24, s7, 5
	s_lshl_b32 s24, s24, 3
	s_sub_i32 s25, 0xc0, s24
	s_min_i32 s25, s25, 8
	s_abs_i32 s80, s25
	v_cvt_f32_u32_e32 v0, s80
	s_sub_i32 s84, 0, s80
	s_andn2_b32 s7, s7, 31
	s_sub_i32 s6, s6, s7
	v_rcp_iflag_f32_e32 v0, v0
	s_abs_i32 s7, s6
	s_xor_b32 s81, s6, s25
	s_ashr_i32 s81, s81, 31
	v_mul_f32_e32 v0, 0x4f7ffffe, v0
	v_cvt_u32_f32_e32 v0, v0
	s_nop 0
	v_readfirstlane_b32 s85, v0
	s_mul_i32 s84, s84, s85
	s_mul_hi_u32 s84, s85, s84
	s_add_i32 s85, s85, s84
	s_mul_hi_u32 s84, s7, s85
	s_mul_i32 s85, s84, s80
	s_sub_i32 s7, s7, s85
	s_add_i32 s86, s84, 1
	s_sub_i32 s85, s7, s80
	s_cmp_ge_u32 s7, s80
	s_cselect_b32 s84, s86, s84
	s_cselect_b32 s7, s85, s7
	s_add_i32 s85, s84, 1
	s_cmp_ge_u32 s7, s80
	s_cselect_b32 s7, s85, s84
	s_xor_b32 s7, s7, s81
	s_sub_i32 s80, s7, s81
	s_mul_i32 s7, s80, s25
	s_sub_i32 s6, s6, s7
	s_add_i32 s81, s24, s6

; #define PG8_STAGE(bufoff, gbase, voff) do { _Pragma("unroll") for (int _i = 0; _i < 2; ++_i) \
;         __builtin_amdgcn_global_load_lds((const unsigned*)((const char*)(gbase) + (voff)[_i]), (PG8_LAS unsigned*)(lds + (bufoff) + ldsw + _i * 8192), 16, 0, 0); } while (0)
; #define PG8_LDA(dst, b, h) do { _Pragma("unroll") for (int m = 0; m < 4; ++m) _Pragma("unroll") for (int k = 0; k < 2; ++k) dst[m][k] = *(const PG8_LAS bf16x8*)(lds + PG8_SA(b, h) + aoff + m * 2048 + k * 1024); } while (0)
; #define PG8_LDB(dst, b, h) do { _Pragma("unroll") for (int n = 0; n < 2; ++n) _Pragma("unroll") for (int k = 0; k < 2; ++k) dst[n][k] = *(const PG8_LAS bf16x8*)(lds + PG8_SB(b, h) + boff + n * 2048 + k * 1024); } while (0)
; #define PG8_MMA(ai, bj, At, Bt) do { __builtin_amdgcn_s_setprio(1); _Pragma("unroll") for (int m = 0; m < 4; ++m) _Pragma("unroll") for (int n = 0; n < 2; ++n) _Pragma("unroll") for (int k = 0; k < 2; ++k) \
;         acc[ai][bj][m][n] = __builtin_amdgcn_mfma_f32_16x16x32_bf16(Bt[n][k], At[m][k], acc[ai][bj][m][n], 0, 0, 0); __builtin_amdgcn_s_setprio(0); } while (0)
; #define PG8_WAIT_V(n) asm volatile("s_waitcnt vmcnt(" #n ")" ::: "memory")
; template <class Epi, class Sched, bool ALIGN_EPI = false, bool SP2 = false>
; __device__ __forceinline__ void gemm_phase(PG8_LAS unsigned char* lds, const Gemm g, const Sched& S, const Epi& E) {
;     ...
;         const char* nA = has_next ? (const char*)g.A + (size_t)nxt.pm * tstep : cA; const char* nB = has_next ? (const char*)g.Bt + (size_t)nxt.pn * tstep : cB;
;         for (int t = 0; t < nt; t += 2) {
;             const bool last = (t == nt - 2);
;             const char* a1 = cA + (size_t)(t + 1) * kstep;
;             const char* a2 = last ? nA : cA + (size_t)(t + 2) * kstep; const char* b2 = last ? nB : cB + (size_t)(t + 2) * kstep;
;             const char* a3 = a2 + kstep; const char* b3 = b2 + kstep;
;             if (last && has_next) S.a_ready(nxt);
;             if constexpr (SP2) {
;             PG8_LDB(B0, 0, 0); PG8_LDB(B1, 0, 1); PG8_SCHED; PG8_LDA(At, 0, 0); PG8_STAGE(PG8_SA(1, 1), a1 + hstep, voffA);
;             PG8_WAIT_V(8); PG8_WAIT_L(0); PG8_BAR; PG8_MMA(0, 0, At, B0); PG8_MMA(0, 1, At, B1); PG8_BAR; PG8_SCHED;
;             PG8_LDA(At, 0, 1); PG8_STAGE(PG8_SB(0, 0), b2, voffB); PG8_STAGE(PG8_SB(0, 1), b2 + hstep, voffB); PG8_STAGE(PG8_SA(0, 0), a2, voffA);
.LBB0_266:
	ds_read_b128 v[128:131], v171
	ds_read_b128 v[132:135], v171 offset:1024
	ds_read_b128 v[136:139], v171 offset:2048
	ds_read_b128 v[140:143], v171 offset:3072
	ds_read_b128 v[160:163], v172
	ds_read_b128 v[164:167], v172 offset:1024
	ds_read_b128 v[176:179], v172 offset:2048
	ds_read_b128 v[182:185], v172 offset:3072
	s_add_u32 s22, s20, 0xfff50080
	s_addc_u32 s23, s21, -1
	s_cmp_eq_u32 s86, 40
	s_cselect_b32 s25, s1, s23
	s_cselect_b32 s24, s0, s22
	s_cselect_b32 s23, s7, s85
	s_cselect_b32 s22, s6, s84
	v_lshl_add_u64 v[220:221], s[20:21], 0, v[152:153]
	s_add_i32 m0, s40, 0xc000
	ds_read_b128 v[186:189], v173
	ds_read_b128 v[192:195], v173 offset:1024
	ds_read_b128 v[196:199], v173 offset:2048
	ds_read_b128 v[200:203], v173 offset:3072
	ds_read_b128 v[204:207], v173 offset:4096
	ds_read_b128 v[208:211], v173 offset:5120
	ds_read_b128 v[212:215], v173 offset:6144
	ds_read_b128 v[216:219], v173 offset:7168
	global_load_lds_dwordx4 v[220:221], off
	v_lshl_add_u64 v[220:221], s[20:21], 0, v[154:155]
	s_add_i32 m0, s40, 0xe000
	s_nop 0
	global_load_lds_dwordx4 v[220:221], off
	s_waitcnt vmcnt(8)
	s_waitcnt lgkmcnt(0)
	s_barrier
	s_setprio 1
	s_waitcnt lgkmcnt(0)
	v_mfma_f32_16x16x32_bf16 v[124:127], v[128:131], v[186:189], v[124:127]
	v_mfma_f32_16x16x32_bf16 v[120:123], v[136:139], v[186:189], v[120:123]
	v_mfma_f32_16x16x32_bf16 v[108:111], v[128:131], v[196:199], v[108:111]
	v_mfma_f32_16x16x32_bf16 v[104:107], v[136:139], v[196:199], v[104:107]
	v_mfma_f32_16x16x32_bf16 v[92:95], v[128:131], v[204:207], v[92:95]
	v_mfma_f32_16x16x32_bf16 v[88:91], v[136:139], v[204:207], v[88:91]
	v_mfma_f32_16x16x32_bf16 v[76:79], v[128:131], v[212:215], v[76:79]
	v_mfma_f32_16x16x32_bf16 v[72:75], v[136:139], v[212:215], v[72:75]
	v_mfma_f32_16x16x32_bf16 v[124:127], v[132:135], v[192:195], v[124:127]
	v_mfma_f32_16x16x32_bf16 v[120:123], v[140:143], v[192:195], v[120:123]
	v_mfma_f32_16x16x32_bf16 v[108:111], v[132:135], v[200:203], v[108:111]
	v_mfma_f32_16x16x32_bf16 v[104:107], v[140:143], v[200:203], v[104:107]
	v_mfma_f32_16x16x32_bf16 v[92:95], v[132:135], v[208:211], v[92:95]
	v_mfma_f32_16x16x32_bf16 v[88:91], v[140:143], v[208:211], v[88:91]
	v_mfma_f32_16x16x32_bf16 v[76:79], v[132:135], v[216:219], v[76:79]
	v_mfma_f32_16x16x32_bf16 v[72:75], v[140:143], v[216:219], v[72:75]
	s_setprio 0
	s_setprio 1
	v_mfma_f32_16x16x32_bf16 v[116:119], v[160:163], v[186:189], v[116:119]
	v_mfma_f32_16x16x32_bf16 v[112:115], v[176:179], v[186:189], v[112:115]
	v_mfma_f32_16x16x32_bf16 v[100:103], v[160:163], v[196:199], v[100:103]
	v_mfma_f32_16x16x32_bf16 v[96:99], v[176:179], v[196:199], v[96:99]
	v_mfma_f32_16x16x32_bf16 v[84:87], v[160:163], v[204:207], v[84:87]
	v_mfma_f32_16x16x32_bf16 v[80:83], v[176:179], v[204:207], v[80:83]
	v_mfma_f32_16x16x32_bf16 v[68:71], v[160:163], v[212:215], v[68:71]
	v_mfma_f32_16x16x32_bf16 v[64:67], v[176:179], v[212:215], v[64:67]
	v_mfma_f32_16x16x32_bf16 v[116:119], v[164:167], v[192:195], v[116:119]
	v_mfma_f32_16x16x32_bf16 v[112:115], v[182:185], v[192:195], v[112:115]
	v_mfma_f32_16x16x32_bf16 v[100:103], v[164:167], v[200:203], v[100:103]
	v_mfma_f32_16x16x32_bf16 v[96:99], v[182:185], v[200:203], v[96:99]
	v_mfma_f32_16x16x32_bf16 v[84:87], v[164:167], v[208:211], v[84:87]
	v_mfma_f32_16x16x32_bf16 v[80:83], v[182:185], v[208:211], v[80:83]
	v_mfma_f32_16x16x32_bf16 v[68:71], v[164:167], v[216:219], v[68:71]
	v_mfma_f32_16x16x32_bf16 v[64:67], v[182:185], v[216:219], v[64:67]
	s_setprio 0
	s_barrier
	s_add_i32 s87, s78, s27
	v_lshl_add_u64 v[220:221], s[22:23], 0, v[146:147]
	s_mov_b32 m0, s87
	ds_read_b128 v[186:189], v173 offset:16384
	ds_read_b128 v[192:195], v173 offset:17408
	ds_read_b128 v[196:199], v173 offset:18432
	ds_read_b128 v[200:203], v173 offset:19456
	ds_read_b128 v[204:207], v173 offset:20480
	ds_read_b128 v[208:211], v173 offset:21504
	ds_read_b128 v[212:215], v173 offset:22528
	ds_read_b128 v[216:219], v173 offset:23552
	global_load_lds_dwordx4 v[220:221], off
	s_add_i32 m0, s87, 0x2000
	s_add_u32 s88, s22, 0xb0000
	v_lshl_add_u64 v[222:223], s[22:23], 0, v[150:151]
	s_addc_u32 s89, s23, 0
	s_add_i32 s87, s79, s27
	global_load_lds_dwordx4 v[222:223], off
	v_lshl_add_u64 v[224:225], s[88:89], 0, v[146:147]
	s_mov_b32 m0, s87
	v_lshl_add_u64 v[226:227], s[24:25], 0, v[148:149]
	global_load_lds_dwordx4 v[224:225], off
	v_lshl_add_u64 v[224:225], s[88:89], 0, v[150:151]
	s_add_i32 m0, s87, 0x2000
	s_nop 0
	global_load_lds_dwordx4 v[224:225], off
	v_lshl_add_u64 v[224:225], s[24:25], 0, v[144:145]
	s_mov_b32 m0, s40
	s_nop 0
	global_load_lds_dwordx4 v[224:225], off
	s_mov_b32 m0, s41
	s_nop 0
	global_load_lds_dwordx4 v[226:227], off
	s_waitcnt vmcnt(8)
	s_waitcnt lgkmcnt(0)
	s_barrier
; #define PG8_STAGE(bufoff, gbase, voff) do { _Pragma("unroll") for (int _i = 0; _i < 2; ++_i) \
;         __builtin_amdgcn_global_load_lds((const unsigned*)((const char*)(gbase) + (voff)[_i]), (PG8_LAS unsigned*)(lds + (bufoff) + ldsw + _i * 8192), 16, 0, 0); } while (0)
; #define PG8_LDA(dst, b, h) do { _Pragma("unroll") for (int m = 0; m < 4; ++m) _Pragma("unroll") for (int k = 0; k < 2; ++k) dst[m][k] = *(const PG8_LAS bf16x8*)(lds + PG8_SA(b, h) + aoff + m * 2048 + k * 1024); } while (0)
; #define PG8_LDB(dst, b, h) do { _Pragma("unroll") for (int n = 0; n < 2; ++n) _Pragma("unroll") for (int k = 0; k < 2; ++k) dst[n][k] = *(const PG8_LAS bf16x8*)(lds + PG8_SB(b, h) + boff + n * 2048 + k * 1024); } while (0)
; #define PG8_MMA(ai, bj, At, Bt) do { __builtin_amdgcn_s_setprio(1); _Pragma("unroll") for (int m = 0; m < 4; ++m) _Pragma("unroll") for (int n = 0; n < 2; ++n) _Pragma("unroll") for (int k = 0; k < 2; ++k) \
;         acc[ai][bj][m][n] = __builtin_amdgcn_mfma_f32_16x16x32_bf16(Bt[n][k], At[m][k], acc[ai][bj][m][n], 0, 0, 0); __builtin_amdgcn_s_setprio(0); } while (0)
; #define PG8_WAIT_V(n) asm volatile("s_waitcnt vmcnt(" #n ")" ::: "memory")
; #define PG8_WAIT_L(n) asm volatile("s_waitcnt lgkmcnt(" #n ")" ::: "memory")
; #define PG8_BAR __builtin_amdgcn_s_barrier()
; #define PG8_SCHED __builtin_amdgcn_sched_barrier(0)
; template <class Epi, class Sched, bool ALIGN_EPI = false, bool SP2 = false>
; __device__ __forceinline__ void gemm_phase(PG8_LAS unsigned char* lds, const Gemm g, const Sched& S, const Epi& E) {
;     ...
;             PG8_WAIT_V(8); PG8_WAIT_L(0); PG8_BAR; PG8_MMA(1, 0, At, B0); PG8_MMA(1, 1, At, B1); PG8_BAR; PG8_SCHED;
;             PG8_LDB(B0, 1, 0); PG8_LDB(B1, 1, 1); PG8_SCHED; PG8_LDA(At, 1, 0); PG8_STAGE(PG8_SA(0, 1), a2 + hstep, voffA);
;             PG8_WAIT_V(8); PG8_WAIT_L(0); PG8_BAR; PG8_MMA(0, 0, At, B0); PG8_MMA(0, 1, At, B1); PG8_BAR; PG8_SCHED;
	s_setprio 1
	s_waitcnt lgkmcnt(0)
	v_mfma_f32_16x16x32_bf16 v[60:63], v[128:131], v[186:189], v[60:63]
	v_mfma_f32_16x16x32_bf16 v[56:59], v[136:139], v[186:189], v[56:59]
	v_mfma_f32_16x16x32_bf16 v[44:47], v[128:131], v[196:199], v[44:47]
	v_mfma_f32_16x16x32_bf16 v[40:43], v[136:139], v[196:199], v[40:43]
	v_mfma_f32_16x16x32_bf16 v[28:31], v[128:131], v[204:207], v[28:31]
	v_mfma_f32_16x16x32_bf16 v[24:27], v[136:139], v[204:207], v[24:27]
	v_mfma_f32_16x16x32_bf16 v[12:15], v[128:131], v[212:215], v[12:15]
	v_mfma_f32_16x16x32_bf16 v[8:11], v[136:139], v[212:215], v[8:11]
	v_mfma_f32_16x16x32_bf16 v[60:63], v[132:135], v[192:195], v[60:63]
	v_mfma_f32_16x16x32_bf16 v[56:59], v[140:143], v[192:195], v[56:59]
	v_mfma_f32_16x16x32_bf16 v[44:47], v[132:135], v[200:203], v[44:47]
	v_mfma_f32_16x16x32_bf16 v[40:43], v[140:143], v[200:203], v[40:43]
	v_mfma_f32_16x16x32_bf16 v[28:31], v[132:135], v[208:211], v[28:31]
	v_mfma_f32_16x16x32_bf16 v[24:27], v[140:143], v[208:211], v[24:27]
	v_mfma_f32_16x16x32_bf16 v[12:15], v[132:135], v[216:219], v[12:15]
	v_mfma_f32_16x16x32_bf16 v[8:11], v[140:143], v[216:219], v[8:11]
	s_setprio 0
	s_setprio 1
	v_mfma_f32_16x16x32_bf16 v[52:55], v[160:163], v[186:189], v[52:55]
	v_mfma_f32_16x16x32_bf16 v[48:51], v[176:179], v[186:189], v[48:51]
	v_mfma_f32_16x16x32_bf16 v[36:39], v[160:163], v[196:199], v[36:39]
	v_mfma_f32_16x16x32_bf16 v[32:35], v[176:179], v[196:199], v[32:35]
	v_mfma_f32_16x16x32_bf16 v[20:23], v[160:163], v[204:207], v[20:23]
	v_mfma_f32_16x16x32_bf16 v[16:19], v[176:179], v[204:207], v[16:19]
	v_mfma_f32_16x16x32_bf16 v[4:7], v[160:163], v[212:215], v[4:7]
	v_mfma_f32_16x16x32_bf16 v[0:3], v[176:179], v[212:215], v[0:3]
	v_mfma_f32_16x16x32_bf16 v[52:55], v[164:167], v[192:195], v[52:55]
	v_mfma_f32_16x16x32_bf16 v[48:51], v[182:185], v[192:195], v[48:51]
	v_mfma_f32_16x16x32_bf16 v[36:39], v[164:167], v[200:203], v[36:39]
	v_mfma_f32_16x16x32_bf16 v[32:35], v[182:185], v[200:203], v[32:35]
	v_mfma_f32_16x16x32_bf16 v[20:23], v[164:167], v[208:211], v[20:23]
	v_mfma_f32_16x16x32_bf16 v[16:19], v[182:185], v[208:211], v[16:19]
	v_mfma_f32_16x16x32_bf16 v[4:7], v[164:167], v[216:219], v[4:7]
	v_mfma_f32_16x16x32_bf16 v[0:3], v[182:185], v[216:219], v[0:3]
	s_setprio 0
	s_barrier
	s_add_i32 s87, 0, 0x18000
	s_add_i32 s88, 0, 0x1c000
	v_add_u32_e32 v140, s87, v169
	v_add_u32_e32 v175, s88, v169
	ds_read_b128 v[128:131], v140
	ds_read_b128 v[132:135], v140 offset:1024
	ds_read_b128 v[136:139], v140 offset:2048
	ds_read_b128 v[140:143], v140 offset:3072
	ds_read_b128 v[160:163], v175
	ds_read_b128 v[164:167], v175 offset:1024
	ds_read_b128 v[176:179], v175 offset:2048
	ds_read_b128 v[182:185], v175 offset:3072
	s_add_u32 s24, s24, 0xb0000
	s_addc_u32 s25, s25, 0
	s_mov_b32 m0, s42
	v_lshl_add_u64 v[228:229], s[24:25], 0, v[144:145]
	ds_read_b128 v[186:189], v173 offset:32768
	ds_read_b128 v[192:195], v173 offset:33792
	ds_read_b128 v[196:199], v173 offset:34816
	ds_read_b128 v[200:203], v173 offset:35840
	ds_read_b128 v[204:207], v173 offset:36864
	ds_read_b128 v[208:211], v173 offset:37888
	ds_read_b128 v[212:215], v173 offset:38912
	ds_read_b128 v[216:219], v173 offset:39936
	global_load_lds_dwordx4 v[228:229], off
	v_lshl_add_u64 v[228:229], s[24:25], 0, v[148:149]
	s_mov_b32 m0, s43
	s_nop 0
	global_load_lds_dwordx4 v[228:229], off
	s_waitcnt vmcnt(8)
	s_waitcnt lgkmcnt(0)
	s_barrier
	s_setprio 1
	s_waitcnt lgkmcnt(0)
	v_mfma_f32_16x16x32_bf16 v[124:127], v[128:131], v[186:189], v[124:127]
	v_mfma_f32_16x16x32_bf16 v[120:123], v[136:139], v[186:189], v[120:123]
	v_mfma_f32_16x16x32_bf16 v[108:111], v[128:131], v[196:199], v[108:111]
	v_mfma_f32_16x16x32_bf16 v[104:107], v[136:139], v[196:199], v[104:107]
	v_mfma_f32_16x16x32_bf16 v[92:95], v[128:131], v[204:207], v[92:95]
	v_mfma_f32_16x16x32_bf16 v[88:91], v[136:139], v[204:207], v[88:91]
	v_mfma_f32_16x16x32_bf16 v[76:79], v[128:131], v[212:215], v[76:79]
	v_mfma_f32_16x16x32_bf16 v[72:75], v[136:139], v[212:215], v[72:75]
	v_mfma_f32_16x16x32_bf16 v[124:127], v[132:135], v[192:195], v[124:127]
	v_mfma_f32_16x16x32_bf16 v[120:123], v[140:143], v[192:195], v[120:123]
	v_mfma_f32_16x16x32_bf16 v[108:111], v[132:135], v[200:203], v[108:111]
	v_mfma_f32_16x16x32_bf16 v[104:107], v[140:143], v[200:203], v[104:107]
	v_mfma_f32_16x16x32_bf16 v[92:95], v[132:135], v[208:211], v[92:95]
	v_mfma_f32_16x16x32_bf16 v[88:91], v[140:143], v[208:211], v[88:91]
	v_mfma_f32_16x16x32_bf16 v[76:79], v[132:135], v[216:219], v[76:79]
	v_mfma_f32_16x16x32_bf16 v[72:75], v[140:143], v[216:219], v[72:75]
	s_setprio 0
	s_setprio 1
	v_mfma_f32_16x16x32_bf16 v[116:119], v[160:163], v[186:189], v[116:119]
	v_mfma_f32_16x16x32_bf16 v[112:115], v[176:179], v[186:189], v[112:115]
	v_mfma_f32_16x16x32_bf16 v[100:103], v[160:163], v[196:199], v[100:103]
	v_mfma_f32_16x16x32_bf16 v[96:99], v[176:179], v[196:199], v[96:99]
	v_mfma_f32_16x16x32_bf16 v[84:87], v[160:163], v[204:207], v[84:87]
	v_mfma_f32_16x16x32_bf16 v[80:83], v[176:179], v[204:207], v[80:83]
	v_mfma_f32_16x16x32_bf16 v[68:71], v[160:163], v[212:215], v[68:71]
	v_mfma_f32_16x16x32_bf16 v[64:67], v[176:179], v[212:215], v[64:67]
	v_mfma_f32_16x16x32_bf16 v[116:119], v[164:167], v[192:195], v[116:119]
	v_mfma_f32_16x16x32_bf16 v[112:115], v[182:185], v[192:195], v[112:115]
	v_mfma_f32_16x16x32_bf16 v[100:103], v[164:167], v[200:203], v[100:103]
	v_mfma_f32_16x16x32_bf16 v[96:99], v[182:185], v[200:203], v[96:99]
	v_mfma_f32_16x16x32_bf16 v[84:87], v[164:167], v[208:211], v[84:87]
	v_mfma_f32_16x16x32_bf16 v[80:83], v[182:185], v[208:211], v[80:83]
	v_mfma_f32_16x16x32_bf16 v[68:71], v[164:167], v[216:219], v[68:71]
	v_mfma_f32_16x16x32_bf16 v[64:67], v[182:185], v[216:219], v[64:67]
	s_setprio 0
	s_barrier
; #define PG8_STAGE(bufoff, gbase, voff) do { _Pragma("unroll") for (int _i = 0; _i < 2; ++_i) \
;         __builtin_amdgcn_global_load_lds((const unsigned*)((const char*)(gbase) + (voff)[_i]), (PG8_LAS unsigned*)(lds + (bufoff) + ldsw + _i * 8192), 16, 0, 0); } while (0)
; #define PG8_LDA(dst, b, h) do { _Pragma("unroll") for (int m = 0; m < 4; ++m) _Pragma("unroll") for (int k = 0; k < 2; ++k) dst[m][k] = *(const PG8_LAS bf16x8*)(lds + PG8_SA(b, h) + aoff + m * 2048 + k * 1024); } while (0)
; #define PG8_MMA(ai, bj, At, Bt) do { __builtin_amdgcn_s_setprio(1); _Pragma("unroll") for (int m = 0; m < 4; ++m) _Pragma("unroll") for (int n = 0; n < 2; ++n) _Pragma("unroll") for (int k = 0; k < 2; ++k) \
;         acc[ai][bj][m][n] = __builtin_amdgcn_mfma_f32_16x16x32_bf16(Bt[n][k], At[m][k], acc[ai][bj][m][n], 0, 0, 0); __builtin_amdgcn_s_setprio(0); } while (0)
; #define PG8_WAIT_V(n) asm volatile("s_waitcnt vmcnt(" #n ")" ::: "memory")
; #define PG8_WAIT_L(n) asm volatile("s_waitcnt lgkmcnt(" #n ")" ::: "memory")
; #define PG8_BAR __builtin_amdgcn_s_barrier()
; #define PG8_SCHED __builtin_amdgcn_sched_barrier(0)
; template <class Epi, class Sched, bool ALIGN_EPI = false, bool SP2 = false>
; __device__ __forceinline__ void gemm_phase(PG8_LAS unsigned char* lds, const Gemm g, const Sched& S, const Epi& E) {
;     ...
;             PG8_LDA(At, 1, 1); PG8_STAGE(PG8_SB(1, 0), b3, voffB); PG8_STAGE(PG8_SB(1, 1), b3 + hstep, voffB); PG8_STAGE(PG8_SA(1, 0), a3, voffA);
;             PG8_WAIT_V(8); PG8_WAIT_L(0); PG8_BAR; PG8_MMA(1, 0, At, B0); PG8_MMA(1, 1, At, B1); PG8_BAR; PG8_SCHED;
;     ...
;         if constexpr (ALIGN_EPI) { if (wr == 0) PG8_BAR; }
	s_add_i32 s24, s87, s27
	v_lshl_add_u64 v[220:221], v[220:221], 0, s[18:19]
	s_mov_b32 m0, s24
	ds_read_b128 v[186:189], v173 offset:49152
	ds_read_b128 v[192:195], v173 offset:50176
	ds_read_b128 v[196:199], v173 offset:51200
	ds_read_b128 v[200:203], v173 offset:52224
	ds_read_b128 v[204:207], v173 offset:53248
	ds_read_b128 v[208:211], v173 offset:54272
	ds_read_b128 v[212:215], v173 offset:55296
	ds_read_b128 v[216:219], v173 offset:56320
	global_load_lds_dwordx4 v[220:221], off
	s_add_i32 m0, s24, 0x2000
	s_add_u32 s22, s22, 0xb0080
	v_lshl_add_u64 v[220:221], v[222:223], 0, s[18:19]
	s_addc_u32 s23, s23, 0
	s_add_i32 s24, s88, s27
	global_load_lds_dwordx4 v[220:221], off
	v_lshl_add_u64 v[220:221], s[22:23], 0, v[146:147]
	s_mov_b32 m0, s24
	s_nop 0
	global_load_lds_dwordx4 v[220:221], off
	v_lshl_add_u64 v[220:221], s[22:23], 0, v[150:151]
	s_add_i32 m0, s24, 0x2000
	s_nop 0
	global_load_lds_dwordx4 v[220:221], off
	v_lshl_add_u64 v[220:221], v[224:225], 0, s[18:19]
	s_mov_b32 m0, s45
	s_nop 0
	global_load_lds_dwordx4 v[220:221], off
	v_lshl_add_u64 v[220:221], v[226:227], 0, s[18:19]
	s_mov_b32 m0, s46
	s_nop 0
	global_load_lds_dwordx4 v[220:221], off
	s_waitcnt vmcnt(8)
	s_waitcnt lgkmcnt(0)
	s_barrier
	s_setprio 1
	s_waitcnt lgkmcnt(0)
	v_mfma_f32_16x16x32_bf16 v[60:63], v[128:131], v[186:189], v[60:63]
	v_mfma_f32_16x16x32_bf16 v[56:59], v[136:139], v[186:189], v[56:59]
	v_mfma_f32_16x16x32_bf16 v[44:47], v[128:131], v[196:199], v[44:47]
	v_mfma_f32_16x16x32_bf16 v[40:43], v[136:139], v[196:199], v[40:43]
	v_mfma_f32_16x16x32_bf16 v[28:31], v[128:131], v[204:207], v[28:31]
	v_mfma_f32_16x16x32_bf16 v[24:27], v[136:139], v[204:207], v[24:27]
	v_mfma_f32_16x16x32_bf16 v[12:15], v[128:131], v[212:215], v[12:15]
	v_mfma_f32_16x16x32_bf16 v[8:11], v[136:139], v[212:215], v[8:11]
	v_mfma_f32_16x16x32_bf16 v[60:63], v[132:135], v[192:195], v[60:63]
	v_mfma_f32_16x16x32_bf16 v[56:59], v[140:143], v[192:195], v[56:59]
	v_mfma_f32_16x16x32_bf16 v[44:47], v[132:135], v[200:203], v[44:47]
	v_mfma_f32_16x16x32_bf16 v[40:43], v[140:143], v[200:203], v[40:43]
	v_mfma_f32_16x16x32_bf16 v[28:31], v[132:135], v[208:211], v[28:31]
	v_mfma_f32_16x16x32_bf16 v[24:27], v[140:143], v[208:211], v[24:27]
	v_mfma_f32_16x16x32_bf16 v[12:15], v[132:135], v[216:219], v[12:15]
	v_mfma_f32_16x16x32_bf16 v[8:11], v[140:143], v[216:219], v[8:11]
	s_setprio 0
	s_setprio 1
	v_mfma_f32_16x16x32_bf16 v[52:55], v[160:163], v[186:189], v[52:55]
	v_mfma_f32_16x16x32_bf16 v[48:51], v[176:179], v[186:189], v[48:51]
	v_mfma_f32_16x16x32_bf16 v[36:39], v[160:163], v[196:199], v[36:39]
	v_mfma_f32_16x16x32_bf16 v[32:35], v[176:179], v[196:199], v[32:35]
	v_mfma_f32_16x16x32_bf16 v[20:23], v[160:163], v[204:207], v[20:23]
	v_mfma_f32_16x16x32_bf16 v[16:19], v[176:179], v[204:207], v[16:19]
	v_mfma_f32_16x16x32_bf16 v[4:7], v[160:163], v[212:215], v[4:7]
	v_mfma_f32_16x16x32_bf16 v[0:3], v[176:179], v[212:215], v[0:3]
	v_mfma_f32_16x16x32_bf16 v[52:55], v[164:167], v[192:195], v[52:55]
	v_mfma_f32_16x16x32_bf16 v[48:51], v[182:185], v[192:195], v[48:51]
	v_mfma_f32_16x16x32_bf16 v[36:39], v[164:167], v[200:203], v[36:39]
	v_mfma_f32_16x16x32_bf16 v[32:35], v[182:185], v[200:203], v[32:35]
	v_mfma_f32_16x16x32_bf16 v[20:23], v[164:167], v[208:211], v[20:23]
	v_mfma_f32_16x16x32_bf16 v[16:19], v[182:185], v[208:211], v[16:19]
	v_mfma_f32_16x16x32_bf16 v[4:7], v[164:167], v[216:219], v[4:7]
	v_mfma_f32_16x16x32_bf16 v[0:3], v[182:185], v[216:219], v[0:3]
	s_setprio 0
	s_barrier
	s_add_i32 s86, s86, 2
	s_add_u32 s20, s20, 0x100
	s_addc_u32 s21, s21, 0
	s_add_u32 s84, s84, 0x100
	s_addc_u32 s85, s85, 0
	s_cmp_gt_u32 s86, 41
	s_cbranch_scc0 .LBB0_266
	s_cmpk_gt_u32 s26, 0xff
	s_cbranch_scc1 .Lal_p2_pre
	s_barrier
; __device__ __forceinline__ u32x2 pack4(f32x4 v) { u32x2 w; w.x = cvt_pk_bf16(v[0], v[1]); w.y = cvt_pk_bf16(v[2], v[3]); return w; }
;     __device__ __forceinline__ void operator()(const f32x4 (&acc)[2][2][4][2], const Unit& u, int wr, int wc, int fr, int fq) const {
;         const int row0 = u.pm * BM + wr * 64 + fr, col0 = u.pn * BM + wc * 32 + 8 * fq;
;         const float* base = (u.pm * BM < split) ? base0 : base1; bf16_t* const xn = (bf16_t*)(ws + WS_XN); float* const ssq = (float*)(ws + WS_SSQ);
; #pragma unroll
;         for (int ai = 0; ai < 2; ++ai)
; #pragma unroll
;         for (int mh = 0; mh < 4; mh += 2) {
;             f32x4 pre[4][2][2];
; #pragma unroll
;             for (int m = mh; m < mh + 2; ++m)
; #pragma unroll
;                 for (int bj = 0; bj < 2; ++bj)
; #pragma unroll
;                     for (int n = 0; n < 2; ++n) pre[m][bj][n] = *(const f32x4*)(base + (size_t)(row0 + ai * HALF + m * 16) * 1024 + col0 + bj * HALF + n * 4);
;             asm volatile("" ::: "memory");
; #pragma unroll
;             for (int m = mh; m < mh + 2; ++m) { const int row = row0 + ai * HALF + m * 16; const size_t off = (size_t)row * 1024 + col0; float ss = 0.f;
; #pragma unroll
;                 for (int bj = 0; bj < 2; ++bj) { u32x4e w;
; #pragma unroll
;                     for (int n = 0; n < 2; ++n) { const f32x4 o = pre[m][bj][n] + acc[ai][bj][m][n] * s;
;                         *(f32x4*)(out + off + bj * HALF + n * 4) = o;
;                         if (NORMOUT) { const u32x2 p = pack4(o); w[2 * n] = p.x; w[2 * n + 1] = p.y; ss += (o[0] * o[0] + o[1] * o[1]) + (o[2] * o[2] + o[3] * o[3]); } }
;                     if (NORMOUT) *(u32x4e*)(xn + off + bj * HALF) = w; }
;                 if (NORMOUT) { ss += __shfl_xor(ss, 16); ss += __shfl_xor(ss, 32); if (fq == 0) ssq[(size_t)row * 16 + u.pn * 4 + wc] = ss; } }
.Lal_p2_pre:
	s_cmpk_lt_i32 s83, 0x80
	v_lshl_add_u32 v162, s83, 8, v168
	v_lshl_or_b32 v160, s82, 8, v170
	s_cselect_b32 s20, s37, s39
	s_cselect_b32 s21, s36, s38
	v_mov_b32_e32 v128, s21
	v_mov_b32_e32 v129, s20
	v_ashrrev_i32_e32 v161, 31, v160
	v_ashrrev_i32_e32 v163, 31, v162
	v_lshl_add_u64 v[164:165], v[160:161], 2, v[128:129]
	v_lshlrev_b64 v[128:129], 12, v[162:163]
	v_lshl_add_u64 v[128:129], v[164:165], 0, v[128:129]
	global_load_dwordx4 v[182:185], v[128:129], off
	global_load_dwordx4 v[186:189], v[128:129], off offset:16
	global_load_dwordx4 v[192:195], v[128:129], off offset:512
	global_load_dwordx4 v[196:199], v[128:129], off offset:528
	v_or_b32_e32 v166, 16, v162
	v_ashrrev_i32_e32 v167, 31, v166
	v_lshlrev_b64 v[128:129], 12, v[166:167]
	v_lshl_add_u64 v[132:133], v[164:165], 0, v[128:129]
	global_load_dwordx4 v[136:139], v[132:133], off offset:16
	global_load_dwordx4 v[140:143], v[132:133], off
	global_load_dwordx4 v[128:131], v[132:133], off offset:528
	s_nop 0
	global_load_dwordx4 v[132:135], v[132:133], off offset:512
	v_and_b32_e32 v176, 64, v174
	v_xor_b32_e32 v175, 16, v174
	v_add_u32_e32 v176, 64, v176
	v_lshlrev_b64 v[178:179], 10, v[162:163]
	v_xor_b32_e32 v177, 32, v174
	v_cmp_lt_i32_e32 vcc, v175, v176
	v_lshl_add_u64 v[178:179], v[178:179], 0, v[160:161]
	v_lshl_add_u64 v[200:201], v[178:179], 1, s[64:65]
	v_cndmask_b32_e32 v175, v174, v175, vcc
	v_cmp_lt_i32_e32 vcc, v177, v176
	v_lshl_add_u64 v[178:179], v[178:179], 2, s[56:57]
	v_lshlrev_b32_e32 v176, 2, v175
	v_cndmask_b32_e32 v177, v174, v177, vcc
	v_lshlrev_b32_e32 v175, 2, v177
	s_lshl_b32 s20, s82, 2
	s_ashr_i32 s21, s20, 31
	s_lshl_b64 s[20:21], s[20:21], 2
	s_add_u32 s20, s49, s20
	s_addc_u32 s21, s60, s21
	s_waitcnt vmcnt(0)
	v_pk_fma_f32 v[126:127], v[126:127], 0.5, v[184:185] op_sel_hi:[1,0,1]
	v_pk_fma_f32 v[124:125], v[124:125], 0.5, v[182:183] op_sel_hi:[1,0,1]
	v_pk_fma_f32 v[122:123], v[122:123], 0.5, v[188:189] op_sel_hi:[1,0,1]
	v_pk_fma_f32 v[120:121], v[120:121], 0.5, v[186:187] op_sel_hi:[1,0,1]
	v_pk_fma_f32 v[118:119], v[118:119], 0.5, v[194:195] op_sel_hi:[1,0,1]
	v_pk_fma_f32 v[116:117], v[116:117], 0.5, v[192:193] op_sel_hi:[1,0,1]
	v_pk_fma_f32 v[184:185], v[114:115], 0.5, v[198:199] op_sel_hi:[1,0,1]
	v_pk_fma_f32 v[182:183], v[112:113], 0.5, v[196:197] op_sel_hi:[1,0,1]
	global_store_dwordx4 v[178:179], v[124:127], off
	v_cvt_pk_bf16_f32 v112, v124, v125
	v_cvt_pk_bf16_f32 v113, v126, v127
	v_mul_f32_e32 v125, v125, v125
	v_mul_f32_e32 v127, v127, v127
	global_store_dwordx4 v[178:179], v[120:123], off offset:16
	v_cvt_pk_bf16_f32 v114, v120, v121
	v_cvt_pk_bf16_f32 v115, v122, v123
	v_mul_f32_e32 v121, v121, v121
	v_mul_f32_e32 v123, v123, v123
	v_mul_f32_e32 v177, v117, v117
	v_mul_f32_e32 v181, v119, v119
	v_fmac_f32_e32 v125, v124, v124
	v_fmac_f32_e32 v127, v126, v126
	v_fmac_f32_e32 v121, v120, v120
	v_fmac_f32_e32 v123, v122, v122
	v_mul_f32_e32 v186, v183, v183
	v_mul_f32_e32 v187, v185, v185
	v_fmac_f32_e32 v177, v116, v116
	v_fmac_f32_e32 v181, v118, v118
	v_add_f32_e32 v120, v125, v127
	v_add_f32_e32 v121, v121, v123
	v_fmac_f32_e32 v186, v182, v182
	v_fmac_f32_e32 v187, v184, v184
	v_add_f32_e32 v122, v177, v181
	v_add_f32_e32 v120, v120, v121
	v_add_f32_e32 v120, v122, v120
	v_add_f32_e32 v121, v186, v187
	v_add_f32_e32 v120, v121, v120
	ds_bpermute_b32 v121, v176, v120
	global_store_dwordx4 v[200:201], v[112:115], off
	global_store_dwordx4 v[178:179], v[116:119], off offset:512
	global_store_dwordx4 v[178:179], v[182:185], off offset:528
	v_cvt_pk_bf16_f32 v114, v116, v117
	v_cvt_pk_bf16_f32 v115, v118, v119
	s_waitcnt lgkmcnt(0)
	v_add_f32_e32 v112, v120, v121
	ds_bpermute_b32 v113, v175, v112
	v_cvt_pk_bf16_f32 v116, v182, v183
	v_cvt_pk_bf16_f32 v117, v184, v185
	global_store_dwordx4 v[200:201], v[114:117], off offset:256
	s_and_saveexec_b64 s[22:23], s[2:3]
	s_cbranch_execz .LBB0_269
	v_lshlrev_b64 v[114:115], 6, v[162:163]
	v_lshl_add_u64 v[114:115], s[20:21], 0, v[114:115]
	s_waitcnt lgkmcnt(0)
	v_add_f32_e32 v112, v112, v113
	global_store_dword v[114:115], v112, off

; #define PG8_WAIT_V(n) asm volatile("s_waitcnt vmcnt(" #n ")" ::: "memory")
; #define PG8_BAR __builtin_amdgcn_s_barrier()
; template <class Epi, class Sched, bool ALIGN_EPI = false, bool SP2 = false>
; __device__ __forceinline__ void gemm_phase(PG8_LAS unsigned char* lds, const Gemm g, const Sched& S, const Epi& E) {
;     ...
;     PG8_WAIT_V(0);
;     if constexpr (!ALIGN_EPI) { if (wr == 0) PG8_BAR; }
;     PG8_BAR;
.LBB0_283:
	s_waitcnt vmcnt(0)
.LBB0_285:
	s_barrier

; #define PG8_STAGE(bufoff, gbase, voff) do { _Pragma("unroll") for (int _i = 0; _i < 2; ++_i) \
;         __builtin_amdgcn_global_load_lds((const unsigned*)((const char*)(gbase) + (voff)[_i]), (PG8_LAS unsigned*)(lds + (bufoff) + ldsw + _i * 8192), 16, 0, 0); } while (0)
; #define PG8_LDA(dst, b, h) do { _Pragma("unroll") for (int m = 0; m < 4; ++m) _Pragma("unroll") for (int k = 0; k < 2; ++k) dst[m][k] = *(const PG8_LAS bf16x8*)(lds + PG8_SA(b, h) + aoff + m * 2048 + k * 1024); } while (0)
; #define PG8_LDB(dst, b, h) do { _Pragma("unroll") for (int n = 0; n < 2; ++n) _Pragma("unroll") for (int k = 0; k < 2; ++k) dst[n][k] = *(const PG8_LAS bf16x8*)(lds + PG8_SB(b, h) + boff + n * 2048 + k * 1024); } while (0)
; #define PG8_MMA(ai, bj, At, Bt) do { __builtin_amdgcn_s_setprio(1); _Pragma("unroll") for (int m = 0; m < 4; ++m) _Pragma("unroll") for (int n = 0; n < 2; ++n) _Pragma("unroll") for (int k = 0; k < 2; ++k) \
;         acc[ai][bj][m][n] = __builtin_amdgcn_mfma_f32_16x16x32_bf16(Bt[n][k], At[m][k], acc[ai][bj][m][n], 0, 0, 0); __builtin_amdgcn_s_setprio(0); } while (0)
; #define PG8_WAIT_V(n) asm volatile("s_waitcnt vmcnt(" #n ")" ::: "memory")
; template <class Epi, class Sched, bool ALIGN_EPI = false, bool SP2 = false>
; __device__ __forceinline__ void gemm_phase(PG8_LAS unsigned char* lds, const Gemm g, const Sched& S, const Epi& E) {
;     ...
;         const char* nA = has_next ? (const char*)g.A + (size_t)nxt.pm * tstep : cA; const char* nB = has_next ? (const char*)g.Bt + (size_t)nxt.pn * tstep : cB;
;         for (int t = 0; t < nt; t += 2) {
;             const bool last = (t == nt - 2);
;             const char* a1 = cA + (size_t)(t + 1) * kstep;
;             const char* a2 = last ? nA : cA + (size_t)(t + 2) * kstep; const char* b2 = last ? nB : cB + (size_t)(t + 2) * kstep;
;             const char* a3 = a2 + kstep; const char* b3 = b2 + kstep;
;             if (last && has_next) S.a_ready(nxt);
;             if constexpr (SP2) {
;             PG8_LDB(B0, 0, 0); PG8_LDB(B1, 0, 1); PG8_SCHED; PG8_LDA(At, 0, 0); PG8_STAGE(PG8_SA(1, 1), a1 + hstep, voffA);
;             PG8_WAIT_V(8); PG8_WAIT_L(0); PG8_BAR; PG8_MMA(0, 0, At, B0); PG8_MMA(0, 1, At, B1); PG8_BAR; PG8_SCHED;
;             PG8_LDA(At, 0, 1); PG8_STAGE(PG8_SB(0, 0), b2, voffB); PG8_STAGE(PG8_SB(0, 1), b2 + hstep, voffB); PG8_STAGE(PG8_SA(0, 0), a2, voffA);
.LBB0_735:
	ds_read_b128 v[144:147], v159
	ds_read_b128 v[162:165], v159 offset:1024
	ds_read_b128 v[166:169], v159 offset:2048
	ds_read_b128 v[170:173], v159 offset:3072
	ds_read_b128 v[174:177], v160
	ds_read_b128 v[178:181], v160 offset:1024
	ds_read_b128 v[182:185], v160 offset:2048
	ds_read_b128 v[186:189], v160 offset:3072
	s_add_u32 s44, s42, 0xfffe0080
	s_addc_u32 s45, s43, -1
	s_cmp_eq_u32 s86, 4
	s_cselect_b32 s47, s27, s45
	s_cselect_b32 s46, s82, s44
	s_cselect_b32 s45, s25, s85
	s_cselect_b32 s44, s83, s84
	v_lshl_add_u64 v[222:223], s[42:43], 0, v[136:137]
	s_add_i32 m0, s41, 0xc000
	ds_read_b128 v[190:193], v161
	ds_read_b128 v[194:197], v161 offset:1024
	ds_read_b128 v[198:201], v161 offset:2048
	ds_read_b128 v[202:205], v161 offset:3072
	ds_read_b128 v[206:209], v161 offset:4096
	ds_read_b128 v[210:213], v161 offset:5120
	ds_read_b128 v[214:217], v161 offset:6144
	ds_read_b128 v[218:221], v161 offset:7168
	global_load_lds_dwordx4 v[222:223], off
	v_lshl_add_u64 v[222:223], s[42:43], 0, v[138:139]
	s_add_i32 m0, s41, 0xe000
	s_nop 0
	global_load_lds_dwordx4 v[222:223], off
	s_waitcnt vmcnt(8)
	s_waitcnt lgkmcnt(0)
	s_barrier
	s_setprio 1
	s_waitcnt lgkmcnt(0)
	v_mfma_f32_16x16x32_bf16 v[124:127], v[144:147], v[190:193], v[124:127]
	v_mfma_f32_16x16x32_bf16 v[120:123], v[166:169], v[190:193], v[120:123]
	v_mfma_f32_16x16x32_bf16 v[112:115], v[144:147], v[198:201], v[112:115]
	v_mfma_f32_16x16x32_bf16 v[104:107], v[166:169], v[198:201], v[104:107]
	v_mfma_f32_16x16x32_bf16 v[92:95], v[144:147], v[206:209], v[92:95]
	v_mfma_f32_16x16x32_bf16 v[88:91], v[166:169], v[206:209], v[88:91]
	v_mfma_f32_16x16x32_bf16 v[84:87], v[144:147], v[214:217], v[84:87]
	v_mfma_f32_16x16x32_bf16 v[80:83], v[166:169], v[214:217], v[80:83]
	v_mfma_f32_16x16x32_bf16 v[124:127], v[162:165], v[194:197], v[124:127]
	v_mfma_f32_16x16x32_bf16 v[120:123], v[170:173], v[194:197], v[120:123]
	v_mfma_f32_16x16x32_bf16 v[112:115], v[162:165], v[202:205], v[112:115]
	v_mfma_f32_16x16x32_bf16 v[104:107], v[170:173], v[202:205], v[104:107]
	v_mfma_f32_16x16x32_bf16 v[92:95], v[162:165], v[210:213], v[92:95]
	v_mfma_f32_16x16x32_bf16 v[88:91], v[170:173], v[210:213], v[88:91]
	v_mfma_f32_16x16x32_bf16 v[84:87], v[162:165], v[218:221], v[84:87]
	v_mfma_f32_16x16x32_bf16 v[80:83], v[170:173], v[218:221], v[80:83]
	s_setprio 0
	s_setprio 1
	v_mfma_f32_16x16x32_bf16 v[116:119], v[174:177], v[190:193], v[116:119]
	v_mfma_f32_16x16x32_bf16 v[108:111], v[182:185], v[190:193], v[108:111]
	v_mfma_f32_16x16x32_bf16 v[100:103], v[174:177], v[198:201], v[100:103]
	v_mfma_f32_16x16x32_bf16 v[96:99], v[182:185], v[198:201], v[96:99]
	v_mfma_f32_16x16x32_bf16 v[76:79], v[174:177], v[206:209], v[76:79]
	v_mfma_f32_16x16x32_bf16 v[72:75], v[182:185], v[206:209], v[72:75]
	v_mfma_f32_16x16x32_bf16 v[68:71], v[174:177], v[214:217], v[68:71]
	v_mfma_f32_16x16x32_bf16 v[64:67], v[182:185], v[214:217], v[64:67]
	v_mfma_f32_16x16x32_bf16 v[116:119], v[178:181], v[194:197], v[116:119]
	v_mfma_f32_16x16x32_bf16 v[108:111], v[186:189], v[194:197], v[108:111]
	v_mfma_f32_16x16x32_bf16 v[100:103], v[178:181], v[202:205], v[100:103]
	v_mfma_f32_16x16x32_bf16 v[96:99], v[186:189], v[202:205], v[96:99]
	v_mfma_f32_16x16x32_bf16 v[76:79], v[178:181], v[210:213], v[76:79]
	v_mfma_f32_16x16x32_bf16 v[72:75], v[186:189], v[210:213], v[72:75]
	v_mfma_f32_16x16x32_bf16 v[68:71], v[178:181], v[218:221], v[68:71]
	v_mfma_f32_16x16x32_bf16 v[64:67], v[186:189], v[218:221], v[64:67]
	s_setprio 0
	s_barrier
	s_add_i32 s87, s75, s49
	v_lshl_add_u64 v[222:223], s[44:45], 0, v[130:131]
	s_mov_b32 m0, s87
	ds_read_b128 v[190:193], v161 offset:16384
	ds_read_b128 v[194:197], v161 offset:17408
	ds_read_b128 v[198:201], v161 offset:18432
	ds_read_b128 v[202:205], v161 offset:19456
	ds_read_b128 v[206:209], v161 offset:20480
	ds_read_b128 v[210:213], v161 offset:21504
	ds_read_b128 v[214:217], v161 offset:22528
	ds_read_b128 v[218:221], v161 offset:23552
	global_load_lds_dwordx4 v[222:223], off
	s_add_i32 m0, s87, 0x2000
	s_add_u32 s88, s44, 0x20000
	v_lshl_add_u64 v[224:225], s[44:45], 0, v[134:135]
	s_addc_u32 s89, s45, 0
	s_add_i32 s87, s76, s49
	global_load_lds_dwordx4 v[224:225], off
	v_lshl_add_u64 v[226:227], s[88:89], 0, v[130:131]
	s_mov_b32 m0, s87
	v_lshl_add_u64 v[228:229], s[46:47], 0, v[132:133]
	global_load_lds_dwordx4 v[226:227], off
	v_lshl_add_u64 v[226:227], s[88:89], 0, v[134:135]
	s_add_i32 m0, s87, 0x2000
	s_nop 0
	global_load_lds_dwordx4 v[226:227], off
	v_lshl_add_u64 v[226:227], s[46:47], 0, v[128:129]
	s_mov_b32 m0, s41
	s_nop 0
	global_load_lds_dwordx4 v[226:227], off
	s_mov_b32 m0, s51
	s_nop 0
	global_load_lds_dwordx4 v[228:229], off
	s_waitcnt vmcnt(8)
	s_waitcnt lgkmcnt(0)
	s_barrier
; #define PG8_STAGE(bufoff, gbase, voff) do { _Pragma("unroll") for (int _i = 0; _i < 2; ++_i) \
;         __builtin_amdgcn_global_load_lds((const unsigned*)((const char*)(gbase) + (voff)[_i]), (PG8_LAS unsigned*)(lds + (bufoff) + ldsw + _i * 8192), 16, 0, 0); } while (0)
; #define PG8_LDA(dst, b, h) do { _Pragma("unroll") for (int m = 0; m < 4; ++m) _Pragma("unroll") for (int k = 0; k < 2; ++k) dst[m][k] = *(const PG8_LAS bf16x8*)(lds + PG8_SA(b, h) + aoff + m * 2048 + k * 1024); } while (0)
; #define PG8_LDB(dst, b, h) do { _Pragma("unroll") for (int n = 0; n < 2; ++n) _Pragma("unroll") for (int k = 0; k < 2; ++k) dst[n][k] = *(const PG8_LAS bf16x8*)(lds + PG8_SB(b, h) + boff + n * 2048 + k * 1024); } while (0)
; #define PG8_MMA(ai, bj, At, Bt) do { __builtin_amdgcn_s_setprio(1); _Pragma("unroll") for (int m = 0; m < 4; ++m) _Pragma("unroll") for (int n = 0; n < 2; ++n) _Pragma("unroll") for (int k = 0; k < 2; ++k) \
;         acc[ai][bj][m][n] = __builtin_amdgcn_mfma_f32_16x16x32_bf16(Bt[n][k], At[m][k], acc[ai][bj][m][n], 0, 0, 0); __builtin_amdgcn_s_setprio(0); } while (0)
; #define PG8_WAIT_V(n) asm volatile("s_waitcnt vmcnt(" #n ")" ::: "memory")
; #define PG8_WAIT_L(n) asm volatile("s_waitcnt lgkmcnt(" #n ")" ::: "memory")
; #define PG8_BAR __builtin_amdgcn_s_barrier()
; #define PG8_SCHED __builtin_amdgcn_sched_barrier(0)
; template <class Epi, class Sched, bool ALIGN_EPI = false, bool SP2 = false>
; __device__ __forceinline__ void gemm_phase(PG8_LAS unsigned char* lds, const Gemm g, const Sched& S, const Epi& E) {
;     ...
;             PG8_WAIT_V(8); PG8_WAIT_L(0); PG8_BAR; PG8_MMA(1, 0, At, B0); PG8_MMA(1, 1, At, B1); PG8_BAR; PG8_SCHED;
;             PG8_LDB(B0, 1, 0); PG8_LDB(B1, 1, 1); PG8_SCHED; PG8_LDA(At, 1, 0); PG8_STAGE(PG8_SA(0, 1), a2 + hstep, voffA);
;             PG8_WAIT_V(8); PG8_WAIT_L(0); PG8_BAR; PG8_MMA(0, 0, At, B0); PG8_MMA(0, 1, At, B1); PG8_BAR; PG8_SCHED;
	s_setprio 1
	s_waitcnt lgkmcnt(0)
	v_mfma_f32_16x16x32_bf16 v[60:63], v[144:147], v[190:193], v[60:63]
	v_mfma_f32_16x16x32_bf16 v[56:59], v[166:169], v[190:193], v[56:59]
	v_mfma_f32_16x16x32_bf16 v[52:55], v[144:147], v[198:201], v[52:55]
	v_mfma_f32_16x16x32_bf16 v[48:51], v[166:169], v[198:201], v[48:51]
	v_mfma_f32_16x16x32_bf16 v[28:31], v[144:147], v[206:209], v[28:31]
	v_mfma_f32_16x16x32_bf16 v[24:27], v[166:169], v[206:209], v[24:27]
	v_mfma_f32_16x16x32_bf16 v[20:23], v[144:147], v[214:217], v[20:23]
	v_mfma_f32_16x16x32_bf16 v[16:19], v[166:169], v[214:217], v[16:19]
	v_mfma_f32_16x16x32_bf16 v[60:63], v[162:165], v[194:197], v[60:63]
	v_mfma_f32_16x16x32_bf16 v[56:59], v[170:173], v[194:197], v[56:59]
	v_mfma_f32_16x16x32_bf16 v[52:55], v[162:165], v[202:205], v[52:55]
	v_mfma_f32_16x16x32_bf16 v[48:51], v[170:173], v[202:205], v[48:51]
	v_mfma_f32_16x16x32_bf16 v[28:31], v[162:165], v[210:213], v[28:31]
	v_mfma_f32_16x16x32_bf16 v[24:27], v[170:173], v[210:213], v[24:27]
	v_mfma_f32_16x16x32_bf16 v[20:23], v[162:165], v[218:221], v[20:23]
	v_mfma_f32_16x16x32_bf16 v[16:19], v[170:173], v[218:221], v[16:19]
	s_setprio 0
	s_setprio 1
	v_mfma_f32_16x16x32_bf16 v[44:47], v[174:177], v[190:193], v[44:47]
	v_mfma_f32_16x16x32_bf16 v[40:43], v[182:185], v[190:193], v[40:43]
	v_mfma_f32_16x16x32_bf16 v[36:39], v[174:177], v[198:201], v[36:39]
	v_mfma_f32_16x16x32_bf16 v[32:35], v[182:185], v[198:201], v[32:35]
	v_mfma_f32_16x16x32_bf16 v[12:15], v[174:177], v[206:209], v[12:15]
	v_mfma_f32_16x16x32_bf16 v[8:11], v[182:185], v[206:209], v[8:11]
	v_mfma_f32_16x16x32_bf16 v[4:7], v[174:177], v[214:217], v[4:7]
	v_mfma_f32_16x16x32_bf16 v[0:3], v[182:185], v[214:217], v[0:3]
	v_mfma_f32_16x16x32_bf16 v[44:47], v[178:181], v[194:197], v[44:47]
	v_mfma_f32_16x16x32_bf16 v[40:43], v[186:189], v[194:197], v[40:43]
	v_mfma_f32_16x16x32_bf16 v[36:39], v[178:181], v[202:205], v[36:39]
	v_mfma_f32_16x16x32_bf16 v[32:35], v[186:189], v[202:205], v[32:35]
	v_mfma_f32_16x16x32_bf16 v[12:15], v[178:181], v[210:213], v[12:15]
	v_mfma_f32_16x16x32_bf16 v[8:11], v[186:189], v[210:213], v[8:11]
	v_mfma_f32_16x16x32_bf16 v[4:7], v[178:181], v[218:221], v[4:7]
	v_mfma_f32_16x16x32_bf16 v[0:3], v[186:189], v[218:221], v[0:3]
	s_setprio 0
	s_barrier
	s_add_i32 s87, 0, 0x18000
	s_add_i32 s88, 0, 0x1c000
	v_add_u32_e32 v170, s87, v157
	v_add_u32_e32 v186, s88, v157
	ds_read_b128 v[144:147], v170
	ds_read_b128 v[162:165], v170 offset:1024
	ds_read_b128 v[166:169], v170 offset:2048
	ds_read_b128 v[170:173], v170 offset:3072
	ds_read_b128 v[174:177], v186
	ds_read_b128 v[178:181], v186 offset:1024
	ds_read_b128 v[182:185], v186 offset:2048
	ds_read_b128 v[186:189], v186 offset:3072
	s_add_u32 s46, s46, 0x20000
	s_addc_u32 s47, s47, 0
	s_mov_b32 m0, s52
	v_lshl_add_u64 v[232:233], s[46:47], 0, v[128:129]
	ds_read_b128 v[190:193], v161 offset:32768
	ds_read_b128 v[194:197], v161 offset:33792
	ds_read_b128 v[198:201], v161 offset:34816
	ds_read_b128 v[202:205], v161 offset:35840
	ds_read_b128 v[206:209], v161 offset:36864
	ds_read_b128 v[210:213], v161 offset:37888
	ds_read_b128 v[214:217], v161 offset:38912
	ds_read_b128 v[218:221], v161 offset:39936
	global_load_lds_dwordx4 v[232:233], off
	v_lshl_add_u64 v[232:233], s[46:47], 0, v[132:133]
	s_mov_b32 m0, s53
	s_nop 0
	global_load_lds_dwordx4 v[232:233], off
	s_waitcnt vmcnt(8)
	s_waitcnt lgkmcnt(0)
	s_barrier
	s_setprio 1
	s_waitcnt lgkmcnt(0)
	v_mfma_f32_16x16x32_bf16 v[124:127], v[144:147], v[190:193], v[124:127]
	v_mfma_f32_16x16x32_bf16 v[120:123], v[166:169], v[190:193], v[120:123]
	v_mfma_f32_16x16x32_bf16 v[112:115], v[144:147], v[198:201], v[112:115]
	v_mfma_f32_16x16x32_bf16 v[104:107], v[166:169], v[198:201], v[104:107]
	v_mfma_f32_16x16x32_bf16 v[92:95], v[144:147], v[206:209], v[92:95]
	v_mfma_f32_16x16x32_bf16 v[88:91], v[166:169], v[206:209], v[88:91]
	v_mfma_f32_16x16x32_bf16 v[84:87], v[144:147], v[214:217], v[84:87]
	v_mfma_f32_16x16x32_bf16 v[80:83], v[166:169], v[214:217], v[80:83]
	v_mfma_f32_16x16x32_bf16 v[124:127], v[162:165], v[194:197], v[124:127]
	v_mfma_f32_16x16x32_bf16 v[120:123], v[170:173], v[194:197], v[120:123]
	v_mfma_f32_16x16x32_bf16 v[112:115], v[162:165], v[202:205], v[112:115]
	v_mfma_f32_16x16x32_bf16 v[104:107], v[170:173], v[202:205], v[104:107]
	v_mfma_f32_16x16x32_bf16 v[92:95], v[162:165], v[210:213], v[92:95]
	v_mfma_f32_16x16x32_bf16 v[88:91], v[170:173], v[210:213], v[88:91]
	v_mfma_f32_16x16x32_bf16 v[84:87], v[162:165], v[218:221], v[84:87]
	v_mfma_f32_16x16x32_bf16 v[80:83], v[170:173], v[218:221], v[80:83]
	s_setprio 0
	s_setprio 1
	v_mfma_f32_16x16x32_bf16 v[116:119], v[174:177], v[190:193], v[116:119]
	v_mfma_f32_16x16x32_bf16 v[108:111], v[182:185], v[190:193], v[108:111]
	v_mfma_f32_16x16x32_bf16 v[100:103], v[174:177], v[198:201], v[100:103]
	v_mfma_f32_16x16x32_bf16 v[96:99], v[182:185], v[198:201], v[96:99]
	v_mfma_f32_16x16x32_bf16 v[76:79], v[174:177], v[206:209], v[76:79]
	v_mfma_f32_16x16x32_bf16 v[72:75], v[182:185], v[206:209], v[72:75]
	v_mfma_f32_16x16x32_bf16 v[68:71], v[174:177], v[214:217], v[68:71]
	v_mfma_f32_16x16x32_bf16 v[64:67], v[182:185], v[214:217], v[64:67]
	v_mfma_f32_16x16x32_bf16 v[116:119], v[178:181], v[194:197], v[116:119]
	v_mfma_f32_16x16x32_bf16 v[108:111], v[186:189], v[194:197], v[108:111]
	v_mfma_f32_16x16x32_bf16 v[100:103], v[178:181], v[202:205], v[100:103]
	v_mfma_f32_16x16x32_bf16 v[96:99], v[186:189], v[202:205], v[96:99]
	v_mfma_f32_16x16x32_bf16 v[76:79], v[178:181], v[210:213], v[76:79]
	v_mfma_f32_16x16x32_bf16 v[72:75], v[186:189], v[210:213], v[72:75]
	v_mfma_f32_16x16x32_bf16 v[68:71], v[178:181], v[218:221], v[68:71]
	v_mfma_f32_16x16x32_bf16 v[64:67], v[186:189], v[218:221], v[64:67]
	s_setprio 0
	s_barrier
; #define PG8_STAGE(bufoff, gbase, voff) do { _Pragma("unroll") for (int _i = 0; _i < 2; ++_i) \
;         __builtin_amdgcn_global_load_lds((const unsigned*)((const char*)(gbase) + (voff)[_i]), (PG8_LAS unsigned*)(lds + (bufoff) + ldsw + _i * 8192), 16, 0, 0); } while (0)
; #define PG8_LDA(dst, b, h) do { _Pragma("unroll") for (int m = 0; m < 4; ++m) _Pragma("unroll") for (int k = 0; k < 2; ++k) dst[m][k] = *(const PG8_LAS bf16x8*)(lds + PG8_SA(b, h) + aoff + m * 2048 + k * 1024); } while (0)
; #define PG8_MMA(ai, bj, At, Bt) do { __builtin_amdgcn_s_setprio(1); _Pragma("unroll") for (int m = 0; m < 4; ++m) _Pragma("unroll") for (int n = 0; n < 2; ++n) _Pragma("unroll") for (int k = 0; k < 2; ++k) \
;         acc[ai][bj][m][n] = __builtin_amdgcn_mfma_f32_16x16x32_bf16(Bt[n][k], At[m][k], acc[ai][bj][m][n], 0, 0, 0); __builtin_amdgcn_s_setprio(0); } while (0)
; #define PG8_WAIT_V(n) asm volatile("s_waitcnt vmcnt(" #n ")" ::: "memory")
;     __device__ __forceinline__ void operator()(const f32x4 (&acc)[2][2][4][2], const Unit& u, int wr, int wc, int fr, int fq) const {
;         const int row0 = u.pm * BM + wr * 64 + fr, col0 = u.pn * BM + wc * 32 + 8 * fq;
;         const bf16_t* const G = (const bf16_t*)(ws + (ADD ? WS_GB : WS_GA)); bf16_t* const Mg = (bf16_t*)(ws + WS_GA);
; #pragma unroll
;         for (int ai = 0; ai < 2; ++ai)
; #pragma unroll
;         for (int mh = 0; mh < 4; mh += 2) {
;             u32x2 pg[4][2][2], pm_[4][2][2];
; #pragma unroll
;             for (int m = mh; m < mh + 2; ++m)
; #pragma unroll
;                 for (int bj = 0; bj < 2; ++bj)
; #pragma unroll
;                     for (int n = 0; n < 2; ++n) { const size_t off = (size_t)(row0 + ai * HALF + m * 16) * 1024 + col0 + bj * HALF + n * 4;
;                         pg[m][bj][n] = *(const u32x2*)(G + off); if (ADD) pm_[m][bj][n] = *(const u32x2*)(Mg + off); }
;             asm volatile("" ::: "memory");
; template <class Epi, class Sched, bool ALIGN_EPI = false, bool SP2 = false>
; __device__ __forceinline__ void gemm_phase(PG8_LAS unsigned char* lds, const Gemm g, const Sched& S, const Epi& E) {
;     ...
;             PG8_LDA(At, 1, 1); PG8_STAGE(PG8_SB(1, 0), b3, voffB); PG8_STAGE(PG8_SB(1, 1), b3 + hstep, voffB); PG8_STAGE(PG8_SA(1, 0), a3, voffA);
;             PG8_WAIT_V(8); PG8_WAIT_L(0); PG8_BAR; PG8_MMA(1, 0, At, B0); PG8_MMA(1, 1, At, B1); PG8_BAR; PG8_SCHED;
	s_add_i32 s46, s87, s49
	v_lshl_add_u64 v[222:223], v[222:223], 0, s[6:7]
	s_mov_b32 m0, s46
	ds_read_b128 v[190:193], v161 offset:49152
	ds_read_b128 v[194:197], v161 offset:50176
	ds_read_b128 v[198:201], v161 offset:51200
	ds_read_b128 v[202:205], v161 offset:52224
	ds_read_b128 v[206:209], v161 offset:53248
	ds_read_b128 v[210:213], v161 offset:54272
	ds_read_b128 v[214:217], v161 offset:55296
	ds_read_b128 v[218:221], v161 offset:56320
	global_load_lds_dwordx4 v[222:223], off
	s_add_i32 m0, s46, 0x2000
	s_add_u32 s44, s44, 0x20080
	v_lshl_add_u64 v[222:223], v[224:225], 0, s[6:7]
	s_addc_u32 s45, s45, 0
	s_add_i32 s46, s88, s49
	global_load_lds_dwordx4 v[222:223], off
	v_lshl_add_u64 v[222:223], s[44:45], 0, v[130:131]
	s_mov_b32 m0, s46
	s_nop 0
	global_load_lds_dwordx4 v[222:223], off
	v_lshl_add_u64 v[222:223], s[44:45], 0, v[134:135]
	s_add_i32 m0, s46, 0x2000
	s_nop 0
	global_load_lds_dwordx4 v[222:223], off
	v_lshl_add_u64 v[222:223], v[226:227], 0, s[6:7]
	s_mov_b32 m0, s61
	s_nop 0
	global_load_lds_dwordx4 v[222:223], off
	v_lshl_add_u64 v[222:223], v[228:229], 0, s[6:7]
	s_mov_b32 m0, s72
	s_nop 0
	global_load_lds_dwordx4 v[222:223], off
	s_waitcnt vmcnt(8)
	s_waitcnt lgkmcnt(0)
	s_barrier
	s_setprio 1
	s_waitcnt lgkmcnt(0)
	v_mfma_f32_16x16x32_bf16 v[60:63], v[144:147], v[190:193], v[60:63]
	v_mfma_f32_16x16x32_bf16 v[56:59], v[166:169], v[190:193], v[56:59]
	v_mfma_f32_16x16x32_bf16 v[52:55], v[144:147], v[198:201], v[52:55]
	v_mfma_f32_16x16x32_bf16 v[48:51], v[166:169], v[198:201], v[48:51]
	v_mfma_f32_16x16x32_bf16 v[28:31], v[144:147], v[206:209], v[28:31]
	v_mfma_f32_16x16x32_bf16 v[24:27], v[166:169], v[206:209], v[24:27]
	v_mfma_f32_16x16x32_bf16 v[20:23], v[144:147], v[214:217], v[20:23]
	v_mfma_f32_16x16x32_bf16 v[16:19], v[166:169], v[214:217], v[16:19]
	v_mfma_f32_16x16x32_bf16 v[60:63], v[162:165], v[194:197], v[60:63]
	v_mfma_f32_16x16x32_bf16 v[56:59], v[170:173], v[194:197], v[56:59]
	v_mfma_f32_16x16x32_bf16 v[52:55], v[162:165], v[202:205], v[52:55]
	v_mfma_f32_16x16x32_bf16 v[48:51], v[170:173], v[202:205], v[48:51]
	v_mfma_f32_16x16x32_bf16 v[28:31], v[162:165], v[210:213], v[28:31]
	v_mfma_f32_16x16x32_bf16 v[24:27], v[170:173], v[210:213], v[24:27]
	v_mfma_f32_16x16x32_bf16 v[20:23], v[162:165], v[218:221], v[20:23]
	v_mfma_f32_16x16x32_bf16 v[16:19], v[170:173], v[218:221], v[16:19]
	s_setprio 0
	s_setprio 1
	v_mfma_f32_16x16x32_bf16 v[44:47], v[174:177], v[190:193], v[44:47]
	v_mfma_f32_16x16x32_bf16 v[40:43], v[182:185], v[190:193], v[40:43]
	v_mfma_f32_16x16x32_bf16 v[36:39], v[174:177], v[198:201], v[36:39]
	v_mfma_f32_16x16x32_bf16 v[32:35], v[182:185], v[198:201], v[32:35]
	v_mfma_f32_16x16x32_bf16 v[12:15], v[174:177], v[206:209], v[12:15]
	v_mfma_f32_16x16x32_bf16 v[8:11], v[182:185], v[206:209], v[8:11]
	v_mfma_f32_16x16x32_bf16 v[4:7], v[174:177], v[214:217], v[4:7]
	v_mfma_f32_16x16x32_bf16 v[0:3], v[182:185], v[214:217], v[0:3]
	v_mfma_f32_16x16x32_bf16 v[44:47], v[178:181], v[194:197], v[44:47]
	v_mfma_f32_16x16x32_bf16 v[40:43], v[186:189], v[194:197], v[40:43]
	v_mfma_f32_16x16x32_bf16 v[36:39], v[178:181], v[202:205], v[36:39]
	v_mfma_f32_16x16x32_bf16 v[32:35], v[186:189], v[202:205], v[32:35]
	v_mfma_f32_16x16x32_bf16 v[12:15], v[178:181], v[210:213], v[12:15]
	v_mfma_f32_16x16x32_bf16 v[8:11], v[186:189], v[210:213], v[8:11]
	v_mfma_f32_16x16x32_bf16 v[4:7], v[178:181], v[218:221], v[4:7]
	v_mfma_f32_16x16x32_bf16 v[0:3], v[186:189], v[218:221], v[0:3]
	s_setprio 0
	s_barrier
	s_add_i32 s86, s86, 2
	s_add_u32 s42, s42, 0x100
	s_addc_u32 s43, s43, 0
	s_add_u32 s84, s84, 0x100
	s_addc_u32 s85, s85, 0
	s_cmp_gt_u32 s86, 5
	s_cbranch_scc0 .LBB0_735
	s_cmpk_gt_u32 s48, 0xff
	s_cbranch_scc1 .Lal_p6a_pre
	s_barrier
.Lal_p6a_pre:
	v_lshl_add_u32 v178, s40, 8, v156
	v_lshl_or_b32 v144, s81, 8, v158
	v_ashrrev_i32_e32 v145, 31, v144
	v_ashrrev_i32_e32 v179, 31, v178
	v_lshl_add_u64 v[180:181], v[144:145], 1, s[0:1]
	v_lshlrev_b64 v[144:145], 11, v[178:179]
	v_or_b32_e32 v146, 16, v178
	v_lshl_add_u64 v[144:145], v[180:181], 0, v[144:145]
	v_ashrrev_i32_e32 v147, 31, v146
	global_load_dwordx4 v[162:165], v[144:145], off
	global_load_dwordx4 v[166:169], v[144:145], off offset:256
	v_lshlrev_b64 v[146:147], 11, v[146:147]
	v_lshl_add_u64 v[182:183], v[180:181], 0, v[146:147]
	global_load_dwordx4 v[170:173], v[182:183], off
	global_load_dwordx4 v[174:177], v[182:183], off offset:256
	v_or_b32_e32 v146, 32, v178
	v_ashrrev_i32_e32 v147, 31, v146
	v_lshlrev_b64 v[146:147], 11, v[146:147]
	v_lshl_add_u64 v[146:147], v[180:181], 0, v[146:147]
	s_mov_b32 s81, s24
	s_mov_b32 s40, s26
	s_mov_b64 s[44:45], s[38:39]
	s_mov_b64 s[42:43], s[36:37]
	s_waitcnt vmcnt(0)
; __device__ __forceinline__ u32x2 pack4(f32x4 v) { u32x2 w; w.x = cvt_pk_bf16(v[0], v[1]); w.y = cvt_pk_bf16(v[2], v[3]); return w; }
; __device__ __forceinline__ f32x4 unpack4(u32x2 w) { f32x4 v; v[0] = __uint_as_float(w.x << 16); v[1] = __uint_as_float(w.x & 0xffff0000u); v[2] = __uint_as_float(w.y << 16); v[3] = __uint_as_float(w.y & 0xffff0000u); return v; }
;     __device__ __forceinline__ void operator()(const f32x4 (&acc)[2][2][4][2], const Unit& u, int wr, int wc, int fr, int fq) const {
;         const int row0 = u.pm * BM + wr * 64 + fr, col0 = u.pn * BM + wc * 32 + 8 * fq;
;         const bf16_t* const G = (const bf16_t*)(ws + (ADD ? WS_GB : WS_GA)); bf16_t* const Mg = (bf16_t*)(ws + WS_GA);
; #pragma unroll
;         for (int ai = 0; ai < 2; ++ai)
; #pragma unroll
;         for (int mh = 0; mh < 4; mh += 2) {
;             u32x2 pg[4][2][2], pm_[4][2][2];
; #pragma unroll
;             for (int m = mh; m < mh + 2; ++m)
; #pragma unroll
;                 for (int bj = 0; bj < 2; ++bj)
; #pragma unroll
;                     for (int n = 0; n < 2; ++n) { const size_t off = (size_t)(row0 + ai * HALF + m * 16) * 1024 + col0 + bj * HALF + n * 4;
;                         pg[m][bj][n] = *(const u32x2*)(G + off); if (ADD) pm_[m][bj][n] = *(const u32x2*)(Mg + off); }
;             asm volatile("" ::: "memory");
; #pragma unroll
;             for (int m = mh; m < mh + 2; ++m)
; #pragma unroll
;                 for (int bj = 0; bj < 2; ++bj)
; #pragma unroll
;                     for (int n = 0; n < 2; ++n) { const size_t off = (size_t)(row0 + ai * HALF + m * 16) * 1024 + col0 + bj * HALF + n * 4;
;                         f32x4 o = unpack4(pg[m][bj][n]) * acc[ai][bj][m][n]; if (ADD) o = o + unpack4(pm_[m][bj][n]);
;                         *(u32x2*)(Mg + off) = pack4(o); }
;             asm volatile("" ::: "memory");
;         }
	v_lshlrev_b32_e32 v184, 16, v162
	v_and_b32_e32 v185, 0xffff0000, v162
	v_lshlrev_b32_e32 v162, 16, v163
	v_and_b32_e32 v163, 0xffff0000, v163
	v_lshlrev_b32_e32 v188, 16, v166
	v_and_b32_e32 v189, 0xffff0000, v166
	v_lshlrev_b32_e32 v166, 16, v167
	v_and_b32_e32 v167, 0xffff0000, v167
	v_lshlrev_b32_e32 v190, 16, v168
	v_and_b32_e32 v191, 0xffff0000, v168
	v_lshlrev_b32_e32 v168, 16, v169
	v_and_b32_e32 v169, 0xffff0000, v169
	v_lshlrev_b32_e32 v186, 16, v164
	v_and_b32_e32 v187, 0xffff0000, v164
	v_lshlrev_b32_e32 v164, 16, v165
	v_and_b32_e32 v165, 0xffff0000, v165
	v_pk_mul_f32 v[126:127], v[126:127], v[162:163]
	v_pk_mul_f32 v[118:119], v[118:119], v[166:167]
	v_pk_mul_f32 v[162:163], v[110:111], v[168:169]
	v_lshlrev_b32_e32 v166, 16, v170
	v_and_b32_e32 v167, 0xffff0000, v170
	v_lshlrev_b32_e32 v168, 16, v171
	v_and_b32_e32 v169, 0xffff0000, v171
	v_lshlrev_b32_e32 v170, 16, v172
	v_and_b32_e32 v171, 0xffff0000, v172
	v_lshlrev_b32_e32 v172, 16, v173
	v_and_b32_e32 v173, 0xffff0000, v173
	v_pk_mul_f32 v[124:125], v[124:125], v[184:185]
	v_pk_mul_f32 v[122:123], v[122:123], v[164:165]
	v_pk_mul_f32 v[120:121], v[120:121], v[186:187]
	v_lshlrev_b32_e32 v184, 16, v174
	v_and_b32_e32 v185, 0xffff0000, v174
	v_lshlrev_b32_e32 v174, 16, v175
	v_and_b32_e32 v175, 0xffff0000, v175
	v_lshlrev_b32_e32 v186, 16, v176
	v_and_b32_e32 v187, 0xffff0000, v176
	v_lshlrev_b32_e32 v176, 16, v177
	v_and_b32_e32 v177, 0xffff0000, v177
	v_pk_mul_f32 v[114:115], v[114:115], v[168:169]
	v_pk_mul_f32 v[112:113], v[112:113], v[166:167]
	v_pk_mul_f32 v[106:107], v[106:107], v[172:173]
	v_pk_mul_f32 v[104:105], v[104:105], v[170:171]
	v_pk_mul_f32 v[116:117], v[116:117], v[188:189]
	v_pk_mul_f32 v[164:165], v[108:109], v[190:191]
	v_cvt_pk_bf16_f32 v108, v124, v125
	v_cvt_pk_bf16_f32 v109, v126, v127
	v_cvt_pk_bf16_f32 v110, v120, v121
	v_cvt_pk_bf16_f32 v111, v122, v123
	v_pk_mul_f32 v[102:103], v[102:103], v[174:175]
	v_pk_mul_f32 v[100:101], v[100:101], v[184:185]
	v_pk_mul_f32 v[120:121], v[98:99], v[176:177]
	v_pk_mul_f32 v[122:123], v[96:97], v[186:187]
	v_cvt_pk_bf16_f32 v96, v112, v113
	v_cvt_pk_bf16_f32 v97, v114, v115
	v_cvt_pk_bf16_f32 v98, v104, v105
	v_cvt_pk_bf16_f32 v99, v106, v107
	v_cvt_pk_bf16_f32 v116, v116, v117
	v_cvt_pk_bf16_f32 v117, v118, v119
	v_cvt_pk_bf16_f32 v118, v164, v165
	v_cvt_pk_bf16_f32 v119, v162, v163
	global_store_dwordx4 v[144:145], v[108:111], off
	global_store_dwordx4 v[144:145], v[116:119], off offset:256
	v_cvt_pk_bf16_f32 v100, v100, v101
	v_cvt_pk_bf16_f32 v101, v102, v103
	v_cvt_pk_bf16_f32 v102, v122, v123
	v_cvt_pk_bf16_f32 v103, v120, v121
	global_store_dwordx4 v[182:183], v[96:99], off
	global_store_dwordx4 v[182:183], v[100:103], off offset:256
	global_load_dwordx4 v[98:101], v[146:147], off
	global_load_dwordx4 v[102:105], v[146:147], off offset:256
	v_or_b32_e32 v96, 48, v178
	v_ashrrev_i32_e32 v97, 31, v96
	v_lshlrev_b64 v[96:97], 11, v[96:97]
	v_lshl_add_u64 v[114:115], v[180:181], 0, v[96:97]
	global_load_dwordx4 v[106:109], v[114:115], off
	global_load_dwordx4 v[110:113], v[114:115], off offset:256
	v_add_co_u32_e32 v96, vcc, s77, v144
	s_waitcnt vmcnt(3)
	v_lshlrev_b32_e32 v116, 16, v98
	v_and_b32_e32 v117, 0xffff0000, v98
	v_lshlrev_b32_e32 v98, 16, v99
	v_and_b32_e32 v99, 0xffff0000, v99
	v_lshlrev_b32_e32 v118, 16, v100
	v_and_b32_e32 v119, 0xffff0000, v100
	v_lshlrev_b32_e32 v100, 16, v101
	v_and_b32_e32 v101, 0xffff0000, v101
	s_waitcnt vmcnt(2)
	v_lshlrev_b32_e32 v120, 16, v102
	v_and_b32_e32 v121, 0xffff0000, v102
	v_lshlrev_b32_e32 v102, 16, v103
	v_and_b32_e32 v103, 0xffff0000, v103
	v_lshlrev_b32_e32 v122, 16, v104
	v_and_b32_e32 v123, 0xffff0000, v104
	v_lshlrev_b32_e32 v104, 16, v105
	v_and_b32_e32 v105, 0xffff0000, v105
	s_waitcnt vmcnt(1)
	v_lshlrev_b32_e32 v124, 16, v106
	v_and_b32_e32 v125, 0xffff0000, v106
	v_lshlrev_b32_e32 v106, 16, v107
	v_and_b32_e32 v107, 0xffff0000, v107
	v_lshlrev_b32_e32 v126, 16, v108
	v_and_b32_e32 v127, 0xffff0000, v108
	v_lshlrev_b32_e32 v108, 16, v109
	v_and_b32_e32 v109, 0xffff0000, v109
	s_waitcnt vmcnt(0)
	v_lshlrev_b32_e32 v162, 16, v110
	v_and_b32_e32 v163, 0xffff0000, v110
	v_lshlrev_b32_e32 v110, 16, v111
	v_and_b32_e32 v111, 0xffff0000, v111
	v_lshlrev_b32_e32 v164, 16, v112
	v_and_b32_e32 v165, 0xffff0000, v112
	v_lshlrev_b32_e32 v112, 16, v113
	v_and_b32_e32 v113, 0xffff0000, v113
	v_pk_mul_f32 v[94:95], v[94:95], v[98:99]
	v_pk_mul_f32 v[92:93], v[92:93], v[116:117]
	v_pk_mul_f32 v[90:91], v[90:91], v[100:101]
	v_pk_mul_f32 v[88:89], v[88:89], v[118:119]
	v_pk_mul_f32 v[78:79], v[78:79], v[102:103]
	v_pk_mul_f32 v[76:77], v[76:77], v[120:121]
	v_pk_mul_f32 v[74:75], v[74:75], v[104:105]
	v_pk_mul_f32 v[72:73], v[72:73], v[122:123]
	v_pk_mul_f32 v[86:87], v[86:87], v[106:107]
	v_pk_mul_f32 v[84:85], v[84:85], v[124:125]
	v_pk_mul_f32 v[82:83], v[82:83], v[108:109]
	v_pk_mul_f32 v[80:81], v[80:81], v[126:127]
	v_pk_mul_f32 v[98:99], v[70:71], v[110:111]
	v_pk_mul_f32 v[100:101], v[68:69], v[162:163]
	v_pk_mul_f32 v[102:103], v[66:67], v[112:113]
	v_pk_mul_f32 v[104:105], v[64:65], v[164:165]
	v_cvt_pk_bf16_f32 v64, v92, v93
	v_cvt_pk_bf16_f32 v65, v94, v95
	v_cvt_pk_bf16_f32 v66, v88, v89
	v_cvt_pk_bf16_f32 v67, v90, v91
	v_addc_co_u32_e32 v97, vcc, 0, v145, vcc
	v_cvt_pk_bf16_f32 v68, v76, v77
	v_cvt_pk_bf16_f32 v69, v78, v79
	v_cvt_pk_bf16_f32 v70, v72, v73
	v_cvt_pk_bf16_f32 v71, v74, v75
	v_cvt_pk_bf16_f32 v72, v84, v85
	v_cvt_pk_bf16_f32 v73, v86, v87
	v_cvt_pk_bf16_f32 v74, v80, v81
	v_cvt_pk_bf16_f32 v75, v82, v83
	v_cvt_pk_bf16_f32 v76, v100, v101
	v_cvt_pk_bf16_f32 v77, v98, v99
	v_cvt_pk_bf16_f32 v78, v104, v105
	v_cvt_pk_bf16_f32 v79, v102, v103
	global_store_dwordx4 v[146:147], v[64:67], off
	global_store_dwordx4 v[146:147], v[68:71], off offset:256
	global_store_dwordx4 v[114:115], v[72:75], off
	global_store_dwordx4 v[114:115], v[76:79], off offset:256
	v_add_co_u32_e32 v84, vcc, s78, v144
	global_load_dwordx4 v[66:69], v[96:97], off
	v_lshl_add_u64 v[82:83], v[144:145], 0, s[12:13]
	v_addc_co_u32_e32 v85, vcc, 0, v145, vcc
	v_lshl_add_u64 v[86:87], v[144:145], 0, s[14:15]
	global_load_dwordx4 v[70:73], v[82:83], off offset:256
	global_load_dwordx4 v[74:77], v[84:85], off
	global_load_dwordx4 v[78:81], v[86:87], off offset:256
	v_add_co_u32_e32 v64, vcc, s79, v144
	s_waitcnt vmcnt(3)
; __device__ __forceinline__ u32x2 pack4(f32x4 v) { u32x2 w; w.x = cvt_pk_bf16(v[0], v[1]); w.y = cvt_pk_bf16(v[2], v[3]); return w; }
; __device__ __forceinline__ f32x4 unpack4(u32x2 w) { f32x4 v; v[0] = __uint_as_float(w.x << 16); v[1] = __uint_as_float(w.x & 0xffff0000u); v[2] = __uint_as_float(w.y << 16); v[3] = __uint_as_float(w.y & 0xffff0000u); return v; }
; #define PG8_BAR __builtin_amdgcn_s_barrier()
;     __device__ __forceinline__ void operator()(const f32x4 (&acc)[2][2][4][2], const Unit& u, int wr, int wc, int fr, int fq) const {
;     ...
; #pragma unroll
;             for (int m = mh; m < mh + 2; ++m)
; #pragma unroll
;                 for (int bj = 0; bj < 2; ++bj)
; #pragma unroll
;                     for (int n = 0; n < 2; ++n) { const size_t off = (size_t)(row0 + ai * HALF + m * 16) * 1024 + col0 + bj * HALF + n * 4;
;                         f32x4 o = unpack4(pg[m][bj][n]) * acc[ai][bj][m][n]; if (ADD) o = o + unpack4(pm_[m][bj][n]);
;                         *(u32x2*)(Mg + off) = pack4(o); }
;             asm volatile("" ::: "memory");
;         }
; template <class Epi, class Sched, bool ALIGN_EPI = false, bool SP2 = false>
; __device__ __forceinline__ void gemm_phase(PG8_LAS unsigned char* lds, const Gemm g, const Sched& S, const Epi& E) {
;     ...
;         if (!has_next) break;
; #pragma unroll
;         for (int a = 0; a < 2; ++a)
; #pragma unroll
;             for (int b = 0; b < 2; ++b)
; #pragma unroll
;                 for (int m = 0; m < 4; ++m)
; #pragma unroll
;                     for (int n = 0; n < 2; ++n) acc[a][b][m][n] = (f32x4){0.f, 0.f, 0.f, 0.f};
;         cur = nxt; cA = nA; cB = nB; ++ui;
;         if constexpr (ALIGN_EPI) { if (wr == 1) PG8_BAR; }
	v_lshlrev_b32_e32 v88, 16, v66
	v_and_b32_e32 v89, 0xffff0000, v66
	v_lshlrev_b32_e32 v66, 16, v67
	v_and_b32_e32 v67, 0xffff0000, v67
	v_lshlrev_b32_e32 v90, 16, v68
	v_and_b32_e32 v91, 0xffff0000, v68
	v_lshlrev_b32_e32 v68, 16, v69
	v_and_b32_e32 v69, 0xffff0000, v69
	s_waitcnt vmcnt(2)
	v_lshlrev_b32_e32 v92, 16, v70
	v_and_b32_e32 v93, 0xffff0000, v70
	v_lshlrev_b32_e32 v70, 16, v71
	v_and_b32_e32 v71, 0xffff0000, v71
	v_lshlrev_b32_e32 v94, 16, v72
	v_and_b32_e32 v95, 0xffff0000, v72
	v_lshlrev_b32_e32 v72, 16, v73
	v_and_b32_e32 v73, 0xffff0000, v73
	s_waitcnt vmcnt(1)
	v_lshlrev_b32_e32 v98, 16, v74
	v_and_b32_e32 v99, 0xffff0000, v74
	v_lshlrev_b32_e32 v74, 16, v75
	v_and_b32_e32 v75, 0xffff0000, v75
	v_lshlrev_b32_e32 v100, 16, v76
	v_and_b32_e32 v101, 0xffff0000, v76
	v_lshlrev_b32_e32 v76, 16, v77
	v_and_b32_e32 v77, 0xffff0000, v77
	s_waitcnt vmcnt(0)
	v_lshlrev_b32_e32 v102, 16, v78
	v_and_b32_e32 v103, 0xffff0000, v78
	v_lshlrev_b32_e32 v78, 16, v79
	v_and_b32_e32 v79, 0xffff0000, v79
	v_lshlrev_b32_e32 v104, 16, v80
	v_and_b32_e32 v105, 0xffff0000, v80
	v_lshlrev_b32_e32 v80, 16, v81
	v_and_b32_e32 v81, 0xffff0000, v81
	v_pk_mul_f32 v[62:63], v[62:63], v[66:67]
	v_pk_mul_f32 v[60:61], v[60:61], v[88:89]
	v_pk_mul_f32 v[58:59], v[58:59], v[68:69]
	v_pk_mul_f32 v[56:57], v[56:57], v[90:91]
	v_pk_mul_f32 v[46:47], v[46:47], v[70:71]
	v_pk_mul_f32 v[44:45], v[44:45], v[92:93]
	v_pk_mul_f32 v[42:43], v[42:43], v[72:73]
	v_pk_mul_f32 v[40:41], v[40:41], v[94:95]
	v_pk_mul_f32 v[54:55], v[54:55], v[74:75]
	v_pk_mul_f32 v[52:53], v[52:53], v[98:99]
	v_pk_mul_f32 v[50:51], v[50:51], v[76:77]
	v_pk_mul_f32 v[48:49], v[48:49], v[100:101]
	v_pk_mul_f32 v[66:67], v[38:39], v[78:79]
	v_pk_mul_f32 v[68:69], v[36:37], v[102:103]
	v_pk_mul_f32 v[70:71], v[34:35], v[80:81]
	v_pk_mul_f32 v[72:73], v[32:33], v[104:105]
	v_cvt_pk_bf16_f32 v32, v60, v61
	v_cvt_pk_bf16_f32 v33, v62, v63
	v_cvt_pk_bf16_f32 v34, v56, v57
	v_cvt_pk_bf16_f32 v35, v58, v59
	v_addc_co_u32_e32 v65, vcc, 0, v145, vcc
	v_cvt_pk_bf16_f32 v36, v44, v45
	v_cvt_pk_bf16_f32 v37, v46, v47
	v_cvt_pk_bf16_f32 v38, v40, v41
	v_cvt_pk_bf16_f32 v39, v42, v43
	v_cvt_pk_bf16_f32 v40, v52, v53
	v_cvt_pk_bf16_f32 v41, v54, v55
	v_cvt_pk_bf16_f32 v42, v48, v49
	v_cvt_pk_bf16_f32 v43, v50, v51
	v_cvt_pk_bf16_f32 v44, v68, v69
	v_cvt_pk_bf16_f32 v45, v66, v67
	v_cvt_pk_bf16_f32 v46, v72, v73
	v_cvt_pk_bf16_f32 v47, v70, v71
	global_store_dwordx4 v[96:97], v[32:35], off
	global_store_dwordx4 v[82:83], v[36:39], off offset:256
	global_store_dwordx4 v[84:85], v[40:43], off
	global_store_dwordx4 v[86:87], v[44:47], off offset:256
	v_add_co_u32_e32 v50, vcc, s80, v144
	global_load_dwordx4 v[32:35], v[64:65], off
	v_lshl_add_u64 v[48:49], v[144:145], 0, s[20:21]
	v_addc_co_u32_e32 v51, vcc, 0, v145, vcc
	v_lshl_add_u64 v[52:53], v[144:145], 0, s[22:23]
	global_load_dwordx4 v[36:39], v[48:49], off offset:256
	global_load_dwordx4 v[40:43], v[50:51], off
	global_load_dwordx4 v[44:47], v[52:53], off offset:256
	s_and_b64 vcc, exec, s[2:3]
	s_waitcnt vmcnt(3)
	v_lshlrev_b32_e32 v54, 16, v32
	v_and_b32_e32 v55, 0xffff0000, v32
	v_lshlrev_b32_e32 v32, 16, v33
	v_and_b32_e32 v33, 0xffff0000, v33
	v_lshlrev_b32_e32 v56, 16, v34
	v_and_b32_e32 v57, 0xffff0000, v34
	v_lshlrev_b32_e32 v34, 16, v35
	v_and_b32_e32 v35, 0xffff0000, v35
	s_waitcnt vmcnt(2)
	v_lshlrev_b32_e32 v58, 16, v36
	v_and_b32_e32 v59, 0xffff0000, v36
	v_lshlrev_b32_e32 v36, 16, v37
	v_and_b32_e32 v37, 0xffff0000, v37
	v_lshlrev_b32_e32 v60, 16, v38
	v_and_b32_e32 v61, 0xffff0000, v38
	v_lshlrev_b32_e32 v38, 16, v39
	v_and_b32_e32 v39, 0xffff0000, v39
	s_waitcnt vmcnt(1)
	v_lshlrev_b32_e32 v62, 16, v40
	v_and_b32_e32 v63, 0xffff0000, v40
	v_lshlrev_b32_e32 v40, 16, v41
	v_and_b32_e32 v41, 0xffff0000, v41
	v_lshlrev_b32_e32 v66, 16, v42
	v_and_b32_e32 v67, 0xffff0000, v42
	v_lshlrev_b32_e32 v42, 16, v43
	v_and_b32_e32 v43, 0xffff0000, v43
	s_waitcnt vmcnt(0)
	v_lshlrev_b32_e32 v68, 16, v44
	v_and_b32_e32 v69, 0xffff0000, v44
	v_lshlrev_b32_e32 v44, 16, v45
	v_and_b32_e32 v45, 0xffff0000, v45
	v_lshlrev_b32_e32 v70, 16, v46
	v_and_b32_e32 v71, 0xffff0000, v46
	v_lshlrev_b32_e32 v46, 16, v47
	v_and_b32_e32 v47, 0xffff0000, v47
	v_pk_mul_f32 v[30:31], v[30:31], v[32:33]
	v_pk_mul_f32 v[28:29], v[28:29], v[54:55]
	v_pk_mul_f32 v[26:27], v[26:27], v[34:35]
	v_pk_mul_f32 v[24:25], v[24:25], v[56:57]
	v_pk_mul_f32 v[14:15], v[14:15], v[36:37]
	v_pk_mul_f32 v[12:13], v[12:13], v[58:59]
	v_pk_mul_f32 v[10:11], v[10:11], v[38:39]
	v_pk_mul_f32 v[8:9], v[8:9], v[60:61]
	v_pk_mul_f32 v[22:23], v[22:23], v[40:41]
	v_pk_mul_f32 v[20:21], v[20:21], v[62:63]
	v_pk_mul_f32 v[18:19], v[18:19], v[42:43]
	v_pk_mul_f32 v[16:17], v[16:17], v[66:67]
	v_pk_mul_f32 v[32:33], v[6:7], v[44:45]
	v_pk_mul_f32 v[34:35], v[4:5], v[68:69]
	v_pk_mul_f32 v[36:37], v[2:3], v[46:47]
	v_pk_mul_f32 v[38:39], v[0:1], v[70:71]
	v_cvt_pk_bf16_f32 v0, v28, v29
	v_cvt_pk_bf16_f32 v1, v30, v31
	v_cvt_pk_bf16_f32 v2, v24, v25
	v_cvt_pk_bf16_f32 v3, v26, v27
	v_cvt_pk_bf16_f32 v4, v12, v13
	v_cvt_pk_bf16_f32 v5, v14, v15
	v_cvt_pk_bf16_f32 v6, v8, v9
	v_cvt_pk_bf16_f32 v7, v10, v11
	v_cvt_pk_bf16_f32 v8, v20, v21
	v_cvt_pk_bf16_f32 v9, v22, v23
	v_cvt_pk_bf16_f32 v10, v16, v17
	v_cvt_pk_bf16_f32 v11, v18, v19
	v_cvt_pk_bf16_f32 v12, v34, v35
	v_cvt_pk_bf16_f32 v13, v32, v33
	v_cvt_pk_bf16_f32 v14, v38, v39
	v_cvt_pk_bf16_f32 v15, v36, v37
	global_store_dwordx4 v[64:65], v[0:3], off
	global_store_dwordx4 v[48:49], v[4:7], off offset:256
	global_store_dwordx4 v[50:51], v[8:11], off
	global_store_dwordx4 v[52:53], v[12:15], off offset:256
	s_cbranch_vccnz .Lal_p6a_exit
	s_cmpk_lt_u32 s48, 0x100
	s_cbranch_scc1 .LBB0_732
	s_barrier
	s_branch .LBB0_732
.Lal_p6a_exit:
	s_waitcnt vmcnt(0)
.LBB0_739:
	s_barrier

; #define PG8_STAGE(bufoff, gbase, voff) do { _Pragma("unroll") for (int _i = 0; _i < 2; ++_i) \
;         __builtin_amdgcn_global_load_lds((const unsigned*)((const char*)(gbase) + (voff)[_i]), (PG8_LAS unsigned*)(lds + (bufoff) + ldsw + _i * 8192), 16, 0, 0); } while (0)
; #define PG8_LDA(dst, b, h) do { _Pragma("unroll") for (int m = 0; m < 4; ++m) _Pragma("unroll") for (int k = 0; k < 2; ++k) dst[m][k] = *(const PG8_LAS bf16x8*)(lds + PG8_SA(b, h) + aoff + m * 2048 + k * 1024); } while (0)
; #define PG8_LDB(dst, b, h) do { _Pragma("unroll") for (int n = 0; n < 2; ++n) _Pragma("unroll") for (int k = 0; k < 2; ++k) dst[n][k] = *(const PG8_LAS bf16x8*)(lds + PG8_SB(b, h) + boff + n * 2048 + k * 1024); } while (0)
; #define PG8_MMA(ai, bj, At, Bt) do { __builtin_amdgcn_s_setprio(1); _Pragma("unroll") for (int m = 0; m < 4; ++m) _Pragma("unroll") for (int n = 0; n < 2; ++n) _Pragma("unroll") for (int k = 0; k < 2; ++k) \
;         acc[ai][bj][m][n] = __builtin_amdgcn_mfma_f32_16x16x32_bf16(Bt[n][k], At[m][k], acc[ai][bj][m][n], 0, 0, 0); __builtin_amdgcn_s_setprio(0); } while (0)
; #define PG8_WAIT_V(n) asm volatile("s_waitcnt vmcnt(" #n ")" ::: "memory")
; template <class Epi, class Sched, bool ALIGN_EPI = false, bool SP2 = false>
; __device__ __forceinline__ void gemm_phase(PG8_LAS unsigned char* lds, const Gemm g, const Sched& S, const Epi& E) {
;     ...
;         const char* nA = has_next ? (const char*)g.A + (size_t)nxt.pm * tstep : cA; const char* nB = has_next ? (const char*)g.Bt + (size_t)nxt.pn * tstep : cB;
;         for (int t = 0; t < nt; t += 2) {
;             const bool last = (t == nt - 2);
;             const char* a1 = cA + (size_t)(t + 1) * kstep;
;             const char* a2 = last ? nA : cA + (size_t)(t + 2) * kstep; const char* b2 = last ? nB : cB + (size_t)(t + 2) * kstep;
;             const char* a3 = a2 + kstep; const char* b3 = b2 + kstep;
;             if (last && has_next) S.a_ready(nxt);
;             if constexpr (SP2) {
;             PG8_LDB(B0, 0, 0); PG8_LDB(B1, 0, 1); PG8_SCHED; PG8_LDA(At, 0, 0); PG8_STAGE(PG8_SA(1, 1), a1 + hstep, voffA);
;             PG8_WAIT_V(8); PG8_WAIT_L(0); PG8_BAR; PG8_MMA(0, 0, At, B0); PG8_MMA(0, 1, At, B1); PG8_BAR; PG8_SCHED;
;             PG8_LDA(At, 0, 1); PG8_STAGE(PG8_SB(0, 0), b2, voffB); PG8_STAGE(PG8_SB(0, 1), b2 + hstep, voffB); PG8_STAGE(PG8_SA(0, 0), a2, voffA);
.LBB0_747:
	ds_read_b128 v[144:147], v150
	ds_read_b128 v[158:161], v150 offset:1024
	ds_read_b128 v[162:165], v150 offset:2048
	ds_read_b128 v[166:169], v150 offset:3072
	ds_read_b128 v[170:173], v152
	ds_read_b128 v[174:177], v152 offset:1024
	ds_read_b128 v[178:181], v152 offset:2048
	ds_read_b128 v[182:185], v152 offset:3072
	s_add_u32 s36, s26, 0xfffe0080
	s_addc_u32 s37, s27, -1
	s_cmp_eq_u32 s72, 4
	s_cselect_b32 s39, s15, s37
	s_cselect_b32 s38, s60, s36
	s_cselect_b32 s37, s13, s71
	s_cselect_b32 s36, s61, s70
	v_lshl_add_u64 v[148:149], s[26:27], 0, v[136:137]
	s_add_i32 m0, s25, 0xc000
	ds_read_b128 v[186:189], v154
	ds_read_b128 v[190:193], v154 offset:1024
	ds_read_b128 v[194:197], v154 offset:2048
	ds_read_b128 v[198:201], v154 offset:3072
	ds_read_b128 v[202:205], v154 offset:4096
	ds_read_b128 v[206:209], v154 offset:5120
	ds_read_b128 v[210:213], v154 offset:6144
	ds_read_b128 v[214:217], v154 offset:7168
	global_load_lds_dwordx4 v[148:149], off
	v_lshl_add_u64 v[148:149], s[26:27], 0, v[138:139]
	s_add_i32 m0, s25, 0xe000
	s_nop 0
	global_load_lds_dwordx4 v[148:149], off
	s_waitcnt vmcnt(8)
	s_waitcnt lgkmcnt(0)
	s_barrier
	s_setprio 1
	s_waitcnt lgkmcnt(0)
	v_mfma_f32_16x16x32_bf16 v[124:127], v[144:147], v[186:189], v[124:127]
	v_mfma_f32_16x16x32_bf16 v[120:123], v[162:165], v[186:189], v[120:123]
	v_mfma_f32_16x16x32_bf16 v[116:119], v[144:147], v[194:197], v[116:119]
	v_mfma_f32_16x16x32_bf16 v[104:107], v[162:165], v[194:197], v[104:107]
	v_mfma_f32_16x16x32_bf16 v[92:95], v[144:147], v[202:205], v[92:95]
	v_mfma_f32_16x16x32_bf16 v[88:91], v[162:165], v[202:205], v[88:91]
	v_mfma_f32_16x16x32_bf16 v[80:83], v[144:147], v[210:213], v[80:83]
	v_mfma_f32_16x16x32_bf16 v[72:75], v[162:165], v[210:213], v[72:75]
	v_mfma_f32_16x16x32_bf16 v[124:127], v[158:161], v[190:193], v[124:127]
	v_mfma_f32_16x16x32_bf16 v[120:123], v[166:169], v[190:193], v[120:123]
	v_mfma_f32_16x16x32_bf16 v[116:119], v[158:161], v[198:201], v[116:119]
	v_mfma_f32_16x16x32_bf16 v[104:107], v[166:169], v[198:201], v[104:107]
	v_mfma_f32_16x16x32_bf16 v[92:95], v[158:161], v[206:209], v[92:95]
	v_mfma_f32_16x16x32_bf16 v[88:91], v[166:169], v[206:209], v[88:91]
	v_mfma_f32_16x16x32_bf16 v[80:83], v[158:161], v[214:217], v[80:83]
	v_mfma_f32_16x16x32_bf16 v[72:75], v[166:169], v[214:217], v[72:75]
	s_setprio 0
	s_setprio 1
	v_mfma_f32_16x16x32_bf16 v[112:115], v[170:173], v[186:189], v[112:115]
	v_mfma_f32_16x16x32_bf16 v[108:111], v[178:181], v[186:189], v[108:111]
	v_mfma_f32_16x16x32_bf16 v[100:103], v[170:173], v[194:197], v[100:103]
	v_mfma_f32_16x16x32_bf16 v[96:99], v[178:181], v[194:197], v[96:99]
	v_mfma_f32_16x16x32_bf16 v[84:87], v[170:173], v[202:205], v[84:87]
	v_mfma_f32_16x16x32_bf16 v[76:79], v[178:181], v[202:205], v[76:79]
	v_mfma_f32_16x16x32_bf16 v[68:71], v[170:173], v[210:213], v[68:71]
	v_mfma_f32_16x16x32_bf16 v[64:67], v[178:181], v[210:213], v[64:67]
	v_mfma_f32_16x16x32_bf16 v[112:115], v[174:177], v[190:193], v[112:115]
	v_mfma_f32_16x16x32_bf16 v[108:111], v[182:185], v[190:193], v[108:111]
	v_mfma_f32_16x16x32_bf16 v[100:103], v[174:177], v[198:201], v[100:103]
	v_mfma_f32_16x16x32_bf16 v[96:99], v[182:185], v[198:201], v[96:99]
	v_mfma_f32_16x16x32_bf16 v[84:87], v[174:177], v[206:209], v[84:87]
	v_mfma_f32_16x16x32_bf16 v[76:79], v[182:185], v[206:209], v[76:79]
	v_mfma_f32_16x16x32_bf16 v[68:71], v[174:177], v[214:217], v[68:71]
	v_mfma_f32_16x16x32_bf16 v[64:67], v[182:185], v[214:217], v[64:67]
	s_setprio 0
	s_barrier
	s_add_i32 s73, s51, s41
	v_lshl_add_u64 v[148:149], s[36:37], 0, v[130:131]
	s_mov_b32 m0, s73
	ds_read_b128 v[186:189], v154 offset:16384
	ds_read_b128 v[190:193], v154 offset:17408
	ds_read_b128 v[194:197], v154 offset:18432
	ds_read_b128 v[198:201], v154 offset:19456
	ds_read_b128 v[202:205], v154 offset:20480
	ds_read_b128 v[206:209], v154 offset:21504
	ds_read_b128 v[210:213], v154 offset:22528
	ds_read_b128 v[214:217], v154 offset:23552
	global_load_lds_dwordx4 v[148:149], off
	s_add_i32 m0, s73, 0x2000
	s_add_u32 s74, s36, 0x20000
	v_lshl_add_u64 v[218:219], s[36:37], 0, v[134:135]
	s_addc_u32 s75, s37, 0
	s_add_i32 s73, s52, s41
	global_load_lds_dwordx4 v[218:219], off
	v_lshl_add_u64 v[220:221], s[74:75], 0, v[130:131]
	s_mov_b32 m0, s73
	v_lshl_add_u64 v[222:223], s[38:39], 0, v[132:133]
	global_load_lds_dwordx4 v[220:221], off
	v_lshl_add_u64 v[220:221], s[74:75], 0, v[134:135]
	s_add_i32 m0, s73, 0x2000
	s_nop 0
	global_load_lds_dwordx4 v[220:221], off
	v_lshl_add_u64 v[220:221], s[38:39], 0, v[128:129]
	s_mov_b32 m0, s25
	s_nop 0
	global_load_lds_dwordx4 v[220:221], off
	s_mov_b32 m0, s44
	s_nop 0
	global_load_lds_dwordx4 v[222:223], off
	s_waitcnt vmcnt(8)
	s_waitcnt lgkmcnt(0)
	s_barrier
; #define PG8_STAGE(bufoff, gbase, voff) do { _Pragma("unroll") for (int _i = 0; _i < 2; ++_i) \
;         __builtin_amdgcn_global_load_lds((const unsigned*)((const char*)(gbase) + (voff)[_i]), (PG8_LAS unsigned*)(lds + (bufoff) + ldsw + _i * 8192), 16, 0, 0); } while (0)
; #define PG8_LDA(dst, b, h) do { _Pragma("unroll") for (int m = 0; m < 4; ++m) _Pragma("unroll") for (int k = 0; k < 2; ++k) dst[m][k] = *(const PG8_LAS bf16x8*)(lds + PG8_SA(b, h) + aoff + m * 2048 + k * 1024); } while (0)
; #define PG8_LDB(dst, b, h) do { _Pragma("unroll") for (int n = 0; n < 2; ++n) _Pragma("unroll") for (int k = 0; k < 2; ++k) dst[n][k] = *(const PG8_LAS bf16x8*)(lds + PG8_SB(b, h) + boff + n * 2048 + k * 1024); } while (0)
; #define PG8_MMA(ai, bj, At, Bt) do { __builtin_amdgcn_s_setprio(1); _Pragma("unroll") for (int m = 0; m < 4; ++m) _Pragma("unroll") for (int n = 0; n < 2; ++n) _Pragma("unroll") for (int k = 0; k < 2; ++k) \
;         acc[ai][bj][m][n] = __builtin_amdgcn_mfma_f32_16x16x32_bf16(Bt[n][k], At[m][k], acc[ai][bj][m][n], 0, 0, 0); __builtin_amdgcn_s_setprio(0); } while (0)
; #define PG8_WAIT_V(n) asm volatile("s_waitcnt vmcnt(" #n ")" ::: "memory")
; #define PG8_WAIT_L(n) asm volatile("s_waitcnt lgkmcnt(" #n ")" ::: "memory")
; #define PG8_BAR __builtin_amdgcn_s_barrier()
; #define PG8_SCHED __builtin_amdgcn_sched_barrier(0)
; template <class Epi, class Sched, bool ALIGN_EPI = false, bool SP2 = false>
; __device__ __forceinline__ void gemm_phase(PG8_LAS unsigned char* lds, const Gemm g, const Sched& S, const Epi& E) {
;     ...
;             PG8_WAIT_V(8); PG8_WAIT_L(0); PG8_BAR; PG8_MMA(1, 0, At, B0); PG8_MMA(1, 1, At, B1); PG8_BAR; PG8_SCHED;
;             PG8_LDB(B0, 1, 0); PG8_LDB(B1, 1, 1); PG8_SCHED; PG8_LDA(At, 1, 0); PG8_STAGE(PG8_SA(0, 1), a2 + hstep, voffA);
;             PG8_WAIT_V(8); PG8_WAIT_L(0); PG8_BAR; PG8_MMA(0, 0, At, B0); PG8_MMA(0, 1, At, B1); PG8_BAR; PG8_SCHED;
	s_setprio 1
	s_waitcnt lgkmcnt(0)
	v_mfma_f32_16x16x32_bf16 v[60:63], v[144:147], v[186:189], v[60:63]
	v_mfma_f32_16x16x32_bf16 v[56:59], v[162:165], v[186:189], v[56:59]
	v_mfma_f32_16x16x32_bf16 v[48:51], v[144:147], v[194:197], v[48:51]
	v_mfma_f32_16x16x32_bf16 v[40:43], v[162:165], v[194:197], v[40:43]
	v_mfma_f32_16x16x32_bf16 v[28:31], v[144:147], v[202:205], v[28:31]
	v_mfma_f32_16x16x32_bf16 v[24:27], v[162:165], v[202:205], v[24:27]
	v_mfma_f32_16x16x32_bf16 v[16:19], v[144:147], v[210:213], v[16:19]
	v_mfma_f32_16x16x32_bf16 v[8:11], v[162:165], v[210:213], v[8:11]
	v_mfma_f32_16x16x32_bf16 v[60:63], v[158:161], v[190:193], v[60:63]
	v_mfma_f32_16x16x32_bf16 v[56:59], v[166:169], v[190:193], v[56:59]
	v_mfma_f32_16x16x32_bf16 v[48:51], v[158:161], v[198:201], v[48:51]
	v_mfma_f32_16x16x32_bf16 v[40:43], v[166:169], v[198:201], v[40:43]
	v_mfma_f32_16x16x32_bf16 v[28:31], v[158:161], v[206:209], v[28:31]
	v_mfma_f32_16x16x32_bf16 v[24:27], v[166:169], v[206:209], v[24:27]
	v_mfma_f32_16x16x32_bf16 v[16:19], v[158:161], v[214:217], v[16:19]
	v_mfma_f32_16x16x32_bf16 v[8:11], v[166:169], v[214:217], v[8:11]
	s_setprio 0
	s_setprio 1
	v_mfma_f32_16x16x32_bf16 v[52:55], v[170:173], v[186:189], v[52:55]
	v_mfma_f32_16x16x32_bf16 v[44:47], v[178:181], v[186:189], v[44:47]
	v_mfma_f32_16x16x32_bf16 v[36:39], v[170:173], v[194:197], v[36:39]
	v_mfma_f32_16x16x32_bf16 v[32:35], v[178:181], v[194:197], v[32:35]
	v_mfma_f32_16x16x32_bf16 v[20:23], v[170:173], v[202:205], v[20:23]
	v_mfma_f32_16x16x32_bf16 v[12:15], v[178:181], v[202:205], v[12:15]
	v_mfma_f32_16x16x32_bf16 v[4:7], v[170:173], v[210:213], v[4:7]
	v_mfma_f32_16x16x32_bf16 v[0:3], v[178:181], v[210:213], v[0:3]
	v_mfma_f32_16x16x32_bf16 v[52:55], v[174:177], v[190:193], v[52:55]
	v_mfma_f32_16x16x32_bf16 v[44:47], v[182:185], v[190:193], v[44:47]
	v_mfma_f32_16x16x32_bf16 v[36:39], v[174:177], v[198:201], v[36:39]
	v_mfma_f32_16x16x32_bf16 v[32:35], v[182:185], v[198:201], v[32:35]
	v_mfma_f32_16x16x32_bf16 v[20:23], v[174:177], v[206:209], v[20:23]
	v_mfma_f32_16x16x32_bf16 v[12:15], v[182:185], v[206:209], v[12:15]
	v_mfma_f32_16x16x32_bf16 v[4:7], v[174:177], v[214:217], v[4:7]
	v_mfma_f32_16x16x32_bf16 v[0:3], v[182:185], v[214:217], v[0:3]
	s_setprio 0
	s_barrier
	s_add_i32 s73, 0, 0x18000
	v_add_u32_e32 v155, s73, v153
	s_add_i32 s74, 0, 0x1c000
	ds_read_b128 v[144:147], v155
	ds_read_b128 v[158:161], v155 offset:1024
	ds_read_b128 v[162:165], v155 offset:2048
	ds_read_b128 v[166:169], v155 offset:3072
	v_add_u32_e32 v155, s74, v153
	ds_read_b128 v[170:173], v155
	ds_read_b128 v[174:177], v155 offset:1024
	ds_read_b128 v[178:181], v155 offset:2048
	ds_read_b128 v[182:185], v155 offset:3072
	s_add_u32 s38, s38, 0x20000
	s_addc_u32 s39, s39, 0
	s_mov_b32 m0, s45
	v_lshl_add_u64 v[224:225], s[38:39], 0, v[128:129]
	ds_read_b128 v[186:189], v154 offset:32768
	ds_read_b128 v[190:193], v154 offset:33792
	ds_read_b128 v[194:197], v154 offset:34816
	ds_read_b128 v[198:201], v154 offset:35840
	ds_read_b128 v[202:205], v154 offset:36864
	ds_read_b128 v[206:209], v154 offset:37888
	ds_read_b128 v[210:213], v154 offset:38912
	ds_read_b128 v[214:217], v154 offset:39936
	global_load_lds_dwordx4 v[224:225], off
	v_lshl_add_u64 v[224:225], s[38:39], 0, v[132:133]
	s_mov_b32 m0, s46
	s_nop 0
	global_load_lds_dwordx4 v[224:225], off
	s_waitcnt vmcnt(8)
	s_waitcnt lgkmcnt(0)
	s_barrier
	s_setprio 1
	s_waitcnt lgkmcnt(0)
	v_mfma_f32_16x16x32_bf16 v[124:127], v[144:147], v[186:189], v[124:127]
	v_mfma_f32_16x16x32_bf16 v[120:123], v[162:165], v[186:189], v[120:123]
	v_mfma_f32_16x16x32_bf16 v[116:119], v[144:147], v[194:197], v[116:119]
	v_mfma_f32_16x16x32_bf16 v[104:107], v[162:165], v[194:197], v[104:107]
	v_mfma_f32_16x16x32_bf16 v[92:95], v[144:147], v[202:205], v[92:95]
	v_mfma_f32_16x16x32_bf16 v[88:91], v[162:165], v[202:205], v[88:91]
	v_mfma_f32_16x16x32_bf16 v[80:83], v[144:147], v[210:213], v[80:83]
	v_mfma_f32_16x16x32_bf16 v[72:75], v[162:165], v[210:213], v[72:75]
	v_mfma_f32_16x16x32_bf16 v[124:127], v[158:161], v[190:193], v[124:127]
	v_mfma_f32_16x16x32_bf16 v[120:123], v[166:169], v[190:193], v[120:123]
	v_mfma_f32_16x16x32_bf16 v[116:119], v[158:161], v[198:201], v[116:119]
	v_mfma_f32_16x16x32_bf16 v[104:107], v[166:169], v[198:201], v[104:107]
	v_mfma_f32_16x16x32_bf16 v[92:95], v[158:161], v[206:209], v[92:95]
	v_mfma_f32_16x16x32_bf16 v[88:91], v[166:169], v[206:209], v[88:91]
	v_mfma_f32_16x16x32_bf16 v[80:83], v[158:161], v[214:217], v[80:83]
	v_mfma_f32_16x16x32_bf16 v[72:75], v[166:169], v[214:217], v[72:75]
	s_setprio 0
	s_setprio 1
	v_mfma_f32_16x16x32_bf16 v[112:115], v[170:173], v[186:189], v[112:115]
	v_mfma_f32_16x16x32_bf16 v[108:111], v[178:181], v[186:189], v[108:111]
	v_mfma_f32_16x16x32_bf16 v[100:103], v[170:173], v[194:197], v[100:103]
	v_mfma_f32_16x16x32_bf16 v[96:99], v[178:181], v[194:197], v[96:99]
	v_mfma_f32_16x16x32_bf16 v[84:87], v[170:173], v[202:205], v[84:87]
	v_mfma_f32_16x16x32_bf16 v[76:79], v[178:181], v[202:205], v[76:79]
	v_mfma_f32_16x16x32_bf16 v[68:71], v[170:173], v[210:213], v[68:71]
	v_mfma_f32_16x16x32_bf16 v[64:67], v[178:181], v[210:213], v[64:67]
	v_mfma_f32_16x16x32_bf16 v[112:115], v[174:177], v[190:193], v[112:115]
	v_mfma_f32_16x16x32_bf16 v[108:111], v[182:185], v[190:193], v[108:111]
	v_mfma_f32_16x16x32_bf16 v[100:103], v[174:177], v[198:201], v[100:103]
	v_mfma_f32_16x16x32_bf16 v[96:99], v[182:185], v[198:201], v[96:99]
	v_mfma_f32_16x16x32_bf16 v[84:87], v[174:177], v[206:209], v[84:87]
	v_mfma_f32_16x16x32_bf16 v[76:79], v[182:185], v[206:209], v[76:79]
	v_mfma_f32_16x16x32_bf16 v[68:71], v[174:177], v[214:217], v[68:71]
	v_mfma_f32_16x16x32_bf16 v[64:67], v[182:185], v[214:217], v[64:67]
	s_setprio 0
	s_barrier
; #define PG8_STAGE(bufoff, gbase, voff) do { _Pragma("unroll") for (int _i = 0; _i < 2; ++_i) \
;         __builtin_amdgcn_global_load_lds((const unsigned*)((const char*)(gbase) + (voff)[_i]), (PG8_LAS unsigned*)(lds + (bufoff) + ldsw + _i * 8192), 16, 0, 0); } while (0)
; #define PG8_LDA(dst, b, h) do { _Pragma("unroll") for (int m = 0; m < 4; ++m) _Pragma("unroll") for (int k = 0; k < 2; ++k) dst[m][k] = *(const PG8_LAS bf16x8*)(lds + PG8_SA(b, h) + aoff + m * 2048 + k * 1024); } while (0)
; #define PG8_MMA(ai, bj, At, Bt) do { __builtin_amdgcn_s_setprio(1); _Pragma("unroll") for (int m = 0; m < 4; ++m) _Pragma("unroll") for (int n = 0; n < 2; ++n) _Pragma("unroll") for (int k = 0; k < 2; ++k) \
;         acc[ai][bj][m][n] = __builtin_amdgcn_mfma_f32_16x16x32_bf16(Bt[n][k], At[m][k], acc[ai][bj][m][n], 0, 0, 0); __builtin_amdgcn_s_setprio(0); } while (0)
; #define PG8_WAIT_V(n) asm volatile("s_waitcnt vmcnt(" #n ")" ::: "memory")
;     __device__ __forceinline__ void operator()(const f32x4 (&acc)[2][2][4][2], const Unit& u, int wr, int wc, int fr, int fq) const {
;         const int row0 = u.pm * BM + wr * 64 + fr, col0 = u.pn * BM + wc * 32 + 8 * fq;
;         const bf16_t* const G = (const bf16_t*)(ws + (ADD ? WS_GB : WS_GA)); bf16_t* const Mg = (bf16_t*)(ws + WS_GA);
; #pragma unroll
;         for (int ai = 0; ai < 2; ++ai)
; #pragma unroll
;         for (int mh = 0; mh < 4; mh += 2) {
;             u32x2 pg[4][2][2], pm_[4][2][2];
; #pragma unroll
;             for (int m = mh; m < mh + 2; ++m)
; #pragma unroll
;                 for (int bj = 0; bj < 2; ++bj)
; #pragma unroll
;                     for (int n = 0; n < 2; ++n) { const size_t off = (size_t)(row0 + ai * HALF + m * 16) * 1024 + col0 + bj * HALF + n * 4;
;                         pg[m][bj][n] = *(const u32x2*)(G + off); if (ADD) pm_[m][bj][n] = *(const u32x2*)(Mg + off); }
;             asm volatile("" ::: "memory");
; template <class Epi, class Sched, bool ALIGN_EPI = false, bool SP2 = false>
; __device__ __forceinline__ void gemm_phase(PG8_LAS unsigned char* lds, const Gemm g, const Sched& S, const Epi& E) {
;     ...
;             PG8_LDA(At, 1, 1); PG8_STAGE(PG8_SB(1, 0), b3, voffB); PG8_STAGE(PG8_SB(1, 1), b3 + hstep, voffB); PG8_STAGE(PG8_SA(1, 0), a3, voffA);
;             PG8_WAIT_V(8); PG8_WAIT_L(0); PG8_BAR; PG8_MMA(1, 0, At, B0); PG8_MMA(1, 1, At, B1); PG8_BAR; PG8_SCHED;
	s_add_i32 s38, s73, s41
	v_lshl_add_u64 v[148:149], v[148:149], 0, s[4:5]
	s_mov_b32 m0, s38
	ds_read_b128 v[186:189], v154 offset:49152
	ds_read_b128 v[190:193], v154 offset:50176
	ds_read_b128 v[194:197], v154 offset:51200
	ds_read_b128 v[198:201], v154 offset:52224
	ds_read_b128 v[202:205], v154 offset:53248
	ds_read_b128 v[206:209], v154 offset:54272
	ds_read_b128 v[210:213], v154 offset:55296
	ds_read_b128 v[214:217], v154 offset:56320
	global_load_lds_dwordx4 v[148:149], off
	s_add_i32 m0, s38, 0x2000
	s_add_u32 s36, s36, 0x20080
	v_lshl_add_u64 v[148:149], v[218:219], 0, s[4:5]
	s_addc_u32 s37, s37, 0
	s_add_i32 s38, s74, s41
	global_load_lds_dwordx4 v[148:149], off
	v_lshl_add_u64 v[148:149], s[36:37], 0, v[130:131]
	s_mov_b32 m0, s38
	s_nop 0
	global_load_lds_dwordx4 v[148:149], off
	v_lshl_add_u64 v[148:149], s[36:37], 0, v[134:135]
	s_add_i32 m0, s38, 0x2000
	s_nop 0
	global_load_lds_dwordx4 v[148:149], off
	v_lshl_add_u64 v[148:149], v[220:221], 0, s[4:5]
	s_mov_b32 m0, s48
	s_nop 0
	global_load_lds_dwordx4 v[148:149], off
	v_lshl_add_u64 v[148:149], v[222:223], 0, s[4:5]
	s_mov_b32 m0, s49
	s_nop 0
	global_load_lds_dwordx4 v[148:149], off
	s_waitcnt vmcnt(8)
	s_waitcnt lgkmcnt(0)
	s_barrier
	s_setprio 1
	s_waitcnt lgkmcnt(0)
	v_mfma_f32_16x16x32_bf16 v[60:63], v[144:147], v[186:189], v[60:63]
	v_mfma_f32_16x16x32_bf16 v[56:59], v[162:165], v[186:189], v[56:59]
	v_mfma_f32_16x16x32_bf16 v[48:51], v[144:147], v[194:197], v[48:51]
	v_mfma_f32_16x16x32_bf16 v[40:43], v[162:165], v[194:197], v[40:43]
	v_mfma_f32_16x16x32_bf16 v[28:31], v[144:147], v[202:205], v[28:31]
	v_mfma_f32_16x16x32_bf16 v[24:27], v[162:165], v[202:205], v[24:27]
	v_mfma_f32_16x16x32_bf16 v[16:19], v[144:147], v[210:213], v[16:19]
	v_mfma_f32_16x16x32_bf16 v[8:11], v[162:165], v[210:213], v[8:11]
	v_mfma_f32_16x16x32_bf16 v[60:63], v[158:161], v[190:193], v[60:63]
	v_mfma_f32_16x16x32_bf16 v[56:59], v[166:169], v[190:193], v[56:59]
	v_mfma_f32_16x16x32_bf16 v[48:51], v[158:161], v[198:201], v[48:51]
	v_mfma_f32_16x16x32_bf16 v[40:43], v[166:169], v[198:201], v[40:43]
	v_mfma_f32_16x16x32_bf16 v[28:31], v[158:161], v[206:209], v[28:31]
	v_mfma_f32_16x16x32_bf16 v[24:27], v[166:169], v[206:209], v[24:27]
	v_mfma_f32_16x16x32_bf16 v[16:19], v[158:161], v[214:217], v[16:19]
	v_mfma_f32_16x16x32_bf16 v[8:11], v[166:169], v[214:217], v[8:11]
	s_setprio 0
	s_setprio 1
	v_mfma_f32_16x16x32_bf16 v[52:55], v[170:173], v[186:189], v[52:55]
	v_mfma_f32_16x16x32_bf16 v[44:47], v[178:181], v[186:189], v[44:47]
	v_mfma_f32_16x16x32_bf16 v[36:39], v[170:173], v[194:197], v[36:39]
	v_mfma_f32_16x16x32_bf16 v[32:35], v[178:181], v[194:197], v[32:35]
	v_mfma_f32_16x16x32_bf16 v[20:23], v[170:173], v[202:205], v[20:23]
	v_mfma_f32_16x16x32_bf16 v[12:15], v[178:181], v[202:205], v[12:15]
	v_mfma_f32_16x16x32_bf16 v[4:7], v[170:173], v[210:213], v[4:7]
	v_mfma_f32_16x16x32_bf16 v[0:3], v[178:181], v[210:213], v[0:3]
	v_mfma_f32_16x16x32_bf16 v[52:55], v[174:177], v[190:193], v[52:55]
	v_mfma_f32_16x16x32_bf16 v[44:47], v[182:185], v[190:193], v[44:47]
	v_mfma_f32_16x16x32_bf16 v[36:39], v[174:177], v[198:201], v[36:39]
	v_mfma_f32_16x16x32_bf16 v[32:35], v[182:185], v[198:201], v[32:35]
	v_mfma_f32_16x16x32_bf16 v[20:23], v[174:177], v[206:209], v[20:23]
	v_mfma_f32_16x16x32_bf16 v[12:15], v[182:185], v[206:209], v[12:15]
	v_mfma_f32_16x16x32_bf16 v[4:7], v[174:177], v[214:217], v[4:7]
	v_mfma_f32_16x16x32_bf16 v[0:3], v[182:185], v[214:217], v[0:3]
	s_setprio 0
	s_barrier
	s_add_i32 s72, s72, 2
	s_add_u32 s26, s26, 0x100
	s_addc_u32 s27, s27, 0
	s_add_u32 s70, s70, 0x100
	s_addc_u32 s71, s71, 0
	s_cmp_gt_u32 s72, 5
	s_cbranch_scc0 .LBB0_747
	s_cmpk_gt_u32 s40, 0xff
	s_cbranch_scc1 .Lal_p6b_pre
	s_barrier
.Lal_p6b_pre:
	v_lshl_add_u32 v146, s24, 8, v156
	v_lshl_or_b32 v144, s53, 8, v151
	v_ashrrev_i32_e32 v147, 31, v146
	v_ashrrev_i32_e32 v145, 31, v144
	v_lshlrev_b64 v[148:149], 10, v[146:147]
	v_lshl_add_u64 v[148:149], v[148:149], 0, v[144:145]
	v_lshlrev_b64 v[170:171], 1, v[148:149]
	v_lshl_add_u64 v[148:149], s[6:7], 0, v[170:171]
	v_or_b32_e32 v170, 0x100, v170
	v_lshl_add_u64 v[166:167], s[6:7], 0, v[170:171]
	v_or_b32_e32 v178, 16, v146
	global_load_dwordx4 v[158:161], v[148:149], off
	v_lshlrev_b64 v[162:163], 11, v[146:147]
	global_load_dwordx4 v[166:169], v[166:167], off
	v_lshl_add_u64 v[148:149], v[144:145], 1, s[0:1]
	v_ashrrev_i32_e32 v179, 31, v178
	v_lshl_add_u64 v[190:191], v[148:149], 0, v[162:163]
	v_lshlrev_b64 v[174:175], 10, v[178:179]
	global_load_dwordx4 v[162:165], v[190:191], off
	v_lshl_add_u64 v[170:171], s[0:1], 0, v[170:171]
	v_lshl_add_u64 v[174:175], v[174:175], 0, v[144:145]
	global_load_dwordx4 v[170:173], v[170:171], off
	v_lshlrev_b64 v[186:187], 1, v[174:175]
	v_lshlrev_b64 v[178:179], 11, v[178:179]
	v_lshl_add_u64 v[174:175], s[6:7], 0, v[186:187]
	v_lshl_add_u64 v[192:193], v[148:149], 0, v[178:179]
	global_load_dwordx4 v[174:177], v[174:175], off
	v_or_b32_e32 v186, 0x100, v186
	global_load_dwordx4 v[178:181], v[192:193], off
	v_lshl_add_u64 v[182:183], s[6:7], 0, v[186:187]
	v_lshl_add_u64 v[186:187], s[0:1], 0, v[186:187]
	global_load_dwordx4 v[182:185], v[182:183], off
	s_and_b64 vcc, exec, s[2:3]
	global_load_dwordx4 v[186:189], v[186:187], off
	s_mov_b32 s53, s12
	s_mov_b32 s24, s14
	s_mov_b64 s[36:37], s[22:23]
	s_mov_b64 s[26:27], s[20:21]
	s_waitcnt vmcnt(0)
; __device__ __forceinline__ u32x2 pack4(f32x4 v) { u32x2 w; w.x = cvt_pk_bf16(v[0], v[1]); w.y = cvt_pk_bf16(v[2], v[3]); return w; }
; __device__ __forceinline__ f32x4 unpack4(u32x2 w) { f32x4 v; v[0] = __uint_as_float(w.x << 16); v[1] = __uint_as_float(w.x & 0xffff0000u); v[2] = __uint_as_float(w.y << 16); v[3] = __uint_as_float(w.y & 0xffff0000u); return v; }
;     __device__ __forceinline__ void operator()(const f32x4 (&acc)[2][2][4][2], const Unit& u, int wr, int wc, int fr, int fq) const {
;     ...
; #pragma unroll
;             for (int m = mh; m < mh + 2; ++m)
; #pragma unroll
;                 for (int bj = 0; bj < 2; ++bj)
; #pragma unroll
;                     for (int n = 0; n < 2; ++n) { const size_t off = (size_t)(row0 + ai * HALF + m * 16) * 1024 + col0 + bj * HALF + n * 4;
;                         f32x4 o = unpack4(pg[m][bj][n]) * acc[ai][bj][m][n]; if (ADD) o = o + unpack4(pm_[m][bj][n]);
;                         *(u32x2*)(Mg + off) = pack4(o); }
;             asm volatile("" ::: "memory");
;         }
	v_lshlrev_b32_e32 v194, 16, v158
	v_and_b32_e32 v195, 0xffff0000, v158
	v_lshlrev_b32_e32 v158, 16, v159
	v_and_b32_e32 v159, 0xffff0000, v159
	v_lshlrev_b32_e32 v198, 16, v160
	v_and_b32_e32 v199, 0xffff0000, v160
	v_lshlrev_b32_e32 v160, 16, v161
	v_lshlrev_b32_e32 v196, 16, v162
	v_and_b32_e32 v197, 0xffff0000, v162
	v_lshlrev_b32_e32 v162, 16, v163
	v_and_b32_e32 v163, 0xffff0000, v163
	v_and_b32_e32 v161, 0xffff0000, v161
	v_lshlrev_b32_e32 v200, 16, v164
	v_and_b32_e32 v201, 0xffff0000, v164
	v_lshlrev_b32_e32 v164, 16, v165
	v_and_b32_e32 v165, 0xffff0000, v165
	v_pk_fma_f32 v[126:127], v[126:127], v[158:159], v[162:163]
	v_pk_fma_f32 v[124:125], v[124:125], v[194:195], v[196:197]
	v_pk_fma_f32 v[158:159], v[122:123], v[160:161], v[164:165]
	v_lshlrev_b32_e32 v160, 16, v166
	v_and_b32_e32 v161, 0xffff0000, v166
	v_lshlrev_b32_e32 v162, 16, v167
	v_and_b32_e32 v163, 0xffff0000, v167
	v_lshlrev_b32_e32 v164, 16, v170
	v_and_b32_e32 v165, 0xffff0000, v170
	v_lshlrev_b32_e32 v166, 16, v171
	v_and_b32_e32 v167, 0xffff0000, v171
	v_lshlrev_b32_e32 v170, 16, v168
	v_and_b32_e32 v171, 0xffff0000, v168
	v_lshlrev_b32_e32 v168, 16, v169
	v_and_b32_e32 v169, 0xffff0000, v169
	v_lshlrev_b32_e32 v194, 16, v172
	v_and_b32_e32 v195, 0xffff0000, v172
	v_lshlrev_b32_e32 v172, 16, v173
	v_and_b32_e32 v173, 0xffff0000, v173
	v_pk_fma_f32 v[122:123], v[120:121], v[198:199], v[200:201]
	v_cvt_pk_bf16_f32 v120, v124, v125
	v_pk_fma_f32 v[114:115], v[114:115], v[162:163], v[166:167]
	v_pk_fma_f32 v[112:113], v[112:113], v[160:161], v[164:165]
	v_pk_fma_f32 v[124:125], v[110:111], v[168:169], v[172:173]
	v_pk_fma_f32 v[110:111], v[108:109], v[170:171], v[194:195]
	v_lshlrev_b32_e32 v196, 16, v174
	v_and_b32_e32 v197, 0xffff0000, v174
	v_lshlrev_b32_e32 v174, 16, v175
	v_and_b32_e32 v175, 0xffff0000, v175
	v_lshlrev_b32_e32 v198, 16, v178
	v_and_b32_e32 v199, 0xffff0000, v178
	v_lshlrev_b32_e32 v178, 16, v179
	v_cvt_pk_bf16_f32 v108, v112, v113
	v_cvt_pk_bf16_f32 v109, v114, v115
	v_cvt_pk_bf16_f32 v110, v110, v111
	v_cvt_pk_bf16_f32 v111, v124, v125
	v_and_b32_e32 v179, 0xffff0000, v179
	global_store_dwordx4 v[190:191], v[108:111], off offset:256
	v_lshlrev_b32_e32 v112, 16, v177
	v_and_b32_e32 v113, 0xffff0000, v177
	v_pk_fma_f32 v[110:111], v[118:119], v[174:175], v[178:179]
	v_pk_fma_f32 v[108:109], v[116:117], v[196:197], v[198:199]
	v_lshlrev_b32_e32 v114, 16, v180
	v_cvt_pk_bf16_f32 v108, v108, v109
	v_cvt_pk_bf16_f32 v109, v110, v111
	v_lshlrev_b32_e32 v110, 16, v176
	v_and_b32_e32 v111, 0xffff0000, v176
	v_and_b32_e32 v115, 0xffff0000, v180
	v_lshlrev_b32_e32 v116, 16, v181
	v_and_b32_e32 v117, 0xffff0000, v181
	v_pk_fma_f32 v[106:107], v[106:107], v[112:113], v[116:117]
	v_pk_fma_f32 v[104:105], v[104:105], v[110:111], v[114:115]
	v_cvt_pk_bf16_f32 v111, v106, v107
	v_cvt_pk_bf16_f32 v110, v104, v105
	global_store_dwordx4 v[192:193], v[108:111], off
	v_lshlrev_b32_e32 v104, 16, v182
	v_and_b32_e32 v105, 0xffff0000, v182
	v_lshlrev_b32_e32 v106, 16, v183
	v_and_b32_e32 v107, 0xffff0000, v183
	v_lshlrev_b32_e32 v108, 16, v186
	v_and_b32_e32 v109, 0xffff0000, v186
	v_lshlrev_b32_e32 v110, 16, v187
	v_and_b32_e32 v111, 0xffff0000, v187
	v_pk_fma_f32 v[102:103], v[102:103], v[106:107], v[110:111]
	v_pk_fma_f32 v[100:101], v[100:101], v[104:105], v[108:109]
	v_lshlrev_b32_e32 v104, 16, v185
	v_cvt_pk_bf16_f32 v100, v100, v101
	v_cvt_pk_bf16_f32 v101, v102, v103
	v_lshlrev_b32_e32 v102, 16, v184
	v_and_b32_e32 v103, 0xffff0000, v184
	v_and_b32_e32 v105, 0xffff0000, v185
	v_lshlrev_b32_e32 v106, 16, v188
	v_and_b32_e32 v107, 0xffff0000, v188
	v_lshlrev_b32_e32 v108, 16, v189
	v_and_b32_e32 v109, 0xffff0000, v189
	v_pk_fma_f32 v[98:99], v[98:99], v[104:105], v[108:109]
	v_pk_fma_f32 v[96:97], v[96:97], v[102:103], v[106:107]
	v_cvt_pk_bf16_f32 v103, v98, v99
	v_cvt_pk_bf16_f32 v102, v96, v97
	global_store_dwordx4 v[192:193], v[100:103], off offset:256
	v_cvt_pk_bf16_f32 v121, v126, v127
	v_cvt_pk_bf16_f32 v122, v122, v123
	v_or_b32_e32 v100, 32, v146
	v_ashrrev_i32_e32 v101, 31, v100
	v_lshlrev_b64 v[96:97], 10, v[100:101]
	v_cvt_pk_bf16_f32 v123, v158, v159
	v_lshl_add_u64 v[96:97], v[96:97], 0, v[144:145]
	global_store_dwordx4 v[190:191], v[120:123], off
	v_lshlrev_b64 v[108:109], 1, v[96:97]
	v_lshlrev_b64 v[100:101], 11, v[100:101]
	v_lshl_add_u64 v[96:97], s[6:7], 0, v[108:109]
	v_lshl_add_u64 v[158:159], v[148:149], 0, v[100:101]
	global_load_dwordx4 v[96:99], v[96:97], off
	v_or_b32_e32 v108, 0x100, v108
	global_load_dwordx4 v[100:103], v[158:159], off
	v_lshl_add_u64 v[104:105], s[6:7], 0, v[108:109]
	v_lshl_add_u64 v[108:109], s[0:1], 0, v[108:109]
	v_or_b32_e32 v116, 48, v146
	global_load_dwordx4 v[104:107], v[104:105], off
	v_ashrrev_i32_e32 v117, 31, v116
	global_load_dwordx4 v[108:111], v[108:109], off
	v_lshlrev_b64 v[112:113], 10, v[116:117]
	v_lshl_add_u64 v[112:113], v[112:113], 0, v[144:145]
	v_lshlrev_b64 v[124:125], 1, v[112:113]
	v_lshlrev_b64 v[116:117], 11, v[116:117]
	v_lshl_add_u64 v[112:113], s[6:7], 0, v[124:125]
	v_lshl_add_u64 v[160:161], v[148:149], 0, v[116:117]
	global_load_dwordx4 v[112:115], v[112:113], off
	v_or_b32_e32 v124, 0x100, v124
	global_load_dwordx4 v[116:119], v[160:161], off
	v_lshl_add_u64 v[120:121], s[6:7], 0, v[124:125]
	v_lshl_add_u64 v[124:125], s[0:1], 0, v[124:125]
	global_load_dwordx4 v[120:123], v[120:121], off
	s_waitcnt vmcnt(6)
	v_lshlrev_b32_e32 v162, 16, v96
	global_load_dwordx4 v[124:127], v[124:125], off
	v_and_b32_e32 v163, 0xffff0000, v96
	v_lshlrev_b32_e32 v96, 16, v97
	v_and_b32_e32 v97, 0xffff0000, v97
	s_waitcnt vmcnt(6)
; __device__ __forceinline__ u32x2 pack4(f32x4 v) { u32x2 w; w.x = cvt_pk_bf16(v[0], v[1]); w.y = cvt_pk_bf16(v[2], v[3]); return w; }
; __device__ __forceinline__ f32x4 unpack4(u32x2 w) { f32x4 v; v[0] = __uint_as_float(w.x << 16); v[1] = __uint_as_float(w.x & 0xffff0000u); v[2] = __uint_as_float(w.y << 16); v[3] = __uint_as_float(w.y & 0xffff0000u); return v; }
;     __device__ __forceinline__ void operator()(const f32x4 (&acc)[2][2][4][2], const Unit& u, int wr, int wc, int fr, int fq) const {
;     ...
;             for (int m = mh; m < mh + 2; ++m)
; #pragma unroll
;                 for (int bj = 0; bj < 2; ++bj)
; #pragma unroll
;                     for (int n = 0; n < 2; ++n) { const size_t off = (size_t)(row0 + ai * HALF + m * 16) * 1024 + col0 + bj * HALF + n * 4;
;                         pg[m][bj][n] = *(const u32x2*)(G + off); if (ADD) pm_[m][bj][n] = *(const u32x2*)(Mg + off); }
;             asm volatile("" ::: "memory");
; #pragma unroll
;             for (int m = mh; m < mh + 2; ++m)
; #pragma unroll
;                 for (int bj = 0; bj < 2; ++bj)
; #pragma unroll
;                     for (int n = 0; n < 2; ++n) { const size_t off = (size_t)(row0 + ai * HALF + m * 16) * 1024 + col0 + bj * HALF + n * 4;
;                         f32x4 o = unpack4(pg[m][bj][n]) * acc[ai][bj][m][n]; if (ADD) o = o + unpack4(pm_[m][bj][n]);
;                         *(u32x2*)(Mg + off) = pack4(o); }
;             asm volatile("" ::: "memory");
;         }
	v_lshlrev_b32_e32 v164, 16, v100
	v_and_b32_e32 v165, 0xffff0000, v100
	v_lshlrev_b32_e32 v100, 16, v101
	v_and_b32_e32 v101, 0xffff0000, v101
	v_pk_fma_f32 v[94:95], v[94:95], v[96:97], v[100:101]
	v_pk_fma_f32 v[92:93], v[92:93], v[162:163], v[164:165]
	v_lshlrev_b32_e32 v96, 16, v99
	v_cvt_pk_bf16_f32 v92, v92, v93
	v_cvt_pk_bf16_f32 v93, v94, v95
	v_lshlrev_b32_e32 v94, 16, v98
	v_and_b32_e32 v95, 0xffff0000, v98
	v_and_b32_e32 v97, 0xffff0000, v99
	v_lshlrev_b32_e32 v98, 16, v102
	v_and_b32_e32 v99, 0xffff0000, v102
	v_lshlrev_b32_e32 v100, 16, v103
	v_and_b32_e32 v101, 0xffff0000, v103
	v_pk_fma_f32 v[90:91], v[90:91], v[96:97], v[100:101]
	v_pk_fma_f32 v[88:89], v[88:89], v[94:95], v[98:99]
	v_cvt_pk_bf16_f32 v95, v90, v91
	v_cvt_pk_bf16_f32 v94, v88, v89
	global_store_dwordx4 v[158:159], v[92:95], off
	s_waitcnt vmcnt(6)
	v_lshlrev_b32_e32 v88, 16, v104
	v_and_b32_e32 v89, 0xffff0000, v104
	v_lshlrev_b32_e32 v90, 16, v105
	v_and_b32_e32 v91, 0xffff0000, v105
	s_waitcnt vmcnt(5)
	v_lshlrev_b32_e32 v92, 16, v108
	v_and_b32_e32 v93, 0xffff0000, v108
	v_lshlrev_b32_e32 v94, 16, v109
	v_and_b32_e32 v95, 0xffff0000, v109
	v_pk_fma_f32 v[86:87], v[86:87], v[90:91], v[94:95]
	v_pk_fma_f32 v[84:85], v[84:85], v[88:89], v[92:93]
	v_lshlrev_b32_e32 v88, 16, v107
	v_cvt_pk_bf16_f32 v84, v84, v85
	v_cvt_pk_bf16_f32 v85, v86, v87
	v_lshlrev_b32_e32 v86, 16, v106
	v_and_b32_e32 v87, 0xffff0000, v106
	v_and_b32_e32 v89, 0xffff0000, v107
	v_lshlrev_b32_e32 v90, 16, v110
	v_and_b32_e32 v91, 0xffff0000, v110
	v_lshlrev_b32_e32 v92, 16, v111
	v_and_b32_e32 v93, 0xffff0000, v111
	v_pk_fma_f32 v[78:79], v[78:79], v[88:89], v[92:93]
	v_pk_fma_f32 v[76:77], v[76:77], v[86:87], v[90:91]
	v_cvt_pk_bf16_f32 v87, v78, v79
	v_cvt_pk_bf16_f32 v86, v76, v77
	global_store_dwordx4 v[158:159], v[84:87], off offset:256
	s_waitcnt vmcnt(5)
	v_lshlrev_b32_e32 v76, 16, v112
	v_and_b32_e32 v77, 0xffff0000, v112
	v_lshlrev_b32_e32 v78, 16, v113
	v_and_b32_e32 v79, 0xffff0000, v113
	s_waitcnt vmcnt(4)
	v_lshlrev_b32_e32 v84, 16, v116
	v_and_b32_e32 v85, 0xffff0000, v116
	v_lshlrev_b32_e32 v86, 16, v117
	v_and_b32_e32 v87, 0xffff0000, v117
	v_pk_fma_f32 v[78:79], v[82:83], v[78:79], v[86:87]
	v_pk_fma_f32 v[76:77], v[80:81], v[76:77], v[84:85]
	v_lshlrev_b32_e32 v80, 16, v115
	v_cvt_pk_bf16_f32 v76, v76, v77
	v_cvt_pk_bf16_f32 v77, v78, v79
	v_lshlrev_b32_e32 v78, 16, v114
	v_and_b32_e32 v79, 0xffff0000, v114
	v_and_b32_e32 v81, 0xffff0000, v115
	v_lshlrev_b32_e32 v82, 16, v118
	v_and_b32_e32 v83, 0xffff0000, v118
	v_lshlrev_b32_e32 v84, 16, v119
	v_and_b32_e32 v85, 0xffff0000, v119
	v_pk_fma_f32 v[74:75], v[74:75], v[80:81], v[84:85]
	v_pk_fma_f32 v[72:73], v[72:73], v[78:79], v[82:83]
	v_cvt_pk_bf16_f32 v79, v74, v75
	v_cvt_pk_bf16_f32 v78, v72, v73
	global_store_dwordx4 v[160:161], v[76:79], off
	s_waitcnt vmcnt(4)
	v_lshlrev_b32_e32 v72, 16, v120
	v_and_b32_e32 v73, 0xffff0000, v120
	v_lshlrev_b32_e32 v74, 16, v121
	v_and_b32_e32 v75, 0xffff0000, v121
	s_waitcnt vmcnt(3)
	v_lshlrev_b32_e32 v76, 16, v124
	v_and_b32_e32 v77, 0xffff0000, v124
	v_lshlrev_b32_e32 v78, 16, v125
	v_and_b32_e32 v79, 0xffff0000, v125
	v_pk_fma_f32 v[70:71], v[70:71], v[74:75], v[78:79]
	v_pk_fma_f32 v[68:69], v[68:69], v[72:73], v[76:77]
	v_lshlrev_b32_e32 v72, 16, v123
	v_cvt_pk_bf16_f32 v68, v68, v69
	v_cvt_pk_bf16_f32 v69, v70, v71
	v_lshlrev_b32_e32 v70, 16, v122
	v_and_b32_e32 v71, 0xffff0000, v122
	v_and_b32_e32 v73, 0xffff0000, v123
	v_lshlrev_b32_e32 v74, 16, v126
	v_and_b32_e32 v75, 0xffff0000, v126
	v_lshlrev_b32_e32 v76, 16, v127
	v_and_b32_e32 v77, 0xffff0000, v127
	v_pk_fma_f32 v[66:67], v[66:67], v[72:73], v[76:77]
	v_pk_fma_f32 v[64:65], v[64:65], v[70:71], v[74:75]
	v_cvt_pk_bf16_f32 v71, v66, v67
	v_cvt_pk_bf16_f32 v70, v64, v65
	global_store_dwordx4 v[160:161], v[68:71], off offset:256
	v_add_u32_e32 v84, 0x90, v146
	v_ashrrev_i32_e32 v85, 31, v84
	v_add_u32_e32 v68, 0x80, v146
	v_ashrrev_i32_e32 v69, 31, v68
	v_lshlrev_b64 v[64:65], 10, v[68:69]
	v_lshl_add_u64 v[64:65], v[64:65], 0, v[144:145]
	v_lshlrev_b64 v[76:77], 1, v[64:65]
	v_lshlrev_b64 v[68:69], 11, v[68:69]
	v_lshl_add_u64 v[64:65], s[6:7], 0, v[76:77]
	v_lshl_add_u64 v[96:97], v[148:149], 0, v[68:69]
	global_load_dwordx4 v[64:67], v[64:65], off
	v_or_b32_e32 v76, 0x100, v76
	global_load_dwordx4 v[68:71], v[96:97], off
	v_lshl_add_u64 v[72:73], s[6:7], 0, v[76:77]
	v_lshl_add_u64 v[76:77], s[0:1], 0, v[76:77]
	global_load_dwordx4 v[72:75], v[72:73], off
	v_lshlrev_b64 v[80:81], 10, v[84:85]
	global_load_dwordx4 v[76:79], v[76:77], off
	v_lshl_add_u64 v[80:81], v[80:81], 0, v[144:145]
	v_lshlrev_b64 v[92:93], 1, v[80:81]
	v_lshlrev_b64 v[84:85], 11, v[84:85]
	v_lshl_add_u64 v[80:81], s[6:7], 0, v[92:93]
	v_lshl_add_u64 v[98:99], v[148:149], 0, v[84:85]
	global_load_dwordx4 v[80:83], v[80:81], off
	v_or_b32_e32 v92, 0x100, v92
	global_load_dwordx4 v[84:87], v[98:99], off
	v_lshl_add_u64 v[88:89], s[6:7], 0, v[92:93]
	v_lshl_add_u64 v[92:93], s[0:1], 0, v[92:93]
	global_load_dwordx4 v[88:91], v[88:89], off
	s_waitcnt vmcnt(6)
	v_lshlrev_b32_e32 v100, 16, v64
	global_load_dwordx4 v[92:95], v[92:93], off
	v_and_b32_e32 v101, 0xffff0000, v64
	v_lshlrev_b32_e32 v64, 16, v65
	v_and_b32_e32 v65, 0xffff0000, v65
	s_waitcnt vmcnt(6)
; __device__ __forceinline__ u32x2 pack4(f32x4 v) { u32x2 w; w.x = cvt_pk_bf16(v[0], v[1]); w.y = cvt_pk_bf16(v[2], v[3]); return w; }
; __device__ __forceinline__ f32x4 unpack4(u32x2 w) { f32x4 v; v[0] = __uint_as_float(w.x << 16); v[1] = __uint_as_float(w.x & 0xffff0000u); v[2] = __uint_as_float(w.y << 16); v[3] = __uint_as_float(w.y & 0xffff0000u); return v; }
;     __device__ __forceinline__ void operator()(const f32x4 (&acc)[2][2][4][2], const Unit& u, int wr, int wc, int fr, int fq) const {
;     ...
;             for (int m = mh; m < mh + 2; ++m)
; #pragma unroll
;                 for (int bj = 0; bj < 2; ++bj)
; #pragma unroll
;                     for (int n = 0; n < 2; ++n) { const size_t off = (size_t)(row0 + ai * HALF + m * 16) * 1024 + col0 + bj * HALF + n * 4;
;                         pg[m][bj][n] = *(const u32x2*)(G + off); if (ADD) pm_[m][bj][n] = *(const u32x2*)(Mg + off); }
;             asm volatile("" ::: "memory");
; #pragma unroll
;             for (int m = mh; m < mh + 2; ++m)
; #pragma unroll
;                 for (int bj = 0; bj < 2; ++bj)
; #pragma unroll
;                     for (int n = 0; n < 2; ++n) { const size_t off = (size_t)(row0 + ai * HALF + m * 16) * 1024 + col0 + bj * HALF + n * 4;
;                         f32x4 o = unpack4(pg[m][bj][n]) * acc[ai][bj][m][n]; if (ADD) o = o + unpack4(pm_[m][bj][n]);
;                         *(u32x2*)(Mg + off) = pack4(o); }
;             asm volatile("" ::: "memory");
;         }
	v_lshlrev_b32_e32 v102, 16, v68
	v_and_b32_e32 v103, 0xffff0000, v68
	v_lshlrev_b32_e32 v68, 16, v69
	v_and_b32_e32 v69, 0xffff0000, v69
	v_pk_fma_f32 v[62:63], v[62:63], v[64:65], v[68:69]
	v_pk_fma_f32 v[60:61], v[60:61], v[100:101], v[102:103]
	v_lshlrev_b32_e32 v64, 16, v67
	v_cvt_pk_bf16_f32 v60, v60, v61
	v_cvt_pk_bf16_f32 v61, v62, v63
	v_lshlrev_b32_e32 v62, 16, v66
	v_and_b32_e32 v63, 0xffff0000, v66
	v_and_b32_e32 v65, 0xffff0000, v67
	v_lshlrev_b32_e32 v66, 16, v70
	v_and_b32_e32 v67, 0xffff0000, v70
	v_lshlrev_b32_e32 v68, 16, v71
	v_and_b32_e32 v69, 0xffff0000, v71
	v_pk_fma_f32 v[58:59], v[58:59], v[64:65], v[68:69]
	v_pk_fma_f32 v[56:57], v[56:57], v[62:63], v[66:67]
	v_cvt_pk_bf16_f32 v63, v58, v59
	v_cvt_pk_bf16_f32 v62, v56, v57
	global_store_dwordx4 v[96:97], v[60:63], off
	s_waitcnt vmcnt(6)
	v_lshlrev_b32_e32 v56, 16, v72
	v_and_b32_e32 v57, 0xffff0000, v72
	v_lshlrev_b32_e32 v58, 16, v73
	v_and_b32_e32 v59, 0xffff0000, v73
	s_waitcnt vmcnt(5)
	v_lshlrev_b32_e32 v60, 16, v76
	v_and_b32_e32 v61, 0xffff0000, v76
	v_lshlrev_b32_e32 v62, 16, v77
	v_and_b32_e32 v63, 0xffff0000, v77
	v_pk_fma_f32 v[54:55], v[54:55], v[58:59], v[62:63]
	v_pk_fma_f32 v[52:53], v[52:53], v[56:57], v[60:61]
	v_lshlrev_b32_e32 v56, 16, v75
	v_cvt_pk_bf16_f32 v52, v52, v53
	v_cvt_pk_bf16_f32 v53, v54, v55
	v_lshlrev_b32_e32 v54, 16, v74
	v_and_b32_e32 v55, 0xffff0000, v74
	v_and_b32_e32 v57, 0xffff0000, v75
	v_lshlrev_b32_e32 v58, 16, v78
	v_and_b32_e32 v59, 0xffff0000, v78
	v_lshlrev_b32_e32 v60, 16, v79
	v_and_b32_e32 v61, 0xffff0000, v79
	v_pk_fma_f32 v[46:47], v[46:47], v[56:57], v[60:61]
	v_pk_fma_f32 v[44:45], v[44:45], v[54:55], v[58:59]
	v_cvt_pk_bf16_f32 v55, v46, v47
	v_cvt_pk_bf16_f32 v54, v44, v45
	global_store_dwordx4 v[96:97], v[52:55], off offset:256
	s_waitcnt vmcnt(5)
	v_lshlrev_b32_e32 v44, 16, v80
	v_and_b32_e32 v45, 0xffff0000, v80
	v_lshlrev_b32_e32 v46, 16, v81
	v_and_b32_e32 v47, 0xffff0000, v81
	s_waitcnt vmcnt(4)
	v_lshlrev_b32_e32 v52, 16, v84
	v_and_b32_e32 v53, 0xffff0000, v84
	v_lshlrev_b32_e32 v54, 16, v85
	v_and_b32_e32 v55, 0xffff0000, v85
	v_pk_fma_f32 v[46:47], v[50:51], v[46:47], v[54:55]
	v_pk_fma_f32 v[44:45], v[48:49], v[44:45], v[52:53]
	v_lshlrev_b32_e32 v48, 16, v83
	v_cvt_pk_bf16_f32 v44, v44, v45
	v_cvt_pk_bf16_f32 v45, v46, v47
	v_lshlrev_b32_e32 v46, 16, v82
	v_and_b32_e32 v47, 0xffff0000, v82
	v_and_b32_e32 v49, 0xffff0000, v83
	v_lshlrev_b32_e32 v50, 16, v86
	v_and_b32_e32 v51, 0xffff0000, v86
	v_lshlrev_b32_e32 v52, 16, v87
	v_and_b32_e32 v53, 0xffff0000, v87
	v_pk_fma_f32 v[42:43], v[42:43], v[48:49], v[52:53]
	v_pk_fma_f32 v[40:41], v[40:41], v[46:47], v[50:51]
	v_cvt_pk_bf16_f32 v47, v42, v43
	v_cvt_pk_bf16_f32 v46, v40, v41
	global_store_dwordx4 v[98:99], v[44:47], off
	s_waitcnt vmcnt(4)
	v_lshlrev_b32_e32 v40, 16, v88
	v_and_b32_e32 v41, 0xffff0000, v88
	v_lshlrev_b32_e32 v42, 16, v89
	v_and_b32_e32 v43, 0xffff0000, v89
	s_waitcnt vmcnt(3)
	v_lshlrev_b32_e32 v44, 16, v92
	v_and_b32_e32 v45, 0xffff0000, v92
	v_lshlrev_b32_e32 v46, 16, v93
	v_and_b32_e32 v47, 0xffff0000, v93
	v_pk_fma_f32 v[38:39], v[38:39], v[42:43], v[46:47]
	v_pk_fma_f32 v[36:37], v[36:37], v[40:41], v[44:45]
	v_lshlrev_b32_e32 v40, 16, v91
	v_cvt_pk_bf16_f32 v36, v36, v37
	v_cvt_pk_bf16_f32 v37, v38, v39
	v_lshlrev_b32_e32 v38, 16, v90
	v_and_b32_e32 v39, 0xffff0000, v90
	v_and_b32_e32 v41, 0xffff0000, v91
	v_lshlrev_b32_e32 v42, 16, v94
	v_and_b32_e32 v43, 0xffff0000, v94
	v_lshlrev_b32_e32 v44, 16, v95
	v_and_b32_e32 v45, 0xffff0000, v95
	v_pk_fma_f32 v[34:35], v[34:35], v[40:41], v[44:45]
	v_pk_fma_f32 v[32:33], v[32:33], v[38:39], v[42:43]
	v_cvt_pk_bf16_f32 v39, v34, v35
	v_cvt_pk_bf16_f32 v38, v32, v33
	global_store_dwordx4 v[98:99], v[36:39], off offset:256
	v_add_u32_e32 v52, 0xb0, v146
	v_ashrrev_i32_e32 v53, 31, v52
	v_add_u32_e32 v36, 0xa0, v146
	v_ashrrev_i32_e32 v37, 31, v36
	v_lshlrev_b64 v[32:33], 10, v[36:37]
	v_lshl_add_u64 v[32:33], v[32:33], 0, v[144:145]
	v_lshlrev_b64 v[44:45], 1, v[32:33]
	v_lshlrev_b64 v[36:37], 11, v[36:37]
	v_lshl_add_u64 v[32:33], s[6:7], 0, v[44:45]
	v_lshl_add_u64 v[64:65], v[148:149], 0, v[36:37]
	global_load_dwordx4 v[32:35], v[32:33], off
	v_or_b32_e32 v44, 0x100, v44
	global_load_dwordx4 v[36:39], v[64:65], off
	v_lshl_add_u64 v[40:41], s[6:7], 0, v[44:45]
	v_lshl_add_u64 v[44:45], s[0:1], 0, v[44:45]
	global_load_dwordx4 v[40:43], v[40:41], off
	v_lshlrev_b64 v[48:49], 10, v[52:53]
	global_load_dwordx4 v[44:47], v[44:45], off
	v_lshl_add_u64 v[48:49], v[48:49], 0, v[144:145]
	v_lshlrev_b64 v[60:61], 1, v[48:49]
	v_lshlrev_b64 v[52:53], 11, v[52:53]
	v_lshl_add_u64 v[48:49], s[6:7], 0, v[60:61]
	v_lshl_add_u64 v[66:67], v[148:149], 0, v[52:53]
	global_load_dwordx4 v[48:51], v[48:49], off
	v_or_b32_e32 v60, 0x100, v60
	global_load_dwordx4 v[52:55], v[66:67], off
	v_lshl_add_u64 v[56:57], s[6:7], 0, v[60:61]
	v_lshl_add_u64 v[60:61], s[0:1], 0, v[60:61]
	global_load_dwordx4 v[56:59], v[56:57], off
	s_waitcnt vmcnt(6)
; __device__ __forceinline__ u32x2 pack4(f32x4 v) { u32x2 w; w.x = cvt_pk_bf16(v[0], v[1]); w.y = cvt_pk_bf16(v[2], v[3]); return w; }
; __device__ __forceinline__ f32x4 unpack4(u32x2 w) { f32x4 v; v[0] = __uint_as_float(w.x << 16); v[1] = __uint_as_float(w.x & 0xffff0000u); v[2] = __uint_as_float(w.y << 16); v[3] = __uint_as_float(w.y & 0xffff0000u); return v; }
; #define PG8_BAR __builtin_amdgcn_s_barrier()
;     __device__ __forceinline__ void operator()(const f32x4 (&acc)[2][2][4][2], const Unit& u, int wr, int wc, int fr, int fq) const {
;     ...
; #pragma unroll
;             for (int m = mh; m < mh + 2; ++m)
; #pragma unroll
;                 for (int bj = 0; bj < 2; ++bj)
; #pragma unroll
;                     for (int n = 0; n < 2; ++n) { const size_t off = (size_t)(row0 + ai * HALF + m * 16) * 1024 + col0 + bj * HALF + n * 4;
;                         f32x4 o = unpack4(pg[m][bj][n]) * acc[ai][bj][m][n]; if (ADD) o = o + unpack4(pm_[m][bj][n]);
;                         *(u32x2*)(Mg + off) = pack4(o); }
;             asm volatile("" ::: "memory");
;         }
; template <class Epi, class Sched, bool ALIGN_EPI = false, bool SP2 = false>
; __device__ __forceinline__ void gemm_phase(PG8_LAS unsigned char* lds, const Gemm g, const Sched& S, const Epi& E) {
;     ...
;         if (!has_next) break;
; #pragma unroll
;         for (int a = 0; a < 2; ++a)
; #pragma unroll
;             for (int b = 0; b < 2; ++b)
; #pragma unroll
;                 for (int m = 0; m < 4; ++m)
; #pragma unroll
;                     for (int n = 0; n < 2; ++n) acc[a][b][m][n] = (f32x4){0.f, 0.f, 0.f, 0.f};
;         cur = nxt; cA = nA; cB = nB; ++ui;
;         if constexpr (ALIGN_EPI) { if (wr == 1) PG8_BAR; }
	v_lshlrev_b32_e32 v68, 16, v32
	global_load_dwordx4 v[60:63], v[60:61], off
	v_and_b32_e32 v69, 0xffff0000, v32
	v_lshlrev_b32_e32 v32, 16, v33
	v_and_b32_e32 v33, 0xffff0000, v33
	s_waitcnt vmcnt(6)
	v_lshlrev_b32_e32 v70, 16, v36
	v_and_b32_e32 v71, 0xffff0000, v36
	v_lshlrev_b32_e32 v36, 16, v37
	v_and_b32_e32 v37, 0xffff0000, v37
	v_pk_fma_f32 v[30:31], v[30:31], v[32:33], v[36:37]
	v_pk_fma_f32 v[28:29], v[28:29], v[68:69], v[70:71]
	v_lshlrev_b32_e32 v32, 16, v35
	v_cvt_pk_bf16_f32 v28, v28, v29
	v_cvt_pk_bf16_f32 v29, v30, v31
	v_lshlrev_b32_e32 v30, 16, v34
	v_and_b32_e32 v31, 0xffff0000, v34
	v_and_b32_e32 v33, 0xffff0000, v35
	v_lshlrev_b32_e32 v34, 16, v38
	v_and_b32_e32 v35, 0xffff0000, v38
	v_lshlrev_b32_e32 v36, 16, v39
	v_and_b32_e32 v37, 0xffff0000, v39
	v_pk_fma_f32 v[26:27], v[26:27], v[32:33], v[36:37]
	v_pk_fma_f32 v[24:25], v[24:25], v[30:31], v[34:35]
	v_cvt_pk_bf16_f32 v31, v26, v27
	v_cvt_pk_bf16_f32 v30, v24, v25
	global_store_dwordx4 v[64:65], v[28:31], off
	s_waitcnt vmcnt(6)
	v_lshlrev_b32_e32 v24, 16, v40
	v_and_b32_e32 v25, 0xffff0000, v40
	v_lshlrev_b32_e32 v26, 16, v41
	v_and_b32_e32 v27, 0xffff0000, v41
	s_waitcnt vmcnt(5)
	v_lshlrev_b32_e32 v28, 16, v44
	v_and_b32_e32 v29, 0xffff0000, v44
	v_lshlrev_b32_e32 v30, 16, v45
	v_and_b32_e32 v31, 0xffff0000, v45
	v_pk_fma_f32 v[22:23], v[22:23], v[26:27], v[30:31]
	v_pk_fma_f32 v[20:21], v[20:21], v[24:25], v[28:29]
	v_lshlrev_b32_e32 v24, 16, v43
	v_cvt_pk_bf16_f32 v20, v20, v21
	v_cvt_pk_bf16_f32 v21, v22, v23
	v_lshlrev_b32_e32 v22, 16, v42
	v_and_b32_e32 v23, 0xffff0000, v42
	v_and_b32_e32 v25, 0xffff0000, v43
	v_lshlrev_b32_e32 v26, 16, v46
	v_and_b32_e32 v27, 0xffff0000, v46
	v_lshlrev_b32_e32 v28, 16, v47
	v_and_b32_e32 v29, 0xffff0000, v47
	v_pk_fma_f32 v[14:15], v[14:15], v[24:25], v[28:29]
	v_pk_fma_f32 v[12:13], v[12:13], v[22:23], v[26:27]
	v_cvt_pk_bf16_f32 v23, v14, v15
	v_cvt_pk_bf16_f32 v22, v12, v13
	global_store_dwordx4 v[64:65], v[20:23], off offset:256
	s_waitcnt vmcnt(5)
	v_lshlrev_b32_e32 v12, 16, v48
	v_and_b32_e32 v13, 0xffff0000, v48
	v_lshlrev_b32_e32 v14, 16, v49
	v_and_b32_e32 v15, 0xffff0000, v49
	s_waitcnt vmcnt(4)
	v_lshlrev_b32_e32 v20, 16, v52
	v_and_b32_e32 v21, 0xffff0000, v52
	v_lshlrev_b32_e32 v22, 16, v53
	v_and_b32_e32 v23, 0xffff0000, v53
	v_pk_fma_f32 v[14:15], v[18:19], v[14:15], v[22:23]
	v_pk_fma_f32 v[12:13], v[16:17], v[12:13], v[20:21]
	v_lshlrev_b32_e32 v16, 16, v51
	v_cvt_pk_bf16_f32 v12, v12, v13
	v_cvt_pk_bf16_f32 v13, v14, v15
	v_lshlrev_b32_e32 v14, 16, v50
	v_and_b32_e32 v15, 0xffff0000, v50
	v_and_b32_e32 v17, 0xffff0000, v51
	v_lshlrev_b32_e32 v18, 16, v54
	v_and_b32_e32 v19, 0xffff0000, v54
	v_lshlrev_b32_e32 v20, 16, v55
	v_and_b32_e32 v21, 0xffff0000, v55
	v_pk_fma_f32 v[10:11], v[10:11], v[16:17], v[20:21]
	v_pk_fma_f32 v[8:9], v[8:9], v[14:15], v[18:19]
	v_cvt_pk_bf16_f32 v15, v10, v11
	v_cvt_pk_bf16_f32 v14, v8, v9
	global_store_dwordx4 v[66:67], v[12:15], off
	s_waitcnt vmcnt(4)
	v_lshlrev_b32_e32 v8, 16, v56
	v_and_b32_e32 v9, 0xffff0000, v56
	v_lshlrev_b32_e32 v10, 16, v57
	v_and_b32_e32 v11, 0xffff0000, v57
	s_waitcnt vmcnt(3)
	v_lshlrev_b32_e32 v12, 16, v60
	v_and_b32_e32 v13, 0xffff0000, v60
	v_lshlrev_b32_e32 v14, 16, v61
	v_and_b32_e32 v15, 0xffff0000, v61
	v_pk_fma_f32 v[6:7], v[6:7], v[10:11], v[14:15]
	v_pk_fma_f32 v[4:5], v[4:5], v[8:9], v[12:13]
	v_lshlrev_b32_e32 v8, 16, v59
	v_cvt_pk_bf16_f32 v4, v4, v5
	v_cvt_pk_bf16_f32 v5, v6, v7
	v_lshlrev_b32_e32 v6, 16, v58
	v_and_b32_e32 v7, 0xffff0000, v58
	v_and_b32_e32 v9, 0xffff0000, v59
	v_lshlrev_b32_e32 v10, 16, v62
	v_and_b32_e32 v11, 0xffff0000, v62
	v_lshlrev_b32_e32 v12, 16, v63
	v_and_b32_e32 v13, 0xffff0000, v63
	v_pk_fma_f32 v[2:3], v[2:3], v[8:9], v[12:13]
	v_pk_fma_f32 v[0:1], v[0:1], v[6:7], v[10:11]
	v_cvt_pk_bf16_f32 v7, v2, v3
	v_cvt_pk_bf16_f32 v6, v0, v1
	global_store_dwordx4 v[66:67], v[4:7], off offset:256
	s_cbranch_vccnz .Lal_p6b_exit
	s_cmpk_lt_u32 s40, 0x100
	s_cbranch_scc1 .LBB0_744
	s_barrier
	s_branch .LBB0_744
.Lal_p6b_exit:
	s_waitcnt vmcnt(0)
.LBB0_751:
	s_barrier

; #define PG8_BAR __builtin_amdgcn_s_barrier()
;     __host__ __device__ bool next(int i, Unit& u) const {
;         const long L = (long)i * G + c; if (L >= nwg) return false;
;         int wgid = (int)L; { const int q = nwg / NXCD, r = nwg % NXCD, xcd = wgid % NXCD, off = wgid / NXCD; wgid = (xcd < r ? xcd * (q + 1) : r * (q + 1) + (xcd - r) * q) + off; }
;         const int nig = WGM * nN, gid = wgid / nig, fm = gid * WGM, gsz = (nM - fm) < WGM ? (nM - fm) : WGM;
;         u.pm = fm + ((wgid % nig) % gsz); u.pn = (wgid % nig) / gsz; return true;
;     }
; template <class Epi, class Sched, bool ALIGN_EPI = false, bool SP2 = false>
; __device__ __forceinline__ void gemm_phase(PG8_LAS unsigned char* lds, const Gemm g, const Sched& S, const Epi& E) {
;     ...
;         if (!has_next) break;
; #pragma unroll
;         for (int a = 0; a < 2; ++a)
; #pragma unroll
;             for (int b = 0; b < 2; ++b)
; #pragma unroll
;                 for (int m = 0; m < 4; ++m)
; #pragma unroll
;                     for (int n = 0; n < 2; ++n) acc[a][b][m][n] = (f32x4){0.f, 0.f, 0.f, 0.f};
;         cur = nxt; cA = nA; cB = nB; ++ui;
;         if constexpr (ALIGN_EPI) { if (wr == 1) PG8_BAR; }
.LBB0_809:
	s_or_b64 exec, exec, s[24:25]
	s_and_b64 vcc, exec, s[4:5]
	s_mov_b32 s23, s12
	s_mov_b32 s22, s14
	s_mov_b64 s[26:27], s[20:21]
	s_mov_b64 s[24:25], s[18:19]
	s_cbranch_vccnz .LBB0_830
	s_cmpk_lt_u32 s38, 0x100
	s_cbranch_scc1 .Lal_p7_post
	s_barrier
.Lal_p7_post:
.LBB0_810:
	s_add_i32 s46, s46, 1
	s_mul_i32 s4, s46, s49
	s_mul_hi_u32 s5, s46, s11
	s_add_i32 s5, s5, s4
	s_mul_i32 s4, s46, s11
	s_add_u32 s18, s4, s10
	s_addc_u32 s19, s5, s40
	v_cmp_gt_i64_e64 s[4:5], s[18:19], v[158:159]
	s_and_b64 vcc, exec, s[4:5]
	s_cbranch_vccnz .LBB0_812
	s_ashr_i32 s12, s18, 31
	s_lshr_b32 s12, s12, 29
	s_add_i32 s12, s18, s12
	s_ashr_i32 s13, s12, 3
	s_and_b32 s12, s12, -8
	s_sub_i32 s12, s18, s12
	s_cmp_lt_i32 s12, 0
	s_cselect_b32 s14, s41, 0x60
	s_mul_i32 s12, s12, s14
	s_add_i32 s12, s12, s13
	s_ashr_i32 s13, s12, 31
	s_lshr_b32 s13, s13, 27
	s_add_i32 s13, s12, s13
	s_ashr_i32 s14, s13, 5
	s_lshl_b32 s14, s14, 3
	s_sub_i32 s15, 0xc0, s14
	s_min_i32 s15, s15, 8
	s_abs_i32 s20, s15
	v_cvt_f32_u32_e32 v0, s20
	s_sub_i32 s36, 0, s20
	s_andn2_b32 s13, s13, 31
	s_sub_i32 s13, s12, s13
	v_rcp_iflag_f32_e32 v0, v0
	s_abs_i32 s12, s13
	s_xor_b32 s21, s13, s15
	s_ashr_i32 s21, s21, 31
	v_mul_f32_e32 v0, 0x4f7ffffe, v0
	v_cvt_u32_f32_e32 v0, v0
	s_nop 0
	v_readfirstlane_b32 s37, v0
	s_mul_i32 s36, s36, s37
	s_mul_hi_u32 s36, s37, s36
	s_add_i32 s37, s37, s36
	s_mul_hi_u32 s36, s12, s37
	s_mul_i32 s37, s36, s20
	s_sub_i32 s12, s12, s37
	s_add_i32 s60, s36, 1
	s_sub_i32 s37, s12, s20
	s_cmp_ge_u32 s12, s20
	s_cselect_b32 s36, s60, s36
	s_cselect_b32 s12, s37, s12
	s_add_i32 s37, s36, 1
	s_cmp_ge_u32 s12, s20
	s_cselect_b32 s12, s37, s36
	s_xor_b32 s12, s12, s21
	s_sub_i32 s12, s12, s21
	s_mul_i32 s15, s12, s15
	s_sub_i32 s13, s13, s15
	s_add_i32 s14, s14, s13

; #define PG8_STAGE(bufoff, gbase, voff) do { _Pragma("unroll") for (int _i = 0; _i < 2; ++_i) \
;         __builtin_amdgcn_global_load_lds((const unsigned*)((const char*)(gbase) + (voff)[_i]), (PG8_LAS unsigned*)(lds + (bufoff) + ldsw + _i * 8192), 16, 0, 0); } while (0)
; #define PG8_LDA(dst, b, h) do { _Pragma("unroll") for (int m = 0; m < 4; ++m) _Pragma("unroll") for (int k = 0; k < 2; ++k) dst[m][k] = *(const PG8_LAS bf16x8*)(lds + PG8_SA(b, h) + aoff + m * 2048 + k * 1024); } while (0)
; #define PG8_LDB(dst, b, h) do { _Pragma("unroll") for (int n = 0; n < 2; ++n) _Pragma("unroll") for (int k = 0; k < 2; ++k) dst[n][k] = *(const PG8_LAS bf16x8*)(lds + PG8_SB(b, h) + boff + n * 2048 + k * 1024); } while (0)
; #define PG8_MMA(ai, bj, At, Bt) do { __builtin_amdgcn_s_setprio(1); _Pragma("unroll") for (int m = 0; m < 4; ++m) _Pragma("unroll") for (int n = 0; n < 2; ++n) _Pragma("unroll") for (int k = 0; k < 2; ++k) \
;         acc[ai][bj][m][n] = __builtin_amdgcn_mfma_f32_16x16x32_bf16(Bt[n][k], At[m][k], acc[ai][bj][m][n], 0, 0, 0); __builtin_amdgcn_s_setprio(0); } while (0)
; #define PG8_WAIT_V(n) asm volatile("s_waitcnt vmcnt(" #n ")" ::: "memory")
; template <class Epi, class Sched, bool ALIGN_EPI = false, bool SP2 = false>
; __device__ __forceinline__ void gemm_phase(PG8_LAS unsigned char* lds, const Gemm g, const Sched& S, const Epi& E) {
;     ...
;         const char* nA = has_next ? (const char*)g.A + (size_t)nxt.pm * tstep : cA; const char* nB = has_next ? (const char*)g.Bt + (size_t)nxt.pn * tstep : cB;
;         for (int t = 0; t < nt; t += 2) {
;             const bool last = (t == nt - 2);
;             const char* a1 = cA + (size_t)(t + 1) * kstep;
;             const char* a2 = last ? nA : cA + (size_t)(t + 2) * kstep; const char* b2 = last ? nB : cB + (size_t)(t + 2) * kstep;
;             const char* a3 = a2 + kstep; const char* b3 = b2 + kstep;
;             if (last && has_next) S.a_ready(nxt);
;             if constexpr (SP2) {
;             PG8_LDB(B0, 0, 0); PG8_LDB(B1, 0, 1); PG8_SCHED; PG8_LDA(At, 0, 0); PG8_STAGE(PG8_SA(1, 1), a1 + hstep, voffA);
;             PG8_WAIT_V(8); PG8_WAIT_L(0); PG8_BAR; PG8_MMA(0, 0, At, B0); PG8_MMA(0, 1, At, B1); PG8_BAR; PG8_SCHED;
;             PG8_LDA(At, 0, 1); PG8_STAGE(PG8_SB(0, 0), b2, voffB); PG8_STAGE(PG8_SB(0, 1), b2 + hstep, voffB); PG8_STAGE(PG8_SA(0, 0), a2, voffA);
.LBB0_813:
	ds_read_b128 v[128:131], v173
	ds_read_b128 v[132:135], v173 offset:1024
	ds_read_b128 v[136:139], v173 offset:2048
	ds_read_b128 v[140:143], v173 offset:3072
	ds_read_b128 v[160:163], v174
	ds_read_b128 v[164:167], v174 offset:1024
	ds_read_b128 v[178:181], v174 offset:2048
	ds_read_b128 v[182:185], v174 offset:3072
	s_add_u32 s26, s24, 0xfffc0080
	s_addc_u32 s27, s25, -1
	s_cmp_eq_u32 s70, 12
	s_cselect_b32 s37, s15, s27
	s_cselect_b32 s36, s60, s26
	s_cselect_b32 s27, s13, s69
	s_cselect_b32 s26, s61, s68
	v_lshl_add_u64 v[168:169], s[24:25], 0, v[152:153]
	s_add_i32 m0, s42, 0xc000
	ds_read_b128 v[186:189], v175
	ds_read_b128 v[190:193], v175 offset:1024
	ds_read_b128 v[194:197], v175 offset:2048
	ds_read_b128 v[198:201], v175 offset:3072
	ds_read_b128 v[202:205], v175 offset:4096
	ds_read_b128 v[206:209], v175 offset:5120
	ds_read_b128 v[210:213], v175 offset:6144
	ds_read_b128 v[214:217], v175 offset:7168
	global_load_lds_dwordx4 v[168:169], off
	v_lshl_add_u64 v[168:169], s[24:25], 0, v[154:155]
	s_add_i32 m0, s42, 0xe000
	s_nop 0
	global_load_lds_dwordx4 v[168:169], off
	s_waitcnt vmcnt(8)
	s_waitcnt lgkmcnt(0)
	s_barrier
	s_setprio 1
	s_waitcnt lgkmcnt(0)
	v_mfma_f32_16x16x32_bf16 v[124:127], v[128:131], v[186:189], v[124:127]
	v_mfma_f32_16x16x32_bf16 v[120:123], v[136:139], v[186:189], v[120:123]
	v_mfma_f32_16x16x32_bf16 v[108:111], v[128:131], v[194:197], v[108:111]
	v_mfma_f32_16x16x32_bf16 v[104:107], v[136:139], v[194:197], v[104:107]
	v_mfma_f32_16x16x32_bf16 v[92:95], v[128:131], v[202:205], v[92:95]
	v_mfma_f32_16x16x32_bf16 v[88:91], v[136:139], v[202:205], v[88:91]
	v_mfma_f32_16x16x32_bf16 v[76:79], v[128:131], v[210:213], v[76:79]
	v_mfma_f32_16x16x32_bf16 v[72:75], v[136:139], v[210:213], v[72:75]
	v_mfma_f32_16x16x32_bf16 v[124:127], v[132:135], v[190:193], v[124:127]
	v_mfma_f32_16x16x32_bf16 v[120:123], v[140:143], v[190:193], v[120:123]
	v_mfma_f32_16x16x32_bf16 v[108:111], v[132:135], v[198:201], v[108:111]
	v_mfma_f32_16x16x32_bf16 v[104:107], v[140:143], v[198:201], v[104:107]
	v_mfma_f32_16x16x32_bf16 v[92:95], v[132:135], v[206:209], v[92:95]
	v_mfma_f32_16x16x32_bf16 v[88:91], v[140:143], v[206:209], v[88:91]
	v_mfma_f32_16x16x32_bf16 v[76:79], v[132:135], v[214:217], v[76:79]
	v_mfma_f32_16x16x32_bf16 v[72:75], v[140:143], v[214:217], v[72:75]
	s_setprio 0
	s_setprio 1
	v_mfma_f32_16x16x32_bf16 v[116:119], v[160:163], v[186:189], v[116:119]
	v_mfma_f32_16x16x32_bf16 v[112:115], v[178:181], v[186:189], v[112:115]
	v_mfma_f32_16x16x32_bf16 v[100:103], v[160:163], v[194:197], v[100:103]
	v_mfma_f32_16x16x32_bf16 v[96:99], v[178:181], v[194:197], v[96:99]
	v_mfma_f32_16x16x32_bf16 v[84:87], v[160:163], v[202:205], v[84:87]
	v_mfma_f32_16x16x32_bf16 v[80:83], v[178:181], v[202:205], v[80:83]
	v_mfma_f32_16x16x32_bf16 v[68:71], v[160:163], v[210:213], v[68:71]
	v_mfma_f32_16x16x32_bf16 v[64:67], v[178:181], v[210:213], v[64:67]
	v_mfma_f32_16x16x32_bf16 v[116:119], v[164:167], v[190:193], v[116:119]
	v_mfma_f32_16x16x32_bf16 v[112:115], v[182:185], v[190:193], v[112:115]
	v_mfma_f32_16x16x32_bf16 v[100:103], v[164:167], v[198:201], v[100:103]
	v_mfma_f32_16x16x32_bf16 v[96:99], v[182:185], v[198:201], v[96:99]
	v_mfma_f32_16x16x32_bf16 v[84:87], v[164:167], v[206:209], v[84:87]
	v_mfma_f32_16x16x32_bf16 v[80:83], v[182:185], v[206:209], v[80:83]
	v_mfma_f32_16x16x32_bf16 v[68:71], v[164:167], v[214:217], v[68:71]
	v_mfma_f32_16x16x32_bf16 v[64:67], v[182:185], v[214:217], v[64:67]
	s_setprio 0
	s_barrier
	s_add_i32 s71, s52, s39
	v_lshl_add_u64 v[168:169], s[26:27], 0, v[148:149]
	s_mov_b32 m0, s71
	ds_read_b128 v[186:189], v175 offset:16384
	ds_read_b128 v[190:193], v175 offset:17408
	ds_read_b128 v[194:197], v175 offset:18432
	ds_read_b128 v[198:201], v175 offset:19456
	ds_read_b128 v[202:205], v175 offset:20480
	ds_read_b128 v[206:209], v175 offset:21504
	ds_read_b128 v[210:213], v175 offset:22528
	ds_read_b128 v[214:217], v175 offset:23552
	global_load_lds_dwordx4 v[168:169], off
	s_add_i32 m0, s71, 0x2000
	s_add_u32 s72, s26, 0x40000
	v_lshl_add_u64 v[218:219], s[26:27], 0, v[144:145]
	s_addc_u32 s73, s27, 0
	s_add_i32 s71, s53, s39
	global_load_lds_dwordx4 v[218:219], off
	v_lshl_add_u64 v[220:221], s[72:73], 0, v[148:149]
	s_mov_b32 m0, s71
	v_lshl_add_u64 v[222:223], s[36:37], 0, v[146:147]
	global_load_lds_dwordx4 v[220:221], off
	v_lshl_add_u64 v[220:221], s[72:73], 0, v[144:145]
	s_add_i32 m0, s71, 0x2000
	s_nop 0
	global_load_lds_dwordx4 v[220:221], off
	v_lshl_add_u64 v[220:221], s[36:37], 0, v[150:151]
	s_mov_b32 m0, s42
	s_nop 0
	global_load_lds_dwordx4 v[220:221], off
	s_mov_b32 m0, s43
	s_nop 0
	global_load_lds_dwordx4 v[222:223], off
	s_waitcnt vmcnt(8)
	s_waitcnt lgkmcnt(0)
	s_barrier
; #define PG8_STAGE(bufoff, gbase, voff) do { _Pragma("unroll") for (int _i = 0; _i < 2; ++_i) \
;         __builtin_amdgcn_global_load_lds((const unsigned*)((const char*)(gbase) + (voff)[_i]), (PG8_LAS unsigned*)(lds + (bufoff) + ldsw + _i * 8192), 16, 0, 0); } while (0)
; #define PG8_LDA(dst, b, h) do { _Pragma("unroll") for (int m = 0; m < 4; ++m) _Pragma("unroll") for (int k = 0; k < 2; ++k) dst[m][k] = *(const PG8_LAS bf16x8*)(lds + PG8_SA(b, h) + aoff + m * 2048 + k * 1024); } while (0)
; #define PG8_LDB(dst, b, h) do { _Pragma("unroll") for (int n = 0; n < 2; ++n) _Pragma("unroll") for (int k = 0; k < 2; ++k) dst[n][k] = *(const PG8_LAS bf16x8*)(lds + PG8_SB(b, h) + boff + n * 2048 + k * 1024); } while (0)
; #define PG8_MMA(ai, bj, At, Bt) do { __builtin_amdgcn_s_setprio(1); _Pragma("unroll") for (int m = 0; m < 4; ++m) _Pragma("unroll") for (int n = 0; n < 2; ++n) _Pragma("unroll") for (int k = 0; k < 2; ++k) \
;         acc[ai][bj][m][n] = __builtin_amdgcn_mfma_f32_16x16x32_bf16(Bt[n][k], At[m][k], acc[ai][bj][m][n], 0, 0, 0); __builtin_amdgcn_s_setprio(0); } while (0)
; #define PG8_WAIT_V(n) asm volatile("s_waitcnt vmcnt(" #n ")" ::: "memory")
; #define PG8_WAIT_L(n) asm volatile("s_waitcnt lgkmcnt(" #n ")" ::: "memory")
; #define PG8_BAR __builtin_amdgcn_s_barrier()
; #define PG8_SCHED __builtin_amdgcn_sched_barrier(0)
; template <class Epi, class Sched, bool ALIGN_EPI = false, bool SP2 = false>
; __device__ __forceinline__ void gemm_phase(PG8_LAS unsigned char* lds, const Gemm g, const Sched& S, const Epi& E) {
;     ...
;             PG8_WAIT_V(8); PG8_WAIT_L(0); PG8_BAR; PG8_MMA(1, 0, At, B0); PG8_MMA(1, 1, At, B1); PG8_BAR; PG8_SCHED;
;             PG8_LDB(B0, 1, 0); PG8_LDB(B1, 1, 1); PG8_SCHED; PG8_LDA(At, 1, 0); PG8_STAGE(PG8_SA(0, 1), a2 + hstep, voffA);
;             PG8_WAIT_V(8); PG8_WAIT_L(0); PG8_BAR; PG8_MMA(0, 0, At, B0); PG8_MMA(0, 1, At, B1); PG8_BAR; PG8_SCHED;
	s_setprio 1
	s_waitcnt lgkmcnt(0)
	v_mfma_f32_16x16x32_bf16 v[60:63], v[128:131], v[186:189], v[60:63]
	v_mfma_f32_16x16x32_bf16 v[56:59], v[136:139], v[186:189], v[56:59]
	v_mfma_f32_16x16x32_bf16 v[44:47], v[128:131], v[194:197], v[44:47]
	v_mfma_f32_16x16x32_bf16 v[40:43], v[136:139], v[194:197], v[40:43]
	v_mfma_f32_16x16x32_bf16 v[28:31], v[128:131], v[202:205], v[28:31]
	v_mfma_f32_16x16x32_bf16 v[24:27], v[136:139], v[202:205], v[24:27]
	v_mfma_f32_16x16x32_bf16 v[12:15], v[128:131], v[210:213], v[12:15]
	v_mfma_f32_16x16x32_bf16 v[8:11], v[136:139], v[210:213], v[8:11]
	v_mfma_f32_16x16x32_bf16 v[60:63], v[132:135], v[190:193], v[60:63]
	v_mfma_f32_16x16x32_bf16 v[56:59], v[140:143], v[190:193], v[56:59]
	v_mfma_f32_16x16x32_bf16 v[44:47], v[132:135], v[198:201], v[44:47]
	v_mfma_f32_16x16x32_bf16 v[40:43], v[140:143], v[198:201], v[40:43]
	v_mfma_f32_16x16x32_bf16 v[28:31], v[132:135], v[206:209], v[28:31]
	v_mfma_f32_16x16x32_bf16 v[24:27], v[140:143], v[206:209], v[24:27]
	v_mfma_f32_16x16x32_bf16 v[12:15], v[132:135], v[214:217], v[12:15]
	v_mfma_f32_16x16x32_bf16 v[8:11], v[140:143], v[214:217], v[8:11]
	s_setprio 0
	s_setprio 1
	v_mfma_f32_16x16x32_bf16 v[52:55], v[160:163], v[186:189], v[52:55]
	v_mfma_f32_16x16x32_bf16 v[48:51], v[178:181], v[186:189], v[48:51]
	v_mfma_f32_16x16x32_bf16 v[36:39], v[160:163], v[194:197], v[36:39]
	v_mfma_f32_16x16x32_bf16 v[32:35], v[178:181], v[194:197], v[32:35]
	v_mfma_f32_16x16x32_bf16 v[20:23], v[160:163], v[202:205], v[20:23]
	v_mfma_f32_16x16x32_bf16 v[16:19], v[178:181], v[202:205], v[16:19]
	v_mfma_f32_16x16x32_bf16 v[4:7], v[160:163], v[210:213], v[4:7]
	v_mfma_f32_16x16x32_bf16 v[0:3], v[178:181], v[210:213], v[0:3]
	v_mfma_f32_16x16x32_bf16 v[52:55], v[164:167], v[190:193], v[52:55]
	v_mfma_f32_16x16x32_bf16 v[48:51], v[182:185], v[190:193], v[48:51]
	v_mfma_f32_16x16x32_bf16 v[36:39], v[164:167], v[198:201], v[36:39]
	v_mfma_f32_16x16x32_bf16 v[32:35], v[182:185], v[198:201], v[32:35]
	v_mfma_f32_16x16x32_bf16 v[20:23], v[164:167], v[206:209], v[20:23]
	v_mfma_f32_16x16x32_bf16 v[16:19], v[182:185], v[206:209], v[16:19]
	v_mfma_f32_16x16x32_bf16 v[4:7], v[164:167], v[214:217], v[4:7]
	v_mfma_f32_16x16x32_bf16 v[0:3], v[182:185], v[214:217], v[0:3]
	s_setprio 0
	s_barrier
	s_add_i32 s71, 0, 0x18000
	s_add_i32 s72, 0, 0x1c000
	v_add_u32_e32 v140, s71, v171
	v_add_u32_e32 v177, s72, v171
	ds_read_b128 v[128:131], v140
	ds_read_b128 v[132:135], v140 offset:1024
	ds_read_b128 v[136:139], v140 offset:2048
	ds_read_b128 v[140:143], v140 offset:3072
	ds_read_b128 v[160:163], v177
	ds_read_b128 v[164:167], v177 offset:1024
	ds_read_b128 v[178:181], v177 offset:2048
	ds_read_b128 v[182:185], v177 offset:3072
	s_add_u32 s36, s36, 0x40000
	s_addc_u32 s37, s37, 0
	s_mov_b32 m0, s44
	v_lshl_add_u64 v[224:225], s[36:37], 0, v[150:151]
	ds_read_b128 v[186:189], v175 offset:32768
	ds_read_b128 v[190:193], v175 offset:33792
	ds_read_b128 v[194:197], v175 offset:34816
	ds_read_b128 v[198:201], v175 offset:35840
	ds_read_b128 v[202:205], v175 offset:36864
	ds_read_b128 v[206:209], v175 offset:37888
	ds_read_b128 v[210:213], v175 offset:38912
	ds_read_b128 v[214:217], v175 offset:39936
	global_load_lds_dwordx4 v[224:225], off
	v_lshl_add_u64 v[224:225], s[36:37], 0, v[146:147]
	s_mov_b32 m0, s45
	s_nop 0
	global_load_lds_dwordx4 v[224:225], off
	s_waitcnt vmcnt(8)
	s_waitcnt lgkmcnt(0)
	s_barrier
	s_setprio 1
	s_waitcnt lgkmcnt(0)
	v_mfma_f32_16x16x32_bf16 v[124:127], v[128:131], v[186:189], v[124:127]
	v_mfma_f32_16x16x32_bf16 v[120:123], v[136:139], v[186:189], v[120:123]
	v_mfma_f32_16x16x32_bf16 v[108:111], v[128:131], v[194:197], v[108:111]
	v_mfma_f32_16x16x32_bf16 v[104:107], v[136:139], v[194:197], v[104:107]
	v_mfma_f32_16x16x32_bf16 v[92:95], v[128:131], v[202:205], v[92:95]
	v_mfma_f32_16x16x32_bf16 v[88:91], v[136:139], v[202:205], v[88:91]
	v_mfma_f32_16x16x32_bf16 v[76:79], v[128:131], v[210:213], v[76:79]
	v_mfma_f32_16x16x32_bf16 v[72:75], v[136:139], v[210:213], v[72:75]
	v_mfma_f32_16x16x32_bf16 v[124:127], v[132:135], v[190:193], v[124:127]
	v_mfma_f32_16x16x32_bf16 v[120:123], v[140:143], v[190:193], v[120:123]
	v_mfma_f32_16x16x32_bf16 v[108:111], v[132:135], v[198:201], v[108:111]
	v_mfma_f32_16x16x32_bf16 v[104:107], v[140:143], v[198:201], v[104:107]
	v_mfma_f32_16x16x32_bf16 v[92:95], v[132:135], v[206:209], v[92:95]
	v_mfma_f32_16x16x32_bf16 v[88:91], v[140:143], v[206:209], v[88:91]
	v_mfma_f32_16x16x32_bf16 v[76:79], v[132:135], v[214:217], v[76:79]
	v_mfma_f32_16x16x32_bf16 v[72:75], v[140:143], v[214:217], v[72:75]
	s_setprio 0
	s_setprio 1
	v_mfma_f32_16x16x32_bf16 v[116:119], v[160:163], v[186:189], v[116:119]
	v_mfma_f32_16x16x32_bf16 v[112:115], v[178:181], v[186:189], v[112:115]
	v_mfma_f32_16x16x32_bf16 v[100:103], v[160:163], v[194:197], v[100:103]
	v_mfma_f32_16x16x32_bf16 v[96:99], v[178:181], v[194:197], v[96:99]
	v_mfma_f32_16x16x32_bf16 v[84:87], v[160:163], v[202:205], v[84:87]
	v_mfma_f32_16x16x32_bf16 v[80:83], v[178:181], v[202:205], v[80:83]
	v_mfma_f32_16x16x32_bf16 v[68:71], v[160:163], v[210:213], v[68:71]
	v_mfma_f32_16x16x32_bf16 v[64:67], v[178:181], v[210:213], v[64:67]
	v_mfma_f32_16x16x32_bf16 v[116:119], v[164:167], v[190:193], v[116:119]
	v_mfma_f32_16x16x32_bf16 v[112:115], v[182:185], v[190:193], v[112:115]
	v_mfma_f32_16x16x32_bf16 v[100:103], v[164:167], v[198:201], v[100:103]
	v_mfma_f32_16x16x32_bf16 v[96:99], v[182:185], v[198:201], v[96:99]
	v_mfma_f32_16x16x32_bf16 v[84:87], v[164:167], v[206:209], v[84:87]
	v_mfma_f32_16x16x32_bf16 v[80:83], v[182:185], v[206:209], v[80:83]
	v_mfma_f32_16x16x32_bf16 v[68:71], v[164:167], v[214:217], v[68:71]
	v_mfma_f32_16x16x32_bf16 v[64:67], v[182:185], v[214:217], v[64:67]
	s_setprio 0
	s_barrier
; #define PG8_STAGE(bufoff, gbase, voff) do { _Pragma("unroll") for (int _i = 0; _i < 2; ++_i) \
;         __builtin_amdgcn_global_load_lds((const unsigned*)((const char*)(gbase) + (voff)[_i]), (PG8_LAS unsigned*)(lds + (bufoff) + ldsw + _i * 8192), 16, 0, 0); } while (0)
; #define PG8_LDA(dst, b, h) do { _Pragma("unroll") for (int m = 0; m < 4; ++m) _Pragma("unroll") for (int k = 0; k < 2; ++k) dst[m][k] = *(const PG8_LAS bf16x8*)(lds + PG8_SA(b, h) + aoff + m * 2048 + k * 1024); } while (0)
; #define PG8_MMA(ai, bj, At, Bt) do { __builtin_amdgcn_s_setprio(1); _Pragma("unroll") for (int m = 0; m < 4; ++m) _Pragma("unroll") for (int n = 0; n < 2; ++n) _Pragma("unroll") for (int k = 0; k < 2; ++k) \
;         acc[ai][bj][m][n] = __builtin_amdgcn_mfma_f32_16x16x32_bf16(Bt[n][k], At[m][k], acc[ai][bj][m][n], 0, 0, 0); __builtin_amdgcn_s_setprio(0); } while (0)
; #define PG8_WAIT_V(n) asm volatile("s_waitcnt vmcnt(" #n ")" ::: "memory")
; #define PG8_WAIT_L(n) asm volatile("s_waitcnt lgkmcnt(" #n ")" ::: "memory")
; #define PG8_BAR __builtin_amdgcn_s_barrier()
; #define PG8_SCHED __builtin_amdgcn_sched_barrier(0)
; template <class Epi, class Sched, bool ALIGN_EPI = false, bool SP2 = false>
; __device__ __forceinline__ void gemm_phase(PG8_LAS unsigned char* lds, const Gemm g, const Sched& S, const Epi& E) {
;     ...
;             PG8_LDA(At, 1, 1); PG8_STAGE(PG8_SB(1, 0), b3, voffB); PG8_STAGE(PG8_SB(1, 1), b3 + hstep, voffB); PG8_STAGE(PG8_SA(1, 0), a3, voffA);
;             PG8_WAIT_V(8); PG8_WAIT_L(0); PG8_BAR; PG8_MMA(1, 0, At, B0); PG8_MMA(1, 1, At, B1); PG8_BAR; PG8_SCHED;
;     ...
;         if constexpr (ALIGN_EPI) { if (wr == 0) PG8_BAR; }
	s_add_i32 s36, s71, s39
	v_lshl_add_u64 v[168:169], v[168:169], 0, s[6:7]
	s_mov_b32 m0, s36
	ds_read_b128 v[186:189], v175 offset:49152
	ds_read_b128 v[190:193], v175 offset:50176
	ds_read_b128 v[194:197], v175 offset:51200
	ds_read_b128 v[198:201], v175 offset:52224
	ds_read_b128 v[202:205], v175 offset:53248
	ds_read_b128 v[206:209], v175 offset:54272
	ds_read_b128 v[210:213], v175 offset:55296
	ds_read_b128 v[214:217], v175 offset:56320
	global_load_lds_dwordx4 v[168:169], off
	s_add_i32 m0, s36, 0x2000
	s_add_u32 s26, s26, 0x40080
	v_lshl_add_u64 v[168:169], v[218:219], 0, s[6:7]
	s_addc_u32 s27, s27, 0
	s_add_i32 s36, s72, s39
	global_load_lds_dwordx4 v[168:169], off
	v_lshl_add_u64 v[168:169], s[26:27], 0, v[148:149]
	s_mov_b32 m0, s36
	s_nop 0
	global_load_lds_dwordx4 v[168:169], off
	v_lshl_add_u64 v[168:169], s[26:27], 0, v[144:145]
	s_add_i32 m0, s36, 0x2000
	s_nop 0
	global_load_lds_dwordx4 v[168:169], off
	v_lshl_add_u64 v[168:169], v[220:221], 0, s[6:7]
	s_mov_b32 m0, s47
	s_nop 0
	global_load_lds_dwordx4 v[168:169], off
	v_lshl_add_u64 v[168:169], v[222:223], 0, s[6:7]
	s_mov_b32 m0, s48
	s_nop 0
	global_load_lds_dwordx4 v[168:169], off
	s_waitcnt vmcnt(8)
	s_waitcnt lgkmcnt(0)
	s_barrier
	s_setprio 1
	s_waitcnt lgkmcnt(0)
	v_mfma_f32_16x16x32_bf16 v[60:63], v[128:131], v[186:189], v[60:63]
	v_mfma_f32_16x16x32_bf16 v[56:59], v[136:139], v[186:189], v[56:59]
	v_mfma_f32_16x16x32_bf16 v[44:47], v[128:131], v[194:197], v[44:47]
	v_mfma_f32_16x16x32_bf16 v[40:43], v[136:139], v[194:197], v[40:43]
	v_mfma_f32_16x16x32_bf16 v[28:31], v[128:131], v[202:205], v[28:31]
	v_mfma_f32_16x16x32_bf16 v[24:27], v[136:139], v[202:205], v[24:27]
	v_mfma_f32_16x16x32_bf16 v[12:15], v[128:131], v[210:213], v[12:15]
	v_mfma_f32_16x16x32_bf16 v[8:11], v[136:139], v[210:213], v[8:11]
	v_mfma_f32_16x16x32_bf16 v[60:63], v[132:135], v[190:193], v[60:63]
	v_mfma_f32_16x16x32_bf16 v[56:59], v[140:143], v[190:193], v[56:59]
	v_mfma_f32_16x16x32_bf16 v[44:47], v[132:135], v[198:201], v[44:47]
	v_mfma_f32_16x16x32_bf16 v[40:43], v[140:143], v[198:201], v[40:43]
	v_mfma_f32_16x16x32_bf16 v[28:31], v[132:135], v[206:209], v[28:31]
	v_mfma_f32_16x16x32_bf16 v[24:27], v[140:143], v[206:209], v[24:27]
	v_mfma_f32_16x16x32_bf16 v[12:15], v[132:135], v[214:217], v[12:15]
	v_mfma_f32_16x16x32_bf16 v[8:11], v[140:143], v[214:217], v[8:11]
	s_setprio 0
	s_setprio 1
	v_mfma_f32_16x16x32_bf16 v[52:55], v[160:163], v[186:189], v[52:55]
	v_mfma_f32_16x16x32_bf16 v[48:51], v[178:181], v[186:189], v[48:51]
	v_mfma_f32_16x16x32_bf16 v[36:39], v[160:163], v[194:197], v[36:39]
	v_mfma_f32_16x16x32_bf16 v[32:35], v[178:181], v[194:197], v[32:35]
	v_mfma_f32_16x16x32_bf16 v[20:23], v[160:163], v[202:205], v[20:23]
	v_mfma_f32_16x16x32_bf16 v[16:19], v[178:181], v[202:205], v[16:19]
	v_mfma_f32_16x16x32_bf16 v[4:7], v[160:163], v[210:213], v[4:7]
	v_mfma_f32_16x16x32_bf16 v[0:3], v[178:181], v[210:213], v[0:3]
	v_mfma_f32_16x16x32_bf16 v[52:55], v[164:167], v[190:193], v[52:55]
	v_mfma_f32_16x16x32_bf16 v[48:51], v[182:185], v[190:193], v[48:51]
	v_mfma_f32_16x16x32_bf16 v[36:39], v[164:167], v[198:201], v[36:39]
	v_mfma_f32_16x16x32_bf16 v[32:35], v[182:185], v[198:201], v[32:35]
	v_mfma_f32_16x16x32_bf16 v[20:23], v[164:167], v[206:209], v[20:23]
	v_mfma_f32_16x16x32_bf16 v[16:19], v[182:185], v[206:209], v[16:19]
	v_mfma_f32_16x16x32_bf16 v[4:7], v[164:167], v[214:217], v[4:7]
	v_mfma_f32_16x16x32_bf16 v[0:3], v[182:185], v[214:217], v[0:3]
	s_setprio 0
	s_barrier
	s_add_i32 s70, s70, 2
	s_add_u32 s24, s24, 0x100
	s_addc_u32 s25, s25, 0
	s_add_u32 s68, s68, 0x100
	s_addc_u32 s69, s69, 0
	s_cmp_gt_u32 s70, 13
	s_cbranch_scc0 .LBB0_813
	s_cmpk_gt_u32 s38, 0xff
	s_cbranch_scc1 .Lal_p7_pre
	s_barrier
; __device__ __forceinline__ u32x2 pack4(f32x4 v) { u32x2 w; w.x = cvt_pk_bf16(v[0], v[1]); w.y = cvt_pk_bf16(v[2], v[3]); return w; }
;     __device__ __forceinline__ void operator()(const f32x4 (&acc)[2][2][4][2], const Unit& u, int wr, int wc, int fr, int fq) const {
;         const int row0 = u.pm * BM + wr * 64 + fr, col0 = u.pn * BM + wc * 32 + 8 * fq;
;         const float* base = (u.pm * BM < split) ? base0 : base1; bf16_t* const xn = (bf16_t*)(ws + WS_XN); float* const ssq = (float*)(ws + WS_SSQ);
; #pragma unroll
;         for (int ai = 0; ai < 2; ++ai)
; #pragma unroll
;         for (int mh = 0; mh < 4; mh += 2) {
;             f32x4 pre[4][2][2];
; #pragma unroll
;             for (int m = mh; m < mh + 2; ++m)
; #pragma unroll
;                 for (int bj = 0; bj < 2; ++bj)
; #pragma unroll
;                     for (int n = 0; n < 2; ++n) pre[m][bj][n] = *(const f32x4*)(base + (size_t)(row0 + ai * HALF + m * 16) * 1024 + col0 + bj * HALF + n * 4);
;             asm volatile("" ::: "memory");
; #pragma unroll
;             for (int m = mh; m < mh + 2; ++m) { const int row = row0 + ai * HALF + m * 16; const size_t off = (size_t)row * 1024 + col0; float ss = 0.f;
; #pragma unroll
;                 for (int bj = 0; bj < 2; ++bj) { u32x4e w;
; #pragma unroll
;                     for (int n = 0; n < 2; ++n) { const f32x4 o = pre[m][bj][n] + acc[ai][bj][m][n] * s;
;                         *(f32x4*)(out + off + bj * HALF + n * 4) = o;
;                         if (NORMOUT) { const u32x2 p = pack4(o); w[2 * n] = p.x; w[2 * n + 1] = p.y; ss += (o[0] * o[0] + o[1] * o[1]) + (o[2] * o[2] + o[3] * o[3]); } }
;                     if (NORMOUT) *(u32x4e*)(xn + off + bj * HALF) = w; }
;                 if (NORMOUT) { ss += __shfl_xor(ss, 16); ss += __shfl_xor(ss, 32); if (fq == 0) ssq[(size_t)row * 16 + u.pn * 4 + wc] = ss; } }
.Lal_p7_pre:
	v_lshl_add_u32 v164, s22, 8, v170
	v_lshl_or_b32 v160, s23, 8, v172
	v_ashrrev_i32_e32 v161, 31, v160
	v_ashrrev_i32_e32 v165, 31, v164
	v_lshl_add_u64 v[162:163], v[160:161], 2, s[56:57]
	v_lshlrev_b64 v[128:129], 12, v[164:165]
	v_lshl_add_u64 v[196:197], v[162:163], 0, v[128:129]
	global_load_dwordx4 v[180:183], v[196:197], off
	global_load_dwordx4 v[184:187], v[196:197], off offset:16
	global_load_dwordx4 v[188:191], v[196:197], off offset:512
	global_load_dwordx4 v[192:195], v[196:197], off offset:528
	v_or_b32_e32 v166, 16, v164
	v_ashrrev_i32_e32 v167, 31, v166
	v_lshlrev_b64 v[128:129], 12, v[166:167]
	v_lshl_add_u64 v[168:169], v[162:163], 0, v[128:129]
	global_load_dwordx4 v[136:139], v[168:169], off offset:16
	global_load_dwordx4 v[140:143], v[168:169], off
	global_load_dwordx4 v[128:131], v[168:169], off offset:528
	global_load_dwordx4 v[132:135], v[168:169], off offset:512
	v_and_b32_e32 v178, 64, v176
	v_xor_b32_e32 v177, 16, v176
	v_add_u32_e32 v178, 64, v178
	v_xor_b32_e32 v179, 32, v176
	v_cmp_lt_i32_e32 vcc, v177, v178
	v_lshlrev_b64 v[198:199], 10, v[164:165]
	v_lshl_add_u64 v[198:199], v[198:199], 0, v[160:161]
	v_cndmask_b32_e32 v177, v176, v177, vcc
	v_cmp_lt_i32_e32 vcc, v179, v178
	v_lshlrev_b32_e32 v178, 2, v177
	v_lshl_add_u64 v[198:199], v[198:199], 1, s[64:65]
	v_cndmask_b32_e32 v179, v176, v179, vcc
	v_lshlrev_b32_e32 v177, 2, v179
	s_lshl_b32 s22, s23, 2
	s_ashr_i32 s23, s22, 31
	s_lshl_b64 s[22:23], s[22:23], 2
	s_add_u32 s22, s50, s22
	s_addc_u32 s23, s51, s23
	s_waitcnt vmcnt(0)
	v_pk_add_f32 v[126:127], v[182:183], v[126:127]
	v_pk_add_f32 v[124:125], v[180:181], v[124:125]
	v_pk_add_f32 v[122:123], v[186:187], v[122:123]
	v_pk_add_f32 v[120:121], v[184:185], v[120:121]
	v_pk_add_f32 v[118:119], v[190:191], v[118:119]
	v_pk_add_f32 v[116:117], v[188:189], v[116:117]
	v_pk_add_f32 v[182:183], v[194:195], v[114:115]
	v_pk_add_f32 v[180:181], v[192:193], v[112:113]
	global_store_dwordx4 v[196:197], v[124:127], off
	v_cvt_pk_bf16_f32 v112, v124, v125
	v_cvt_pk_bf16_f32 v113, v126, v127
	v_mul_f32_e32 v125, v125, v125
	v_mul_f32_e32 v127, v127, v127
	global_store_dwordx4 v[196:197], v[120:123], off offset:16
	v_cvt_pk_bf16_f32 v114, v120, v121
	v_cvt_pk_bf16_f32 v115, v122, v123
	v_mul_f32_e32 v121, v121, v121
	v_mul_f32_e32 v123, v123, v123
	v_mul_f32_e32 v179, v117, v117
	v_mul_f32_e32 v184, v119, v119
	v_fmac_f32_e32 v125, v124, v124
	v_fmac_f32_e32 v127, v126, v126
	v_fmac_f32_e32 v121, v120, v120
	v_fmac_f32_e32 v123, v122, v122
	v_mul_f32_e32 v185, v181, v181
	v_mul_f32_e32 v186, v183, v183
	v_fmac_f32_e32 v179, v116, v116
	v_fmac_f32_e32 v184, v118, v118
	v_add_f32_e32 v120, v125, v127
	v_add_f32_e32 v121, v121, v123
	v_fmac_f32_e32 v185, v180, v180
	v_fmac_f32_e32 v186, v182, v182
	v_add_f32_e32 v122, v179, v184
	v_add_f32_e32 v120, v120, v121
	v_add_f32_e32 v120, v122, v120
	v_add_f32_e32 v121, v185, v186
	v_add_f32_e32 v120, v121, v120
	ds_bpermute_b32 v121, v178, v120
	global_store_dwordx4 v[198:199], v[112:115], off
	global_store_dwordx4 v[196:197], v[116:119], off offset:512
	global_store_dwordx4 v[196:197], v[180:183], off offset:528
	v_cvt_pk_bf16_f32 v114, v116, v117
	v_cvt_pk_bf16_f32 v115, v118, v119
	s_waitcnt lgkmcnt(0)
	v_add_f32_e32 v112, v120, v121
	ds_bpermute_b32 v113, v177, v112
	v_cvt_pk_bf16_f32 v116, v180, v181
	v_cvt_pk_bf16_f32 v117, v182, v183
	global_store_dwordx4 v[198:199], v[114:117], off offset:256
	s_and_saveexec_b64 s[24:25], s[2:3]
	s_cbranch_execz .LBB0_816
	v_lshlrev_b64 v[114:115], 6, v[164:165]
	v_lshl_add_u64 v[114:115], s[22:23], 0, v[114:115]
	s_waitcnt lgkmcnt(0)
	v_add_f32_e32 v112, v112, v113
	global_store_dword v[114:115], v112, off

; #define PG8_WAIT_V(n) asm volatile("s_waitcnt vmcnt(" #n ")" ::: "memory")
; #define PG8_BAR __builtin_amdgcn_s_barrier()
; template <class Epi, class Sched, bool ALIGN_EPI = false, bool SP2 = false>
; __device__ __forceinline__ void gemm_phase(PG8_LAS unsigned char* lds, const Gemm g, const Sched& S, const Epi& E) {
;     ...
;     PG8_WAIT_V(0);
;     if constexpr (!ALIGN_EPI) { if (wr == 0) PG8_BAR; }
;     PG8_BAR;
.LBB0_830:
	s_waitcnt vmcnt(0)
.LBB0_832:
	s_barrier
